# K-loops: s_setprio 1 before the opening barrier, redundant lgkmcnt wait and mid-block setprio pair dropped, setprio 0 after the closing barrier
# speedup vs baseline: 1.0047x; 1.0047x over previous
.LBB0_264:
	ds_read_b128 v[148:151], v190
	ds_read_b128 v[152:155], v190 offset:1024
	ds_read_b128 v[156:159], v190 offset:2048
	ds_read_b128 v[160:163], v190 offset:3072
	ds_read_b128 v[196:199], v191
	ds_read_b128 v[200:203], v191 offset:1024
	ds_read_b128 v[204:207], v191 offset:2048
	ds_read_b128 v[208:211], v191 offset:3072
	s_add_u32 s22, s20, 0xfffc0080
	s_addc_u32 s23, s21, -1
	s_cmp_eq_u32 s65, 12
	s_cselect_b32 s25, s13, s23
	s_cselect_b32 s24, s39, s22
	s_cselect_b32 s23, s11, s64
	s_cselect_b32 s22, s62, s63
	v_lshl_add_u64 v[166:167], s[20:21], 0, v[140:141]
	s_add_i32 m0, s19, 0xc000
	ds_read_b128 v[212:215], v192
	ds_read_b128 v[216:219], v192 offset:1024
	ds_read_b128 v[220:223], v192 offset:2048
	ds_read_b128 v[224:227], v192 offset:3072
	ds_read_b128 v[228:231], v192 offset:4096
	ds_read_b128 v[232:235], v192 offset:5120
	ds_read_b128 v[236:239], v192 offset:6144
	ds_read_b128 v[240:243], v192 offset:7168
	global_load_lds_dwordx4 v[166:167], off
	v_lshl_add_u64 v[166:167], s[20:21], 0, v[142:143]
	s_add_i32 m0, s19, 0xe000
	s_nop 0
	global_load_lds_dwordx4 v[166:167], off
	s_waitcnt vmcnt(8)
	s_waitcnt lgkmcnt(0)
	s_setprio 1
	s_barrier
	v_mfma_f32_16x16x32_bf16 v[124:127], v[148:151], v[212:215], v[124:127]
	v_mfma_f32_16x16x32_bf16 v[120:123], v[156:159], v[212:215], v[120:123]
	v_mfma_f32_16x16x32_bf16 v[112:115], v[148:151], v[220:223], v[112:115]
	v_mfma_f32_16x16x32_bf16 v[104:107], v[156:159], v[220:223], v[104:107]
	v_mfma_f32_16x16x32_bf16 v[96:99], v[148:151], v[228:231], v[96:99]
	v_mfma_f32_16x16x32_bf16 v[88:91], v[156:159], v[228:231], v[88:91]
	v_mfma_f32_16x16x32_bf16 v[80:83], v[148:151], v[236:239], v[80:83]
	v_mfma_f32_16x16x32_bf16 v[72:75], v[156:159], v[236:239], v[72:75]
	v_mfma_f32_16x16x32_bf16 v[124:127], v[152:155], v[216:219], v[124:127]
	v_mfma_f32_16x16x32_bf16 v[120:123], v[160:163], v[216:219], v[120:123]
	v_mfma_f32_16x16x32_bf16 v[112:115], v[152:155], v[224:227], v[112:115]
	v_mfma_f32_16x16x32_bf16 v[104:107], v[160:163], v[224:227], v[104:107]
	v_mfma_f32_16x16x32_bf16 v[96:99], v[152:155], v[232:235], v[96:99]
	v_mfma_f32_16x16x32_bf16 v[88:91], v[160:163], v[232:235], v[88:91]
	v_mfma_f32_16x16x32_bf16 v[80:83], v[152:155], v[240:243], v[80:83]
	v_mfma_f32_16x16x32_bf16 v[72:75], v[160:163], v[240:243], v[72:75]
	v_mfma_f32_16x16x32_bf16 v[116:119], v[196:199], v[212:215], v[116:119]
	v_mfma_f32_16x16x32_bf16 v[108:111], v[204:207], v[212:215], v[108:111]
	v_mfma_f32_16x16x32_bf16 v[100:103], v[196:199], v[220:223], v[100:103]
	v_mfma_f32_16x16x32_bf16 v[92:95], v[204:207], v[220:223], v[92:95]
	v_mfma_f32_16x16x32_bf16 v[84:87], v[196:199], v[228:231], v[84:87]
	v_mfma_f32_16x16x32_bf16 v[76:79], v[204:207], v[228:231], v[76:79]
	v_mfma_f32_16x16x32_bf16 v[68:71], v[196:199], v[236:239], v[68:71]
	v_mfma_f32_16x16x32_bf16 v[64:67], v[204:207], v[236:239], v[64:67]
	v_mfma_f32_16x16x32_bf16 v[116:119], v[200:203], v[216:219], v[116:119]
	v_mfma_f32_16x16x32_bf16 v[108:111], v[208:211], v[216:219], v[108:111]
	v_mfma_f32_16x16x32_bf16 v[100:103], v[200:203], v[224:227], v[100:103]
	v_mfma_f32_16x16x32_bf16 v[92:95], v[208:211], v[224:227], v[92:95]
	v_mfma_f32_16x16x32_bf16 v[84:87], v[200:203], v[232:235], v[84:87]
	v_mfma_f32_16x16x32_bf16 v[76:79], v[208:211], v[232:235], v[76:79]
	v_mfma_f32_16x16x32_bf16 v[68:71], v[200:203], v[240:243], v[68:71]
	v_mfma_f32_16x16x32_bf16 v[64:67], v[208:211], v[240:243], v[64:67]
	s_barrier
	s_setprio 0
	s_add_i32 s66, s52, s31
	v_lshl_add_u64 v[166:167], s[22:23], 0, v[130:131]
	s_mov_b32 m0, s66
	ds_read_b128 v[212:215], v192 offset:16384
	ds_read_b128 v[216:219], v192 offset:17408
	ds_read_b128 v[220:223], v192 offset:18432
	ds_read_b128 v[224:227], v192 offset:19456
	ds_read_b128 v[228:231], v192 offset:20480
	ds_read_b128 v[232:235], v192 offset:21504
	ds_read_b128 v[236:239], v192 offset:22528
	ds_read_b128 v[240:243], v192 offset:23552
	global_load_lds_dwordx4 v[166:167], off
	s_add_i32 m0, s66, 0x2000
	s_add_u32 s66, s22, 0x40000
	v_lshl_add_u64 v[244:245], s[22:23], 0, v[134:135]
	s_addc_u32 s67, s23, 0
	s_add_i32 s68, s53, s31
	global_load_lds_dwordx4 v[244:245], off
	v_lshl_add_u64 v[246:247], s[66:67], 0, v[130:131]
	s_mov_b32 m0, s68
	v_lshl_add_u64 v[248:249], s[24:25], 0, v[132:133]
	global_load_lds_dwordx4 v[246:247], off
	v_lshl_add_u64 v[246:247], s[66:67], 0, v[134:135]
	s_add_i32 m0, s68, 0x2000
	s_nop 0
	global_load_lds_dwordx4 v[246:247], off
	v_lshl_add_u64 v[246:247], s[24:25], 0, v[128:129]
	s_mov_b32 m0, s19
	s_nop 0
	global_load_lds_dwordx4 v[246:247], off
	s_mov_b32 m0, s35
	s_nop 0
	global_load_lds_dwordx4 v[248:249], off
	s_waitcnt vmcnt(8)
	s_waitcnt lgkmcnt(0)
	s_setprio 1
	s_barrier
	v_mfma_f32_16x16x32_bf16 v[60:63], v[148:151], v[212:215], v[60:63]
	v_mfma_f32_16x16x32_bf16 v[56:59], v[156:159], v[212:215], v[56:59]
	v_mfma_f32_16x16x32_bf16 v[48:51], v[148:151], v[220:223], v[48:51]
	v_mfma_f32_16x16x32_bf16 v[40:43], v[156:159], v[220:223], v[40:43]
	v_mfma_f32_16x16x32_bf16 v[32:35], v[148:151], v[228:231], v[32:35]
	v_mfma_f32_16x16x32_bf16 v[24:27], v[156:159], v[228:231], v[24:27]
	v_mfma_f32_16x16x32_bf16 v[16:19], v[148:151], v[236:239], v[16:19]
	v_mfma_f32_16x16x32_bf16 v[8:11], v[156:159], v[236:239], v[8:11]
	v_mfma_f32_16x16x32_bf16 v[60:63], v[152:155], v[216:219], v[60:63]
	v_mfma_f32_16x16x32_bf16 v[56:59], v[160:163], v[216:219], v[56:59]
	v_mfma_f32_16x16x32_bf16 v[48:51], v[152:155], v[224:227], v[48:51]
	v_mfma_f32_16x16x32_bf16 v[40:43], v[160:163], v[224:227], v[40:43]
	v_mfma_f32_16x16x32_bf16 v[32:35], v[152:155], v[232:235], v[32:35]
	v_mfma_f32_16x16x32_bf16 v[24:27], v[160:163], v[232:235], v[24:27]
	v_mfma_f32_16x16x32_bf16 v[16:19], v[152:155], v[240:243], v[16:19]
	v_mfma_f32_16x16x32_bf16 v[8:11], v[160:163], v[240:243], v[8:11]
	v_mfma_f32_16x16x32_bf16 v[52:55], v[196:199], v[212:215], v[52:55]
	v_mfma_f32_16x16x32_bf16 v[44:47], v[204:207], v[212:215], v[44:47]
	v_mfma_f32_16x16x32_bf16 v[36:39], v[196:199], v[220:223], v[36:39]
	v_mfma_f32_16x16x32_bf16 v[28:31], v[204:207], v[220:223], v[28:31]
	v_mfma_f32_16x16x32_bf16 v[20:23], v[196:199], v[228:231], v[20:23]
	v_mfma_f32_16x16x32_bf16 v[12:15], v[204:207], v[228:231], v[12:15]
	v_mfma_f32_16x16x32_bf16 v[4:7], v[196:199], v[236:239], v[4:7]
	v_mfma_f32_16x16x32_bf16 v[0:3], v[204:207], v[236:239], v[0:3]
	v_mfma_f32_16x16x32_bf16 v[52:55], v[200:203], v[216:219], v[52:55]
	v_mfma_f32_16x16x32_bf16 v[44:47], v[208:211], v[216:219], v[44:47]
	v_mfma_f32_16x16x32_bf16 v[36:39], v[200:203], v[224:227], v[36:39]
	v_mfma_f32_16x16x32_bf16 v[28:31], v[208:211], v[224:227], v[28:31]
	v_mfma_f32_16x16x32_bf16 v[20:23], v[200:203], v[232:235], v[20:23]
	v_mfma_f32_16x16x32_bf16 v[12:15], v[208:211], v[232:235], v[12:15]
	v_mfma_f32_16x16x32_bf16 v[4:7], v[200:203], v[240:243], v[4:7]
	v_mfma_f32_16x16x32_bf16 v[0:3], v[208:211], v[240:243], v[0:3]
	s_barrier
	s_setprio 0
	s_add_i32 s66, 0, 0x18000
	v_add_u32_e32 v138, s66, v182
	s_add_i32 s67, 0, 0x1c000
	ds_read_b128 v[148:151], v138
	ds_read_b128 v[152:155], v138 offset:1024
	ds_read_b128 v[156:159], v138 offset:2048
	ds_read_b128 v[160:163], v138 offset:3072
	v_add_u32_e32 v138, s67, v182
	ds_read_b128 v[196:199], v138
	ds_read_b128 v[200:203], v138 offset:1024
	ds_read_b128 v[204:207], v138 offset:2048
	ds_read_b128 v[208:211], v138 offset:3072
	s_add_u32 s24, s24, 0x40000
	s_addc_u32 s25, s25, 0
	s_mov_b32 m0, s36
	v_lshl_add_u64 v[250:251], s[24:25], 0, v[128:129]
	ds_read_b128 v[212:215], v192 offset:32768
	ds_read_b128 v[216:219], v192 offset:33792
	ds_read_b128 v[220:223], v192 offset:34816
	ds_read_b128 v[224:227], v192 offset:35840
	ds_read_b128 v[228:231], v192 offset:36864
	ds_read_b128 v[232:235], v192 offset:37888
	ds_read_b128 v[236:239], v192 offset:38912
	ds_read_b128 v[240:243], v192 offset:39936
	global_load_lds_dwordx4 v[250:251], off
	v_lshl_add_u64 v[250:251], s[24:25], 0, v[132:133]
	s_mov_b32 m0, s37
	s_nop 0
	global_load_lds_dwordx4 v[250:251], off
	s_waitcnt vmcnt(8)
	s_waitcnt lgkmcnt(0)
	s_setprio 1
	s_barrier
	v_mfma_f32_16x16x32_bf16 v[124:127], v[148:151], v[212:215], v[124:127]
	v_mfma_f32_16x16x32_bf16 v[120:123], v[156:159], v[212:215], v[120:123]
	v_mfma_f32_16x16x32_bf16 v[112:115], v[148:151], v[220:223], v[112:115]
	v_mfma_f32_16x16x32_bf16 v[104:107], v[156:159], v[220:223], v[104:107]
	v_mfma_f32_16x16x32_bf16 v[96:99], v[148:151], v[228:231], v[96:99]
	v_mfma_f32_16x16x32_bf16 v[88:91], v[156:159], v[228:231], v[88:91]
	v_mfma_f32_16x16x32_bf16 v[80:83], v[148:151], v[236:239], v[80:83]
	v_mfma_f32_16x16x32_bf16 v[72:75], v[156:159], v[236:239], v[72:75]
	v_mfma_f32_16x16x32_bf16 v[124:127], v[152:155], v[216:219], v[124:127]
	v_mfma_f32_16x16x32_bf16 v[120:123], v[160:163], v[216:219], v[120:123]
	v_mfma_f32_16x16x32_bf16 v[112:115], v[152:155], v[224:227], v[112:115]
	v_mfma_f32_16x16x32_bf16 v[104:107], v[160:163], v[224:227], v[104:107]
	v_mfma_f32_16x16x32_bf16 v[96:99], v[152:155], v[232:235], v[96:99]
	v_mfma_f32_16x16x32_bf16 v[88:91], v[160:163], v[232:235], v[88:91]
	v_mfma_f32_16x16x32_bf16 v[80:83], v[152:155], v[240:243], v[80:83]
	v_mfma_f32_16x16x32_bf16 v[72:75], v[160:163], v[240:243], v[72:75]
	v_mfma_f32_16x16x32_bf16 v[116:119], v[196:199], v[212:215], v[116:119]
	v_mfma_f32_16x16x32_bf16 v[108:111], v[204:207], v[212:215], v[108:111]
	v_mfma_f32_16x16x32_bf16 v[100:103], v[196:199], v[220:223], v[100:103]
	v_mfma_f32_16x16x32_bf16 v[92:95], v[204:207], v[220:223], v[92:95]
	v_mfma_f32_16x16x32_bf16 v[84:87], v[196:199], v[228:231], v[84:87]
	v_mfma_f32_16x16x32_bf16 v[76:79], v[204:207], v[228:231], v[76:79]
	v_mfma_f32_16x16x32_bf16 v[68:71], v[196:199], v[236:239], v[68:71]
	v_mfma_f32_16x16x32_bf16 v[64:67], v[204:207], v[236:239], v[64:67]
	v_mfma_f32_16x16x32_bf16 v[116:119], v[200:203], v[216:219], v[116:119]
	v_mfma_f32_16x16x32_bf16 v[108:111], v[208:211], v[216:219], v[108:111]
	v_mfma_f32_16x16x32_bf16 v[100:103], v[200:203], v[224:227], v[100:103]
	v_mfma_f32_16x16x32_bf16 v[92:95], v[208:211], v[224:227], v[92:95]
	v_mfma_f32_16x16x32_bf16 v[84:87], v[200:203], v[232:235], v[84:87]
	v_mfma_f32_16x16x32_bf16 v[76:79], v[208:211], v[232:235], v[76:79]
	v_mfma_f32_16x16x32_bf16 v[68:71], v[200:203], v[240:243], v[68:71]
	v_mfma_f32_16x16x32_bf16 v[64:67], v[208:211], v[240:243], v[64:67]
	s_barrier
	s_setprio 0
	s_add_i32 s24, s66, s31
	v_lshl_add_u64 v[166:167], v[166:167], 0, s[6:7]
	s_mov_b32 m0, s24
	ds_read_b128 v[212:215], v192 offset:49152
	ds_read_b128 v[216:219], v192 offset:50176
	ds_read_b128 v[220:223], v192 offset:51200
	ds_read_b128 v[224:227], v192 offset:52224
	ds_read_b128 v[228:231], v192 offset:53248
	ds_read_b128 v[232:235], v192 offset:54272
	ds_read_b128 v[236:239], v192 offset:55296
	ds_read_b128 v[240:243], v192 offset:56320
	global_load_lds_dwordx4 v[166:167], off
	s_add_i32 m0, s24, 0x2000
	s_add_u32 s22, s22, 0x40080
	v_lshl_add_u64 v[166:167], v[244:245], 0, s[6:7]
	s_addc_u32 s23, s23, 0
	s_add_i32 s24, s67, s31
	global_load_lds_dwordx4 v[166:167], off
	v_lshl_add_u64 v[166:167], s[22:23], 0, v[130:131]
	s_mov_b32 m0, s24
	s_nop 0
	global_load_lds_dwordx4 v[166:167], off
	v_lshl_add_u64 v[166:167], s[22:23], 0, v[134:135]
	s_add_i32 m0, s24, 0x2000
	s_nop 0
	global_load_lds_dwordx4 v[166:167], off
	v_lshl_add_u64 v[166:167], v[246:247], 0, s[6:7]
	s_mov_b32 m0, s48
	s_nop 0
	global_load_lds_dwordx4 v[166:167], off
	v_lshl_add_u64 v[166:167], v[248:249], 0, s[6:7]
	s_mov_b32 m0, s49
	s_nop 0
	global_load_lds_dwordx4 v[166:167], off
	s_waitcnt vmcnt(8)
	s_waitcnt lgkmcnt(0)
	s_setprio 1
	s_barrier
	v_mfma_f32_16x16x32_bf16 v[60:63], v[148:151], v[212:215], v[60:63]
	v_mfma_f32_16x16x32_bf16 v[56:59], v[156:159], v[212:215], v[56:59]
	v_mfma_f32_16x16x32_bf16 v[48:51], v[148:151], v[220:223], v[48:51]
	v_mfma_f32_16x16x32_bf16 v[40:43], v[156:159], v[220:223], v[40:43]
	v_mfma_f32_16x16x32_bf16 v[32:35], v[148:151], v[228:231], v[32:35]
	v_mfma_f32_16x16x32_bf16 v[24:27], v[156:159], v[228:231], v[24:27]
	v_mfma_f32_16x16x32_bf16 v[16:19], v[148:151], v[236:239], v[16:19]
	v_mfma_f32_16x16x32_bf16 v[8:11], v[156:159], v[236:239], v[8:11]
	v_mfma_f32_16x16x32_bf16 v[60:63], v[152:155], v[216:219], v[60:63]
	v_mfma_f32_16x16x32_bf16 v[56:59], v[160:163], v[216:219], v[56:59]
	v_mfma_f32_16x16x32_bf16 v[48:51], v[152:155], v[224:227], v[48:51]
	v_mfma_f32_16x16x32_bf16 v[40:43], v[160:163], v[224:227], v[40:43]
	v_mfma_f32_16x16x32_bf16 v[32:35], v[152:155], v[232:235], v[32:35]
	v_mfma_f32_16x16x32_bf16 v[24:27], v[160:163], v[232:235], v[24:27]
	v_mfma_f32_16x16x32_bf16 v[16:19], v[152:155], v[240:243], v[16:19]
	v_mfma_f32_16x16x32_bf16 v[8:11], v[160:163], v[240:243], v[8:11]
	v_mfma_f32_16x16x32_bf16 v[52:55], v[196:199], v[212:215], v[52:55]
	v_mfma_f32_16x16x32_bf16 v[44:47], v[204:207], v[212:215], v[44:47]
	v_mfma_f32_16x16x32_bf16 v[36:39], v[196:199], v[220:223], v[36:39]
	v_mfma_f32_16x16x32_bf16 v[28:31], v[204:207], v[220:223], v[28:31]
	v_mfma_f32_16x16x32_bf16 v[20:23], v[196:199], v[228:231], v[20:23]
	v_mfma_f32_16x16x32_bf16 v[12:15], v[204:207], v[228:231], v[12:15]
	v_mfma_f32_16x16x32_bf16 v[4:7], v[196:199], v[236:239], v[4:7]
	v_mfma_f32_16x16x32_bf16 v[0:3], v[204:207], v[236:239], v[0:3]
	v_mfma_f32_16x16x32_bf16 v[52:55], v[200:203], v[216:219], v[52:55]
	v_mfma_f32_16x16x32_bf16 v[44:47], v[208:211], v[216:219], v[44:47]
	v_mfma_f32_16x16x32_bf16 v[36:39], v[200:203], v[224:227], v[36:39]
	v_mfma_f32_16x16x32_bf16 v[28:31], v[208:211], v[224:227], v[28:31]
	v_mfma_f32_16x16x32_bf16 v[20:23], v[200:203], v[232:235], v[20:23]
	v_mfma_f32_16x16x32_bf16 v[12:15], v[208:211], v[232:235], v[12:15]
	v_mfma_f32_16x16x32_bf16 v[4:7], v[200:203], v[240:243], v[4:7]
	v_mfma_f32_16x16x32_bf16 v[0:3], v[208:211], v[240:243], v[0:3]
	s_barrier
	s_setprio 0
	s_add_i32 s65, s65, 2
	s_add_u32 s20, s20, 0x100
	s_addc_u32 s21, s21, 0
	s_add_u32 s63, s63, 0x100
	s_addc_u32 s64, s64, 0
	s_cmp_gt_u32 s65, 13
	s_cbranch_scc0 .LBB0_264
	s_and_b64 vcc, exec, s[8:9]
	s_cbranch_vccz .LBB0_267
	s_barrier

.LBB0_280:
	ds_read_b128 v[158:161], v154
	ds_read_b128 v[182:185], v154 offset:1024
	ds_read_b128 v[186:189], v154 offset:2048
	ds_read_b128 v[190:193], v154 offset:3072
	ds_read_b128 v[194:197], v155
	ds_read_b128 v[198:201], v155 offset:1024
	ds_read_b128 v[202:205], v155 offset:2048
	ds_read_b128 v[206:209], v155 offset:3072
	s_add_u32 s26, s24, 0xfffc0080
	s_addc_u32 s27, s25, -1
	s_cmp_eq_u32 s70, 12
	s_cselect_b32 s27, s39, s27
	s_cselect_b32 s26, s67, s26
	s_cselect_b32 s73, s19, s69
	s_cselect_b32 s72, s18, s68
	s_mov_b32 m0, s61
	v_lshl_add_u64 v[162:163], s[24:25], 0, v[144:145]
	ds_read_b128 v[210:213], v156
	ds_read_b128 v[214:217], v156 offset:1024
	ds_read_b128 v[218:221], v156 offset:2048
	ds_read_b128 v[222:225], v156 offset:3072
	ds_read_b128 v[226:229], v156 offset:4096
	ds_read_b128 v[230:233], v156 offset:5120
	ds_read_b128 v[234:237], v156 offset:6144
	ds_read_b128 v[238:241], v156 offset:7168
	global_load_lds_dwordx4 v[162:163], off
	v_lshl_add_u64 v[162:163], s[24:25], 0, v[146:147]
	s_mov_b32 m0, s62
	s_nop 0
	global_load_lds_dwordx4 v[162:163], off
	s_waitcnt vmcnt(8)
	s_waitcnt lgkmcnt(0)
	s_setprio 1
	s_barrier
	v_mfma_f32_16x16x32_bf16 v[124:127], v[158:161], v[210:213], v[124:127]
	v_mfma_f32_16x16x32_bf16 v[120:123], v[186:189], v[210:213], v[120:123]
	v_mfma_f32_16x16x32_bf16 v[112:115], v[158:161], v[218:221], v[112:115]
	v_mfma_f32_16x16x32_bf16 v[104:107], v[186:189], v[218:221], v[104:107]
	v_mfma_f32_16x16x32_bf16 v[96:99], v[158:161], v[226:229], v[96:99]
	v_mfma_f32_16x16x32_bf16 v[88:91], v[186:189], v[226:229], v[88:91]
	v_mfma_f32_16x16x32_bf16 v[80:83], v[158:161], v[234:237], v[80:83]
	v_mfma_f32_16x16x32_bf16 v[72:75], v[186:189], v[234:237], v[72:75]
	v_mfma_f32_16x16x32_bf16 v[124:127], v[182:185], v[214:217], v[124:127]
	v_mfma_f32_16x16x32_bf16 v[120:123], v[190:193], v[214:217], v[120:123]
	v_mfma_f32_16x16x32_bf16 v[112:115], v[182:185], v[222:225], v[112:115]
	v_mfma_f32_16x16x32_bf16 v[104:107], v[190:193], v[222:225], v[104:107]
	v_mfma_f32_16x16x32_bf16 v[96:99], v[182:185], v[230:233], v[96:99]
	v_mfma_f32_16x16x32_bf16 v[88:91], v[190:193], v[230:233], v[88:91]
	v_mfma_f32_16x16x32_bf16 v[80:83], v[182:185], v[238:241], v[80:83]
	v_mfma_f32_16x16x32_bf16 v[72:75], v[190:193], v[238:241], v[72:75]
	v_mfma_f32_16x16x32_bf16 v[116:119], v[194:197], v[210:213], v[116:119]
	v_mfma_f32_16x16x32_bf16 v[108:111], v[202:205], v[210:213], v[108:111]
	v_mfma_f32_16x16x32_bf16 v[100:103], v[194:197], v[218:221], v[100:103]
	v_mfma_f32_16x16x32_bf16 v[92:95], v[202:205], v[218:221], v[92:95]
	v_mfma_f32_16x16x32_bf16 v[84:87], v[194:197], v[226:229], v[84:87]
	v_mfma_f32_16x16x32_bf16 v[76:79], v[202:205], v[226:229], v[76:79]
	v_mfma_f32_16x16x32_bf16 v[68:71], v[194:197], v[234:237], v[68:71]
	v_mfma_f32_16x16x32_bf16 v[64:67], v[202:205], v[234:237], v[64:67]
	v_mfma_f32_16x16x32_bf16 v[116:119], v[198:201], v[214:217], v[116:119]
	v_mfma_f32_16x16x32_bf16 v[108:111], v[206:209], v[214:217], v[108:111]
	v_mfma_f32_16x16x32_bf16 v[100:103], v[198:201], v[222:225], v[100:103]
	v_mfma_f32_16x16x32_bf16 v[92:95], v[206:209], v[222:225], v[92:95]
	v_mfma_f32_16x16x32_bf16 v[84:87], v[198:201], v[230:233], v[84:87]
	v_mfma_f32_16x16x32_bf16 v[76:79], v[206:209], v[230:233], v[76:79]
	v_mfma_f32_16x16x32_bf16 v[68:71], v[198:201], v[238:241], v[68:71]
	v_mfma_f32_16x16x32_bf16 v[64:67], v[206:209], v[238:241], v[64:67]
	s_barrier
	s_setprio 0
	s_mov_b32 m0, s63
	v_lshl_add_u64 v[162:163], s[72:73], 0, v[140:141]
	ds_read_b128 v[210:213], v156 offset:16384
	ds_read_b128 v[214:217], v156 offset:17408
	ds_read_b128 v[218:221], v156 offset:18432
	ds_read_b128 v[222:225], v156 offset:19456
	ds_read_b128 v[226:229], v156 offset:20480
	ds_read_b128 v[230:233], v156 offset:21504
	ds_read_b128 v[234:237], v156 offset:22528
	ds_read_b128 v[238:241], v156 offset:23552
	global_load_lds_dwordx4 v[162:163], off
	v_lshl_add_u64 v[166:167], s[72:73], 0, v[138:139]
	s_mov_b32 m0, s64
	v_lshl_add_u64 v[178:179], v[162:163], 0, s[4:5]
	global_load_lds_dwordx4 v[166:167], off
	s_mov_b32 m0, s65
	v_lshl_add_u64 v[242:243], s[26:27], 0, v[132:133]
	global_load_lds_dwordx4 v[178:179], off
	v_lshl_add_u64 v[178:179], v[166:167], 0, s[4:5]
	s_add_i32 m0, s65, 0x2000
	s_nop 0
	global_load_lds_dwordx4 v[178:179], off
	v_lshl_add_u64 v[178:179], s[26:27], 0, v[128:129]
	s_mov_b32 m0, s44
	s_nop 0
	global_load_lds_dwordx4 v[178:179], off
	s_mov_b32 m0, s45
	s_nop 0
	global_load_lds_dwordx4 v[242:243], off
	s_waitcnt vmcnt(8)
	s_waitcnt lgkmcnt(0)
	s_setprio 1
	s_barrier
	v_mfma_f32_16x16x32_bf16 v[60:63], v[158:161], v[210:213], v[60:63]
	v_mfma_f32_16x16x32_bf16 v[56:59], v[186:189], v[210:213], v[56:59]
	v_mfma_f32_16x16x32_bf16 v[48:51], v[158:161], v[218:221], v[48:51]
	v_mfma_f32_16x16x32_bf16 v[40:43], v[186:189], v[218:221], v[40:43]
	v_mfma_f32_16x16x32_bf16 v[32:35], v[158:161], v[226:229], v[32:35]
	v_mfma_f32_16x16x32_bf16 v[24:27], v[186:189], v[226:229], v[24:27]
	v_mfma_f32_16x16x32_bf16 v[16:19], v[158:161], v[234:237], v[16:19]
	v_mfma_f32_16x16x32_bf16 v[8:11], v[186:189], v[234:237], v[8:11]
	v_mfma_f32_16x16x32_bf16 v[60:63], v[182:185], v[214:217], v[60:63]
	v_mfma_f32_16x16x32_bf16 v[56:59], v[190:193], v[214:217], v[56:59]
	v_mfma_f32_16x16x32_bf16 v[48:51], v[182:185], v[222:225], v[48:51]
	v_mfma_f32_16x16x32_bf16 v[40:43], v[190:193], v[222:225], v[40:43]
	v_mfma_f32_16x16x32_bf16 v[32:35], v[182:185], v[230:233], v[32:35]
	v_mfma_f32_16x16x32_bf16 v[24:27], v[190:193], v[230:233], v[24:27]
	v_mfma_f32_16x16x32_bf16 v[16:19], v[182:185], v[238:241], v[16:19]
	v_mfma_f32_16x16x32_bf16 v[8:11], v[190:193], v[238:241], v[8:11]
	v_mfma_f32_16x16x32_bf16 v[52:55], v[194:197], v[210:213], v[52:55]
	v_mfma_f32_16x16x32_bf16 v[44:47], v[202:205], v[210:213], v[44:47]
	v_mfma_f32_16x16x32_bf16 v[36:39], v[194:197], v[218:221], v[36:39]
	v_mfma_f32_16x16x32_bf16 v[28:31], v[202:205], v[218:221], v[28:31]
	v_mfma_f32_16x16x32_bf16 v[20:23], v[194:197], v[226:229], v[20:23]
	v_mfma_f32_16x16x32_bf16 v[12:15], v[202:205], v[226:229], v[12:15]
	v_mfma_f32_16x16x32_bf16 v[4:7], v[194:197], v[234:237], v[4:7]
	v_mfma_f32_16x16x32_bf16 v[0:3], v[202:205], v[234:237], v[0:3]
	v_mfma_f32_16x16x32_bf16 v[52:55], v[198:201], v[214:217], v[52:55]
	v_mfma_f32_16x16x32_bf16 v[44:47], v[206:209], v[214:217], v[44:47]
	v_mfma_f32_16x16x32_bf16 v[36:39], v[198:201], v[222:225], v[36:39]
	v_mfma_f32_16x16x32_bf16 v[28:31], v[206:209], v[222:225], v[28:31]
	v_mfma_f32_16x16x32_bf16 v[20:23], v[198:201], v[230:233], v[20:23]
	v_mfma_f32_16x16x32_bf16 v[12:15], v[206:209], v[230:233], v[12:15]
	v_mfma_f32_16x16x32_bf16 v[4:7], v[198:201], v[238:241], v[4:7]
	v_mfma_f32_16x16x32_bf16 v[0:3], v[206:209], v[238:241], v[0:3]
	s_barrier
	s_setprio 0
	s_add_i32 s71, 0, 0x18000
	v_add_u32_e32 v157, s71, v131
	s_add_i32 s72, 0, 0x1c000
	ds_read_b128 v[158:161], v157
	ds_read_b128 v[182:185], v157 offset:1024
	ds_read_b128 v[186:189], v157 offset:2048
	ds_read_b128 v[190:193], v157 offset:3072
	v_add_u32_e32 v157, s72, v131
	ds_read_b128 v[194:197], v157
	ds_read_b128 v[198:201], v157 offset:1024
	ds_read_b128 v[202:205], v157 offset:2048
	ds_read_b128 v[206:209], v157 offset:3072
	s_add_u32 s26, s26, 0x40000
	s_addc_u32 s27, s27, 0
	s_mov_b32 m0, s48
	v_lshl_add_u64 v[244:245], s[26:27], 0, v[128:129]
	ds_read_b128 v[210:213], v156 offset:32768
	ds_read_b128 v[214:217], v156 offset:33792
	ds_read_b128 v[218:221], v156 offset:34816
	ds_read_b128 v[222:225], v156 offset:35840
	ds_read_b128 v[226:229], v156 offset:36864
	ds_read_b128 v[230:233], v156 offset:37888
	ds_read_b128 v[234:237], v156 offset:38912
	ds_read_b128 v[238:241], v156 offset:39936
	global_load_lds_dwordx4 v[244:245], off
	v_lshl_add_u64 v[244:245], s[26:27], 0, v[132:133]
	s_mov_b32 m0, s49
	s_nop 0
	global_load_lds_dwordx4 v[244:245], off
	s_waitcnt vmcnt(8)
	s_waitcnt lgkmcnt(0)
	s_setprio 1
	s_barrier
	v_mfma_f32_16x16x32_bf16 v[124:127], v[158:161], v[210:213], v[124:127]
	v_mfma_f32_16x16x32_bf16 v[120:123], v[186:189], v[210:213], v[120:123]
	v_mfma_f32_16x16x32_bf16 v[112:115], v[158:161], v[218:221], v[112:115]
	v_mfma_f32_16x16x32_bf16 v[104:107], v[186:189], v[218:221], v[104:107]
	v_mfma_f32_16x16x32_bf16 v[96:99], v[158:161], v[226:229], v[96:99]
	v_mfma_f32_16x16x32_bf16 v[88:91], v[186:189], v[226:229], v[88:91]
	v_mfma_f32_16x16x32_bf16 v[80:83], v[158:161], v[234:237], v[80:83]
	v_mfma_f32_16x16x32_bf16 v[72:75], v[186:189], v[234:237], v[72:75]
	v_mfma_f32_16x16x32_bf16 v[124:127], v[182:185], v[214:217], v[124:127]
	v_mfma_f32_16x16x32_bf16 v[120:123], v[190:193], v[214:217], v[120:123]
	v_mfma_f32_16x16x32_bf16 v[112:115], v[182:185], v[222:225], v[112:115]
	v_mfma_f32_16x16x32_bf16 v[104:107], v[190:193], v[222:225], v[104:107]
	v_mfma_f32_16x16x32_bf16 v[96:99], v[182:185], v[230:233], v[96:99]
	v_mfma_f32_16x16x32_bf16 v[88:91], v[190:193], v[230:233], v[88:91]
	v_mfma_f32_16x16x32_bf16 v[80:83], v[182:185], v[238:241], v[80:83]
	v_mfma_f32_16x16x32_bf16 v[72:75], v[190:193], v[238:241], v[72:75]
	v_mfma_f32_16x16x32_bf16 v[116:119], v[194:197], v[210:213], v[116:119]
	v_mfma_f32_16x16x32_bf16 v[108:111], v[202:205], v[210:213], v[108:111]
	v_mfma_f32_16x16x32_bf16 v[100:103], v[194:197], v[218:221], v[100:103]
	v_mfma_f32_16x16x32_bf16 v[92:95], v[202:205], v[218:221], v[92:95]
	v_mfma_f32_16x16x32_bf16 v[84:87], v[194:197], v[226:229], v[84:87]
	v_mfma_f32_16x16x32_bf16 v[76:79], v[202:205], v[226:229], v[76:79]
	v_mfma_f32_16x16x32_bf16 v[68:71], v[194:197], v[234:237], v[68:71]
	v_mfma_f32_16x16x32_bf16 v[64:67], v[202:205], v[234:237], v[64:67]
	v_mfma_f32_16x16x32_bf16 v[116:119], v[198:201], v[214:217], v[116:119]
	v_mfma_f32_16x16x32_bf16 v[108:111], v[206:209], v[214:217], v[108:111]
	v_mfma_f32_16x16x32_bf16 v[100:103], v[198:201], v[222:225], v[100:103]
	v_mfma_f32_16x16x32_bf16 v[92:95], v[206:209], v[222:225], v[92:95]
	v_mfma_f32_16x16x32_bf16 v[84:87], v[198:201], v[230:233], v[84:87]
	v_mfma_f32_16x16x32_bf16 v[76:79], v[206:209], v[230:233], v[76:79]
	v_mfma_f32_16x16x32_bf16 v[68:71], v[198:201], v[238:241], v[68:71]
	v_mfma_f32_16x16x32_bf16 v[64:67], v[206:209], v[238:241], v[64:67]
	s_barrier
	s_setprio 0
	s_add_i32 s26, s71, s37
	v_lshl_add_u64 v[244:245], v[162:163], 0, s[12:13]
	s_mov_b32 m0, s26
	ds_read_b128 v[210:213], v156 offset:49152
	ds_read_b128 v[214:217], v156 offset:50176
	ds_read_b128 v[218:221], v156 offset:51200
	ds_read_b128 v[222:225], v156 offset:52224
	ds_read_b128 v[226:229], v156 offset:53248
	ds_read_b128 v[230:233], v156 offset:54272
	ds_read_b128 v[234:237], v156 offset:55296
	ds_read_b128 v[238:241], v156 offset:56320
	global_load_lds_dwordx4 v[244:245], off
	v_lshl_add_u64 v[244:245], v[166:167], 0, s[12:13]
	s_add_i32 m0, s26, 0x2000
	s_add_i32 s26, s72, s37
	global_load_lds_dwordx4 v[244:245], off
	v_lshl_add_u64 v[162:163], v[162:163], 0, s[14:15]
	s_mov_b32 m0, s26
	s_nop 0
	global_load_lds_dwordx4 v[162:163], off
	v_lshl_add_u64 v[162:163], v[166:167], 0, s[14:15]
	s_add_i32 m0, s26, 0x2000
	s_nop 0
	global_load_lds_dwordx4 v[162:163], off
	v_lshl_add_u64 v[162:163], v[178:179], 0, s[12:13]
	s_mov_b32 m0, s50
	s_nop 0
	global_load_lds_dwordx4 v[162:163], off
	v_lshl_add_u64 v[162:163], v[242:243], 0, s[12:13]
	s_mov_b32 m0, s51
	s_nop 0
	global_load_lds_dwordx4 v[162:163], off
	s_waitcnt vmcnt(8)
	s_waitcnt lgkmcnt(0)
	s_setprio 1
	s_barrier
	v_mfma_f32_16x16x32_bf16 v[60:63], v[158:161], v[210:213], v[60:63]
	v_mfma_f32_16x16x32_bf16 v[56:59], v[186:189], v[210:213], v[56:59]
	v_mfma_f32_16x16x32_bf16 v[48:51], v[158:161], v[218:221], v[48:51]
	v_mfma_f32_16x16x32_bf16 v[40:43], v[186:189], v[218:221], v[40:43]
	v_mfma_f32_16x16x32_bf16 v[32:35], v[158:161], v[226:229], v[32:35]
	v_mfma_f32_16x16x32_bf16 v[24:27], v[186:189], v[226:229], v[24:27]
	v_mfma_f32_16x16x32_bf16 v[16:19], v[158:161], v[234:237], v[16:19]
	v_mfma_f32_16x16x32_bf16 v[8:11], v[186:189], v[234:237], v[8:11]
	v_mfma_f32_16x16x32_bf16 v[60:63], v[182:185], v[214:217], v[60:63]
	v_mfma_f32_16x16x32_bf16 v[56:59], v[190:193], v[214:217], v[56:59]
	v_mfma_f32_16x16x32_bf16 v[48:51], v[182:185], v[222:225], v[48:51]
	v_mfma_f32_16x16x32_bf16 v[40:43], v[190:193], v[222:225], v[40:43]
	v_mfma_f32_16x16x32_bf16 v[32:35], v[182:185], v[230:233], v[32:35]
	v_mfma_f32_16x16x32_bf16 v[24:27], v[190:193], v[230:233], v[24:27]
	v_mfma_f32_16x16x32_bf16 v[16:19], v[182:185], v[238:241], v[16:19]
	v_mfma_f32_16x16x32_bf16 v[8:11], v[190:193], v[238:241], v[8:11]
	v_mfma_f32_16x16x32_bf16 v[52:55], v[194:197], v[210:213], v[52:55]
	v_mfma_f32_16x16x32_bf16 v[44:47], v[202:205], v[210:213], v[44:47]
	v_mfma_f32_16x16x32_bf16 v[36:39], v[194:197], v[218:221], v[36:39]
	v_mfma_f32_16x16x32_bf16 v[28:31], v[202:205], v[218:221], v[28:31]
	v_mfma_f32_16x16x32_bf16 v[20:23], v[194:197], v[226:229], v[20:23]
	v_mfma_f32_16x16x32_bf16 v[12:15], v[202:205], v[226:229], v[12:15]
	v_mfma_f32_16x16x32_bf16 v[4:7], v[194:197], v[234:237], v[4:7]
	v_mfma_f32_16x16x32_bf16 v[0:3], v[202:205], v[234:237], v[0:3]
	v_mfma_f32_16x16x32_bf16 v[52:55], v[198:201], v[214:217], v[52:55]
	v_mfma_f32_16x16x32_bf16 v[44:47], v[206:209], v[214:217], v[44:47]
	v_mfma_f32_16x16x32_bf16 v[36:39], v[198:201], v[222:225], v[36:39]
	v_mfma_f32_16x16x32_bf16 v[28:31], v[206:209], v[222:225], v[28:31]
	v_mfma_f32_16x16x32_bf16 v[20:23], v[198:201], v[230:233], v[20:23]
	v_mfma_f32_16x16x32_bf16 v[12:15], v[206:209], v[230:233], v[12:15]
	v_mfma_f32_16x16x32_bf16 v[4:7], v[198:201], v[238:241], v[4:7]
	v_mfma_f32_16x16x32_bf16 v[0:3], v[206:209], v[238:241], v[0:3]
	s_barrier
	s_setprio 0
	s_add_i32 s70, s70, 2
	s_add_u32 s24, s24, 0x100
	s_addc_u32 s25, s25, 0
	s_add_u32 s68, s68, 0x100
	s_addc_u32 s69, s69, 0
	s_cmp_gt_u32 s70, 13
	s_cbranch_scc0 .LBB0_280
	s_and_b64 vcc, exec, s[16:17]
	s_cbranch_vccz .LBB0_283
	s_barrier

.LBB0_296:
	ds_read_b128 v[156:159], v153
	ds_read_b128 v[160:163], v153 offset:1024
	ds_read_b128 v[174:177], v153 offset:2048
	ds_read_b128 v[182:185], v153 offset:3072
	ds_read_b128 v[186:189], v154
	ds_read_b128 v[190:193], v154 offset:1024
	ds_read_b128 v[194:197], v154 offset:2048
	ds_read_b128 v[198:201], v154 offset:3072
	s_add_u32 s22, s20, 0xfffc0080
	s_addc_u32 s23, s21, -1
	s_cmp_eq_u32 s65, 12
	s_cselect_b32 s25, s4, s23
	s_cselect_b32 s24, s38, s22
	s_cselect_b32 s23, s15, s64
	s_cselect_b32 s22, s14, s39
	s_mov_b32 m0, s62
	v_lshl_add_u64 v[166:167], s[20:21], 0, v[144:145]
	ds_read_b128 v[202:205], v155
	ds_read_b128 v[206:209], v155 offset:1024
	ds_read_b128 v[210:213], v155 offset:2048
	ds_read_b128 v[214:217], v155 offset:3072
	ds_read_b128 v[218:221], v155 offset:4096
	ds_read_b128 v[222:225], v155 offset:5120
	ds_read_b128 v[226:229], v155 offset:6144
	ds_read_b128 v[230:233], v155 offset:7168
	global_load_lds_dwordx4 v[166:167], off
	v_lshl_add_u64 v[166:167], s[20:21], 0, v[146:147]
	s_add_i32 m0, s27, 0xe000
	s_nop 0
	global_load_lds_dwordx4 v[166:167], off
	s_waitcnt vmcnt(8)
	s_waitcnt lgkmcnt(0)
	s_setprio 1
	s_barrier
	v_mfma_f32_16x16x32_bf16 v[124:127], v[156:159], v[202:205], v[124:127]
	v_mfma_f32_16x16x32_bf16 v[120:123], v[174:177], v[202:205], v[120:123]
	v_mfma_f32_16x16x32_bf16 v[112:115], v[156:159], v[210:213], v[112:115]
	v_mfma_f32_16x16x32_bf16 v[104:107], v[174:177], v[210:213], v[104:107]
	v_mfma_f32_16x16x32_bf16 v[96:99], v[156:159], v[218:221], v[96:99]
	v_mfma_f32_16x16x32_bf16 v[88:91], v[174:177], v[218:221], v[88:91]
	v_mfma_f32_16x16x32_bf16 v[80:83], v[156:159], v[226:229], v[80:83]
	v_mfma_f32_16x16x32_bf16 v[72:75], v[174:177], v[226:229], v[72:75]
	v_mfma_f32_16x16x32_bf16 v[124:127], v[160:163], v[206:209], v[124:127]
	v_mfma_f32_16x16x32_bf16 v[120:123], v[182:185], v[206:209], v[120:123]
	v_mfma_f32_16x16x32_bf16 v[112:115], v[160:163], v[214:217], v[112:115]
	v_mfma_f32_16x16x32_bf16 v[104:107], v[182:185], v[214:217], v[104:107]
	v_mfma_f32_16x16x32_bf16 v[96:99], v[160:163], v[222:225], v[96:99]
	v_mfma_f32_16x16x32_bf16 v[88:91], v[182:185], v[222:225], v[88:91]
	v_mfma_f32_16x16x32_bf16 v[80:83], v[160:163], v[230:233], v[80:83]
	v_mfma_f32_16x16x32_bf16 v[72:75], v[182:185], v[230:233], v[72:75]
	v_mfma_f32_16x16x32_bf16 v[116:119], v[186:189], v[202:205], v[116:119]
	v_mfma_f32_16x16x32_bf16 v[108:111], v[194:197], v[202:205], v[108:111]
	v_mfma_f32_16x16x32_bf16 v[100:103], v[186:189], v[210:213], v[100:103]
	v_mfma_f32_16x16x32_bf16 v[92:95], v[194:197], v[210:213], v[92:95]
	v_mfma_f32_16x16x32_bf16 v[84:87], v[186:189], v[218:221], v[84:87]
	v_mfma_f32_16x16x32_bf16 v[76:79], v[194:197], v[218:221], v[76:79]
	v_mfma_f32_16x16x32_bf16 v[68:71], v[186:189], v[226:229], v[68:71]
	v_mfma_f32_16x16x32_bf16 v[64:67], v[194:197], v[226:229], v[64:67]
	v_mfma_f32_16x16x32_bf16 v[116:119], v[190:193], v[206:209], v[116:119]
	v_mfma_f32_16x16x32_bf16 v[108:111], v[198:201], v[206:209], v[108:111]
	v_mfma_f32_16x16x32_bf16 v[100:103], v[190:193], v[214:217], v[100:103]
	v_mfma_f32_16x16x32_bf16 v[92:95], v[198:201], v[214:217], v[92:95]
	v_mfma_f32_16x16x32_bf16 v[84:87], v[190:193], v[222:225], v[84:87]
	v_mfma_f32_16x16x32_bf16 v[76:79], v[198:201], v[222:225], v[76:79]
	v_mfma_f32_16x16x32_bf16 v[68:71], v[190:193], v[230:233], v[68:71]
	v_mfma_f32_16x16x32_bf16 v[64:67], v[198:201], v[230:233], v[64:67]
	s_barrier
	s_setprio 0
	s_add_i32 s66, s60, s26
	v_lshl_add_u64 v[166:167], s[22:23], 0, v[140:141]
	s_mov_b32 m0, s66
	ds_read_b128 v[202:205], v155 offset:16384
	ds_read_b128 v[206:209], v155 offset:17408
	ds_read_b128 v[210:213], v155 offset:18432
	ds_read_b128 v[214:217], v155 offset:19456
	ds_read_b128 v[218:221], v155 offset:20480
	ds_read_b128 v[222:225], v155 offset:21504
	ds_read_b128 v[226:229], v155 offset:22528
	ds_read_b128 v[230:233], v155 offset:23552
	global_load_lds_dwordx4 v[166:167], off
	s_add_i32 m0, s66, 0x2000
	s_add_u32 s66, s22, 0x1000
	v_lshl_add_u64 v[178:179], s[22:23], 0, v[138:139]
	s_addc_u32 s67, s23, 0
	s_add_i32 s68, s61, s26
	global_load_lds_dwordx4 v[178:179], off
	v_lshl_add_u64 v[234:235], s[66:67], 0, v[140:141]
	s_mov_b32 m0, s68
	v_lshl_add_u64 v[236:237], s[24:25], 0, v[132:133]
	global_load_lds_dwordx4 v[234:235], off
	v_lshl_add_u64 v[234:235], s[66:67], 0, v[138:139]
	s_add_i32 m0, s68, 0x2000
	s_nop 0
	global_load_lds_dwordx4 v[234:235], off
	v_lshl_add_u64 v[234:235], s[24:25], 0, v[128:129]
	s_mov_b32 m0, s27
	s_nop 0
	global_load_lds_dwordx4 v[234:235], off
	s_mov_b32 m0, s37
	s_nop 0
	global_load_lds_dwordx4 v[236:237], off
	s_waitcnt vmcnt(8)
	s_waitcnt lgkmcnt(0)
	s_setprio 1
	s_barrier
	v_mfma_f32_16x16x32_bf16 v[60:63], v[156:159], v[202:205], v[60:63]
	v_mfma_f32_16x16x32_bf16 v[56:59], v[174:177], v[202:205], v[56:59]
	v_mfma_f32_16x16x32_bf16 v[48:51], v[156:159], v[210:213], v[48:51]
	v_mfma_f32_16x16x32_bf16 v[40:43], v[174:177], v[210:213], v[40:43]
	v_mfma_f32_16x16x32_bf16 v[32:35], v[156:159], v[218:221], v[32:35]
	v_mfma_f32_16x16x32_bf16 v[24:27], v[174:177], v[218:221], v[24:27]
	v_mfma_f32_16x16x32_bf16 v[16:19], v[156:159], v[226:229], v[16:19]
	v_mfma_f32_16x16x32_bf16 v[8:11], v[174:177], v[226:229], v[8:11]
	v_mfma_f32_16x16x32_bf16 v[60:63], v[160:163], v[206:209], v[60:63]
	v_mfma_f32_16x16x32_bf16 v[56:59], v[182:185], v[206:209], v[56:59]
	v_mfma_f32_16x16x32_bf16 v[48:51], v[160:163], v[214:217], v[48:51]
	v_mfma_f32_16x16x32_bf16 v[40:43], v[182:185], v[214:217], v[40:43]
	v_mfma_f32_16x16x32_bf16 v[32:35], v[160:163], v[222:225], v[32:35]
	v_mfma_f32_16x16x32_bf16 v[24:27], v[182:185], v[222:225], v[24:27]
	v_mfma_f32_16x16x32_bf16 v[16:19], v[160:163], v[230:233], v[16:19]
	v_mfma_f32_16x16x32_bf16 v[8:11], v[182:185], v[230:233], v[8:11]
	v_mfma_f32_16x16x32_bf16 v[52:55], v[186:189], v[202:205], v[52:55]
	v_mfma_f32_16x16x32_bf16 v[44:47], v[194:197], v[202:205], v[44:47]
	v_mfma_f32_16x16x32_bf16 v[36:39], v[186:189], v[210:213], v[36:39]
	v_mfma_f32_16x16x32_bf16 v[28:31], v[194:197], v[210:213], v[28:31]
	v_mfma_f32_16x16x32_bf16 v[20:23], v[186:189], v[218:221], v[20:23]
	v_mfma_f32_16x16x32_bf16 v[12:15], v[194:197], v[218:221], v[12:15]
	v_mfma_f32_16x16x32_bf16 v[4:7], v[186:189], v[226:229], v[4:7]
	v_mfma_f32_16x16x32_bf16 v[0:3], v[194:197], v[226:229], v[0:3]
	v_mfma_f32_16x16x32_bf16 v[52:55], v[190:193], v[206:209], v[52:55]
	v_mfma_f32_16x16x32_bf16 v[44:47], v[198:201], v[206:209], v[44:47]
	v_mfma_f32_16x16x32_bf16 v[36:39], v[190:193], v[214:217], v[36:39]
	v_mfma_f32_16x16x32_bf16 v[28:31], v[198:201], v[214:217], v[28:31]
	v_mfma_f32_16x16x32_bf16 v[20:23], v[190:193], v[222:225], v[20:23]
	v_mfma_f32_16x16x32_bf16 v[12:15], v[198:201], v[222:225], v[12:15]
	v_mfma_f32_16x16x32_bf16 v[4:7], v[190:193], v[230:233], v[4:7]
	v_mfma_f32_16x16x32_bf16 v[0:3], v[198:201], v[230:233], v[0:3]
	s_barrier
	s_setprio 0
	s_add_i32 s66, 0, 0x18000
	v_add_u32_e32 v181, s66, v131
	s_add_i32 s67, 0, 0x1c000
	ds_read_b128 v[156:159], v181
	ds_read_b128 v[160:163], v181 offset:1024
	ds_read_b128 v[174:177], v181 offset:2048
	ds_read_b128 v[182:185], v181 offset:3072
	v_add_u32_e32 v181, s67, v131
	ds_read_b128 v[186:189], v181
	ds_read_b128 v[190:193], v181 offset:1024
	ds_read_b128 v[194:197], v181 offset:2048
	ds_read_b128 v[198:201], v181 offset:3072
	s_add_u32 s24, s24, 0x40000
	s_addc_u32 s25, s25, 0
	s_mov_b32 m0, s44
	v_lshl_add_u64 v[238:239], s[24:25], 0, v[128:129]
	ds_read_b128 v[202:205], v155 offset:32768
	ds_read_b128 v[206:209], v155 offset:33792
	ds_read_b128 v[210:213], v155 offset:34816
	ds_read_b128 v[214:217], v155 offset:35840
	ds_read_b128 v[218:221], v155 offset:36864
	ds_read_b128 v[222:225], v155 offset:37888
	ds_read_b128 v[226:229], v155 offset:38912
	ds_read_b128 v[230:233], v155 offset:39936
	global_load_lds_dwordx4 v[238:239], off
	v_lshl_add_u64 v[238:239], s[24:25], 0, v[132:133]
	s_mov_b32 m0, s45
	s_nop 0
	global_load_lds_dwordx4 v[238:239], off
	s_waitcnt vmcnt(8)
	s_waitcnt lgkmcnt(0)
	s_setprio 1
	s_barrier
	v_mfma_f32_16x16x32_bf16 v[124:127], v[156:159], v[202:205], v[124:127]
	v_mfma_f32_16x16x32_bf16 v[120:123], v[174:177], v[202:205], v[120:123]
	v_mfma_f32_16x16x32_bf16 v[112:115], v[156:159], v[210:213], v[112:115]
	v_mfma_f32_16x16x32_bf16 v[104:107], v[174:177], v[210:213], v[104:107]
	v_mfma_f32_16x16x32_bf16 v[96:99], v[156:159], v[218:221], v[96:99]
	v_mfma_f32_16x16x32_bf16 v[88:91], v[174:177], v[218:221], v[88:91]
	v_mfma_f32_16x16x32_bf16 v[80:83], v[156:159], v[226:229], v[80:83]
	v_mfma_f32_16x16x32_bf16 v[72:75], v[174:177], v[226:229], v[72:75]
	v_mfma_f32_16x16x32_bf16 v[124:127], v[160:163], v[206:209], v[124:127]
	v_mfma_f32_16x16x32_bf16 v[120:123], v[182:185], v[206:209], v[120:123]
	v_mfma_f32_16x16x32_bf16 v[112:115], v[160:163], v[214:217], v[112:115]
	v_mfma_f32_16x16x32_bf16 v[104:107], v[182:185], v[214:217], v[104:107]
	v_mfma_f32_16x16x32_bf16 v[96:99], v[160:163], v[222:225], v[96:99]
	v_mfma_f32_16x16x32_bf16 v[88:91], v[182:185], v[222:225], v[88:91]
	v_mfma_f32_16x16x32_bf16 v[80:83], v[160:163], v[230:233], v[80:83]
	v_mfma_f32_16x16x32_bf16 v[72:75], v[182:185], v[230:233], v[72:75]
	v_mfma_f32_16x16x32_bf16 v[116:119], v[186:189], v[202:205], v[116:119]
	v_mfma_f32_16x16x32_bf16 v[108:111], v[194:197], v[202:205], v[108:111]
	v_mfma_f32_16x16x32_bf16 v[100:103], v[186:189], v[210:213], v[100:103]
	v_mfma_f32_16x16x32_bf16 v[92:95], v[194:197], v[210:213], v[92:95]
	v_mfma_f32_16x16x32_bf16 v[84:87], v[186:189], v[218:221], v[84:87]
	v_mfma_f32_16x16x32_bf16 v[76:79], v[194:197], v[218:221], v[76:79]
	v_mfma_f32_16x16x32_bf16 v[68:71], v[186:189], v[226:229], v[68:71]
	v_mfma_f32_16x16x32_bf16 v[64:67], v[194:197], v[226:229], v[64:67]
	v_mfma_f32_16x16x32_bf16 v[116:119], v[190:193], v[206:209], v[116:119]
	v_mfma_f32_16x16x32_bf16 v[108:111], v[198:201], v[206:209], v[108:111]
	v_mfma_f32_16x16x32_bf16 v[100:103], v[190:193], v[214:217], v[100:103]
	v_mfma_f32_16x16x32_bf16 v[92:95], v[198:201], v[214:217], v[92:95]
	v_mfma_f32_16x16x32_bf16 v[84:87], v[190:193], v[222:225], v[84:87]
	v_mfma_f32_16x16x32_bf16 v[76:79], v[198:201], v[222:225], v[76:79]
	v_mfma_f32_16x16x32_bf16 v[68:71], v[190:193], v[230:233], v[68:71]
	v_mfma_f32_16x16x32_bf16 v[64:67], v[198:201], v[230:233], v[64:67]
	s_barrier
	s_setprio 0
	s_add_i32 s24, s66, s26
	v_lshl_add_u64 v[166:167], v[166:167], 0, s[10:11]
	s_mov_b32 m0, s24
	ds_read_b128 v[202:205], v155 offset:49152
	ds_read_b128 v[206:209], v155 offset:50176
	ds_read_b128 v[210:213], v155 offset:51200
	ds_read_b128 v[214:217], v155 offset:52224
	ds_read_b128 v[218:221], v155 offset:53248
	ds_read_b128 v[222:225], v155 offset:54272
	ds_read_b128 v[226:229], v155 offset:55296
	ds_read_b128 v[230:233], v155 offset:56320
	global_load_lds_dwordx4 v[166:167], off
	s_add_i32 m0, s24, 0x2000
	s_add_u32 s22, s22, 0x1080
	v_lshl_add_u64 v[166:167], v[178:179], 0, s[10:11]
	s_addc_u32 s23, s23, 0
	s_add_i32 s24, s67, s26
	global_load_lds_dwordx4 v[166:167], off
	v_lshl_add_u64 v[166:167], s[22:23], 0, v[140:141]
	s_mov_b32 m0, s24
	s_nop 0
	global_load_lds_dwordx4 v[166:167], off
	v_lshl_add_u64 v[166:167], s[22:23], 0, v[138:139]
	s_add_i32 m0, s24, 0x2000
	s_nop 0
	global_load_lds_dwordx4 v[166:167], off
	v_lshl_add_u64 v[166:167], v[234:235], 0, s[10:11]
	s_mov_b32 m0, s50
	s_nop 0
	global_load_lds_dwordx4 v[166:167], off
	v_lshl_add_u64 v[166:167], v[236:237], 0, s[10:11]
	s_mov_b32 m0, s51
	s_nop 0
	global_load_lds_dwordx4 v[166:167], off
	s_waitcnt vmcnt(8)
	s_waitcnt lgkmcnt(0)
	s_setprio 1
	s_barrier
	v_mfma_f32_16x16x32_bf16 v[60:63], v[156:159], v[202:205], v[60:63]
	v_mfma_f32_16x16x32_bf16 v[56:59], v[174:177], v[202:205], v[56:59]
	v_mfma_f32_16x16x32_bf16 v[48:51], v[156:159], v[210:213], v[48:51]
	v_mfma_f32_16x16x32_bf16 v[40:43], v[174:177], v[210:213], v[40:43]
	v_mfma_f32_16x16x32_bf16 v[32:35], v[156:159], v[218:221], v[32:35]
	v_mfma_f32_16x16x32_bf16 v[24:27], v[174:177], v[218:221], v[24:27]
	v_mfma_f32_16x16x32_bf16 v[16:19], v[156:159], v[226:229], v[16:19]
	v_mfma_f32_16x16x32_bf16 v[8:11], v[174:177], v[226:229], v[8:11]
	v_mfma_f32_16x16x32_bf16 v[60:63], v[160:163], v[206:209], v[60:63]
	v_mfma_f32_16x16x32_bf16 v[56:59], v[182:185], v[206:209], v[56:59]
	v_mfma_f32_16x16x32_bf16 v[48:51], v[160:163], v[214:217], v[48:51]
	v_mfma_f32_16x16x32_bf16 v[40:43], v[182:185], v[214:217], v[40:43]
	v_mfma_f32_16x16x32_bf16 v[32:35], v[160:163], v[222:225], v[32:35]
	v_mfma_f32_16x16x32_bf16 v[24:27], v[182:185], v[222:225], v[24:27]
	v_mfma_f32_16x16x32_bf16 v[16:19], v[160:163], v[230:233], v[16:19]
	v_mfma_f32_16x16x32_bf16 v[8:11], v[182:185], v[230:233], v[8:11]
	v_mfma_f32_16x16x32_bf16 v[52:55], v[186:189], v[202:205], v[52:55]
	v_mfma_f32_16x16x32_bf16 v[44:47], v[194:197], v[202:205], v[44:47]
	v_mfma_f32_16x16x32_bf16 v[36:39], v[186:189], v[210:213], v[36:39]
	v_mfma_f32_16x16x32_bf16 v[28:31], v[194:197], v[210:213], v[28:31]
	v_mfma_f32_16x16x32_bf16 v[20:23], v[186:189], v[218:221], v[20:23]
	v_mfma_f32_16x16x32_bf16 v[12:15], v[194:197], v[218:221], v[12:15]
	v_mfma_f32_16x16x32_bf16 v[4:7], v[186:189], v[226:229], v[4:7]
	v_mfma_f32_16x16x32_bf16 v[0:3], v[194:197], v[226:229], v[0:3]
	v_mfma_f32_16x16x32_bf16 v[52:55], v[190:193], v[206:209], v[52:55]
	v_mfma_f32_16x16x32_bf16 v[44:47], v[198:201], v[206:209], v[44:47]
	v_mfma_f32_16x16x32_bf16 v[36:39], v[190:193], v[214:217], v[36:39]
	v_mfma_f32_16x16x32_bf16 v[28:31], v[198:201], v[214:217], v[28:31]
	v_mfma_f32_16x16x32_bf16 v[20:23], v[190:193], v[222:225], v[20:23]
	v_mfma_f32_16x16x32_bf16 v[12:15], v[198:201], v[222:225], v[12:15]
	v_mfma_f32_16x16x32_bf16 v[4:7], v[190:193], v[230:233], v[4:7]
	v_mfma_f32_16x16x32_bf16 v[0:3], v[198:201], v[230:233], v[0:3]
	s_barrier
	s_setprio 0
	s_add_i32 s65, s65, 2
	s_add_u32 s20, s20, 0x100
	s_addc_u32 s21, s21, 0
	s_add_u32 s39, s39, 0x100
	s_addc_u32 s64, s64, 0
	s_cmp_gt_u32 s65, 13
	s_cbranch_scc0 .LBB0_296
	s_and_b64 vcc, exec, s[12:13]
	s_cbranch_vccz .LBB0_299
	s_barrier

.LBB0_312:
	ds_read_b128 v[154:157], v150
	ds_read_b128 v[158:161], v150 offset:1024
	ds_read_b128 v[166:169], v150 offset:2048
	ds_read_b128 v[170:173], v150 offset:3072
	ds_read_b128 v[174:177], v151
	ds_read_b128 v[182:185], v151 offset:1024
	ds_read_b128 v[186:189], v151 offset:2048
	ds_read_b128 v[190:193], v151 offset:3072
	s_add_u32 s22, s20, 0xfffc0080
	s_addc_u32 s23, s21, -1
	s_cmp_eq_u32 s63, 12
	s_cselect_b32 s25, s13, s23
	s_cselect_b32 s24, s39, s22
	s_cselect_b32 s23, s11, s62
	s_cselect_b32 s22, s60, s61
	v_lshl_add_u64 v[146:147], s[20:21], 0, v[138:139]
	s_add_i32 m0, s19, 0xc000
	ds_read_b128 v[194:197], v152
	ds_read_b128 v[198:201], v152 offset:1024
	ds_read_b128 v[202:205], v152 offset:2048
	ds_read_b128 v[206:209], v152 offset:3072
	ds_read_b128 v[210:213], v152 offset:4096
	ds_read_b128 v[214:217], v152 offset:5120
	ds_read_b128 v[218:221], v152 offset:6144
	ds_read_b128 v[222:225], v152 offset:7168
	global_load_lds_dwordx4 v[146:147], off
	v_lshl_add_u64 v[146:147], s[20:21], 0, v[140:141]
	s_add_i32 m0, s19, 0xe000
	s_nop 0
	global_load_lds_dwordx4 v[146:147], off
	s_waitcnt vmcnt(8)
	s_waitcnt lgkmcnt(0)
	s_setprio 1
	s_barrier
	v_mfma_f32_16x16x32_bf16 v[124:127], v[154:157], v[194:197], v[124:127]
	v_mfma_f32_16x16x32_bf16 v[120:123], v[166:169], v[194:197], v[120:123]
	v_mfma_f32_16x16x32_bf16 v[116:119], v[154:157], v[202:205], v[116:119]
	v_mfma_f32_16x16x32_bf16 v[108:111], v[166:169], v[202:205], v[108:111]
	v_mfma_f32_16x16x32_bf16 v[100:103], v[154:157], v[210:213], v[100:103]
	v_mfma_f32_16x16x32_bf16 v[92:95], v[166:169], v[210:213], v[92:95]
	v_mfma_f32_16x16x32_bf16 v[84:87], v[154:157], v[218:221], v[84:87]
	v_mfma_f32_16x16x32_bf16 v[76:79], v[166:169], v[218:221], v[76:79]
	v_mfma_f32_16x16x32_bf16 v[124:127], v[158:161], v[198:201], v[124:127]
	v_mfma_f32_16x16x32_bf16 v[120:123], v[170:173], v[198:201], v[120:123]
	v_mfma_f32_16x16x32_bf16 v[116:119], v[158:161], v[206:209], v[116:119]
	v_mfma_f32_16x16x32_bf16 v[108:111], v[170:173], v[206:209], v[108:111]
	v_mfma_f32_16x16x32_bf16 v[100:103], v[158:161], v[214:217], v[100:103]
	v_mfma_f32_16x16x32_bf16 v[92:95], v[170:173], v[214:217], v[92:95]
	v_mfma_f32_16x16x32_bf16 v[84:87], v[158:161], v[222:225], v[84:87]
	v_mfma_f32_16x16x32_bf16 v[76:79], v[170:173], v[222:225], v[76:79]
	v_mfma_f32_16x16x32_bf16 v[112:115], v[174:177], v[194:197], v[112:115]
	v_mfma_f32_16x16x32_bf16 v[104:107], v[186:189], v[194:197], v[104:107]
	v_mfma_f32_16x16x32_bf16 v[96:99], v[174:177], v[202:205], v[96:99]
	v_mfma_f32_16x16x32_bf16 v[88:91], v[186:189], v[202:205], v[88:91]
	v_mfma_f32_16x16x32_bf16 v[80:83], v[174:177], v[210:213], v[80:83]
	v_mfma_f32_16x16x32_bf16 v[72:75], v[186:189], v[210:213], v[72:75]
	v_mfma_f32_16x16x32_bf16 v[68:71], v[174:177], v[218:221], v[68:71]
	v_mfma_f32_16x16x32_bf16 v[64:67], v[186:189], v[218:221], v[64:67]
	v_mfma_f32_16x16x32_bf16 v[112:115], v[182:185], v[198:201], v[112:115]
	v_mfma_f32_16x16x32_bf16 v[104:107], v[190:193], v[198:201], v[104:107]
	v_mfma_f32_16x16x32_bf16 v[96:99], v[182:185], v[206:209], v[96:99]
	v_mfma_f32_16x16x32_bf16 v[88:91], v[190:193], v[206:209], v[88:91]
	v_mfma_f32_16x16x32_bf16 v[80:83], v[182:185], v[214:217], v[80:83]
	v_mfma_f32_16x16x32_bf16 v[72:75], v[190:193], v[214:217], v[72:75]
	v_mfma_f32_16x16x32_bf16 v[68:71], v[182:185], v[222:225], v[68:71]
	v_mfma_f32_16x16x32_bf16 v[64:67], v[190:193], v[222:225], v[64:67]
	s_barrier
	s_setprio 0
	s_add_i32 s64, s51, s31
	v_lshl_add_u64 v[146:147], s[22:23], 0, v[130:131]
	s_mov_b32 m0, s64
	ds_read_b128 v[194:197], v152 offset:16384
	ds_read_b128 v[198:201], v152 offset:17408
	ds_read_b128 v[202:205], v152 offset:18432
	ds_read_b128 v[206:209], v152 offset:19456
	ds_read_b128 v[210:213], v152 offset:20480
	ds_read_b128 v[214:217], v152 offset:21504
	ds_read_b128 v[218:221], v152 offset:22528
	ds_read_b128 v[222:225], v152 offset:23552
	global_load_lds_dwordx4 v[146:147], off
	s_add_i32 m0, s64, 0x2000
	s_add_u32 s64, s22, 0x40000
	v_lshl_add_u64 v[162:163], s[22:23], 0, v[134:135]
	s_addc_u32 s65, s23, 0
	s_add_i32 s66, s52, s31
	global_load_lds_dwordx4 v[162:163], off
	v_lshl_add_u64 v[178:179], s[64:65], 0, v[130:131]
	s_mov_b32 m0, s66
	v_lshl_add_u64 v[226:227], s[24:25], 0, v[132:133]
	global_load_lds_dwordx4 v[178:179], off
	v_lshl_add_u64 v[178:179], s[64:65], 0, v[134:135]
	s_add_i32 m0, s66, 0x2000
	s_nop 0
	global_load_lds_dwordx4 v[178:179], off
	v_lshl_add_u64 v[178:179], s[24:25], 0, v[128:129]
	s_mov_b32 m0, s19
	s_nop 0
	global_load_lds_dwordx4 v[178:179], off
	s_mov_b32 m0, s35
	s_nop 0
	global_load_lds_dwordx4 v[226:227], off
	s_waitcnt vmcnt(8)
	s_waitcnt lgkmcnt(0)
	s_setprio 1
	s_barrier
	v_mfma_f32_16x16x32_bf16 v[60:63], v[154:157], v[194:197], v[60:63]
	v_mfma_f32_16x16x32_bf16 v[56:59], v[166:169], v[194:197], v[56:59]
	v_mfma_f32_16x16x32_bf16 v[52:55], v[154:157], v[202:205], v[52:55]
	v_mfma_f32_16x16x32_bf16 v[44:47], v[166:169], v[202:205], v[44:47]
	v_mfma_f32_16x16x32_bf16 v[36:39], v[154:157], v[210:213], v[36:39]
	v_mfma_f32_16x16x32_bf16 v[28:31], v[166:169], v[210:213], v[28:31]
	v_mfma_f32_16x16x32_bf16 v[20:23], v[154:157], v[218:221], v[20:23]
	v_mfma_f32_16x16x32_bf16 v[12:15], v[166:169], v[218:221], v[12:15]
	v_mfma_f32_16x16x32_bf16 v[60:63], v[158:161], v[198:201], v[60:63]
	v_mfma_f32_16x16x32_bf16 v[56:59], v[170:173], v[198:201], v[56:59]
	v_mfma_f32_16x16x32_bf16 v[52:55], v[158:161], v[206:209], v[52:55]
	v_mfma_f32_16x16x32_bf16 v[44:47], v[170:173], v[206:209], v[44:47]
	v_mfma_f32_16x16x32_bf16 v[36:39], v[158:161], v[214:217], v[36:39]
	v_mfma_f32_16x16x32_bf16 v[28:31], v[170:173], v[214:217], v[28:31]
	v_mfma_f32_16x16x32_bf16 v[20:23], v[158:161], v[222:225], v[20:23]
	v_mfma_f32_16x16x32_bf16 v[12:15], v[170:173], v[222:225], v[12:15]
	v_mfma_f32_16x16x32_bf16 v[48:51], v[174:177], v[194:197], v[48:51]
	v_mfma_f32_16x16x32_bf16 v[40:43], v[186:189], v[194:197], v[40:43]
	v_mfma_f32_16x16x32_bf16 v[32:35], v[174:177], v[202:205], v[32:35]
	v_mfma_f32_16x16x32_bf16 v[24:27], v[186:189], v[202:205], v[24:27]
	v_mfma_f32_16x16x32_bf16 v[16:19], v[174:177], v[210:213], v[16:19]
	v_mfma_f32_16x16x32_bf16 v[8:11], v[186:189], v[210:213], v[8:11]
	v_mfma_f32_16x16x32_bf16 v[4:7], v[174:177], v[218:221], v[4:7]
	v_mfma_f32_16x16x32_bf16 v[0:3], v[186:189], v[218:221], v[0:3]
	v_mfma_f32_16x16x32_bf16 v[48:51], v[182:185], v[198:201], v[48:51]
	v_mfma_f32_16x16x32_bf16 v[40:43], v[190:193], v[198:201], v[40:43]
	v_mfma_f32_16x16x32_bf16 v[32:35], v[182:185], v[206:209], v[32:35]
	v_mfma_f32_16x16x32_bf16 v[24:27], v[190:193], v[206:209], v[24:27]
	v_mfma_f32_16x16x32_bf16 v[16:19], v[182:185], v[214:217], v[16:19]
	v_mfma_f32_16x16x32_bf16 v[8:11], v[190:193], v[214:217], v[8:11]
	v_mfma_f32_16x16x32_bf16 v[4:7], v[182:185], v[222:225], v[4:7]
	v_mfma_f32_16x16x32_bf16 v[0:3], v[190:193], v[222:225], v[0:3]
	s_barrier
	s_setprio 0
	s_add_i32 s64, 0, 0x18000
	v_add_u32_e32 v153, s64, v149
	s_add_i32 s65, 0, 0x1c000
	ds_read_b128 v[154:157], v153
	ds_read_b128 v[158:161], v153 offset:1024
	ds_read_b128 v[166:169], v153 offset:2048
	ds_read_b128 v[170:173], v153 offset:3072
	v_add_u32_e32 v153, s65, v149
	ds_read_b128 v[174:177], v153
	ds_read_b128 v[182:185], v153 offset:1024
	ds_read_b128 v[186:189], v153 offset:2048
	ds_read_b128 v[190:193], v153 offset:3072
	s_add_u32 s24, s24, 0x40000
	s_addc_u32 s25, s25, 0
	s_mov_b32 m0, s36
	v_lshl_add_u64 v[228:229], s[24:25], 0, v[128:129]
	ds_read_b128 v[194:197], v152 offset:32768
	ds_read_b128 v[198:201], v152 offset:33792
	ds_read_b128 v[202:205], v152 offset:34816
	ds_read_b128 v[206:209], v152 offset:35840
	ds_read_b128 v[210:213], v152 offset:36864
	ds_read_b128 v[214:217], v152 offset:37888
	ds_read_b128 v[218:221], v152 offset:38912
	ds_read_b128 v[222:225], v152 offset:39936
	global_load_lds_dwordx4 v[228:229], off
	v_lshl_add_u64 v[228:229], s[24:25], 0, v[132:133]
	s_mov_b32 m0, s37
	s_nop 0
	global_load_lds_dwordx4 v[228:229], off
	s_waitcnt vmcnt(8)
	s_waitcnt lgkmcnt(0)
	s_setprio 1
	s_barrier
	v_mfma_f32_16x16x32_bf16 v[124:127], v[154:157], v[194:197], v[124:127]
	v_mfma_f32_16x16x32_bf16 v[120:123], v[166:169], v[194:197], v[120:123]
	v_mfma_f32_16x16x32_bf16 v[116:119], v[154:157], v[202:205], v[116:119]
	v_mfma_f32_16x16x32_bf16 v[108:111], v[166:169], v[202:205], v[108:111]
	v_mfma_f32_16x16x32_bf16 v[100:103], v[154:157], v[210:213], v[100:103]
	v_mfma_f32_16x16x32_bf16 v[92:95], v[166:169], v[210:213], v[92:95]
	v_mfma_f32_16x16x32_bf16 v[84:87], v[154:157], v[218:221], v[84:87]
	v_mfma_f32_16x16x32_bf16 v[76:79], v[166:169], v[218:221], v[76:79]
	v_mfma_f32_16x16x32_bf16 v[124:127], v[158:161], v[198:201], v[124:127]
	v_mfma_f32_16x16x32_bf16 v[120:123], v[170:173], v[198:201], v[120:123]
	v_mfma_f32_16x16x32_bf16 v[116:119], v[158:161], v[206:209], v[116:119]
	v_mfma_f32_16x16x32_bf16 v[108:111], v[170:173], v[206:209], v[108:111]
	v_mfma_f32_16x16x32_bf16 v[100:103], v[158:161], v[214:217], v[100:103]
	v_mfma_f32_16x16x32_bf16 v[92:95], v[170:173], v[214:217], v[92:95]
	v_mfma_f32_16x16x32_bf16 v[84:87], v[158:161], v[222:225], v[84:87]
	v_mfma_f32_16x16x32_bf16 v[76:79], v[170:173], v[222:225], v[76:79]
	v_mfma_f32_16x16x32_bf16 v[112:115], v[174:177], v[194:197], v[112:115]
	v_mfma_f32_16x16x32_bf16 v[104:107], v[186:189], v[194:197], v[104:107]
	v_mfma_f32_16x16x32_bf16 v[96:99], v[174:177], v[202:205], v[96:99]
	v_mfma_f32_16x16x32_bf16 v[88:91], v[186:189], v[202:205], v[88:91]
	v_mfma_f32_16x16x32_bf16 v[80:83], v[174:177], v[210:213], v[80:83]
	v_mfma_f32_16x16x32_bf16 v[72:75], v[186:189], v[210:213], v[72:75]
	v_mfma_f32_16x16x32_bf16 v[68:71], v[174:177], v[218:221], v[68:71]
	v_mfma_f32_16x16x32_bf16 v[64:67], v[186:189], v[218:221], v[64:67]
	v_mfma_f32_16x16x32_bf16 v[112:115], v[182:185], v[198:201], v[112:115]
	v_mfma_f32_16x16x32_bf16 v[104:107], v[190:193], v[198:201], v[104:107]
	v_mfma_f32_16x16x32_bf16 v[96:99], v[182:185], v[206:209], v[96:99]
	v_mfma_f32_16x16x32_bf16 v[88:91], v[190:193], v[206:209], v[88:91]
	v_mfma_f32_16x16x32_bf16 v[80:83], v[182:185], v[214:217], v[80:83]
	v_mfma_f32_16x16x32_bf16 v[72:75], v[190:193], v[214:217], v[72:75]
	v_mfma_f32_16x16x32_bf16 v[68:71], v[182:185], v[222:225], v[68:71]
	v_mfma_f32_16x16x32_bf16 v[64:67], v[190:193], v[222:225], v[64:67]
	s_barrier
	s_setprio 0
	s_add_i32 s24, s64, s31
	v_lshl_add_u64 v[146:147], v[146:147], 0, s[6:7]
	s_mov_b32 m0, s24
	ds_read_b128 v[194:197], v152 offset:49152
	ds_read_b128 v[198:201], v152 offset:50176
	ds_read_b128 v[202:205], v152 offset:51200
	ds_read_b128 v[206:209], v152 offset:52224
	ds_read_b128 v[210:213], v152 offset:53248
	ds_read_b128 v[214:217], v152 offset:54272
	ds_read_b128 v[218:221], v152 offset:55296
	ds_read_b128 v[222:225], v152 offset:56320
	global_load_lds_dwordx4 v[146:147], off
	s_add_i32 m0, s24, 0x2000
	s_add_u32 s22, s22, 0x40080
	v_lshl_add_u64 v[146:147], v[162:163], 0, s[6:7]
	s_addc_u32 s23, s23, 0
	s_add_i32 s24, s65, s31
	global_load_lds_dwordx4 v[146:147], off
	v_lshl_add_u64 v[146:147], s[22:23], 0, v[130:131]
	s_mov_b32 m0, s24
	s_nop 0
	global_load_lds_dwordx4 v[146:147], off
	v_lshl_add_u64 v[146:147], s[22:23], 0, v[134:135]
	s_add_i32 m0, s24, 0x2000
	s_nop 0
	global_load_lds_dwordx4 v[146:147], off
	v_lshl_add_u64 v[146:147], v[178:179], 0, s[6:7]
	s_mov_b32 m0, s45
	s_nop 0
	global_load_lds_dwordx4 v[146:147], off
	v_lshl_add_u64 v[146:147], v[226:227], 0, s[6:7]
	s_mov_b32 m0, s48
	s_nop 0
	global_load_lds_dwordx4 v[146:147], off
	s_waitcnt vmcnt(8)
	s_waitcnt lgkmcnt(0)
	s_setprio 1
	s_barrier
	v_mfma_f32_16x16x32_bf16 v[60:63], v[154:157], v[194:197], v[60:63]
	v_mfma_f32_16x16x32_bf16 v[56:59], v[166:169], v[194:197], v[56:59]
	v_mfma_f32_16x16x32_bf16 v[52:55], v[154:157], v[202:205], v[52:55]
	v_mfma_f32_16x16x32_bf16 v[44:47], v[166:169], v[202:205], v[44:47]
	v_mfma_f32_16x16x32_bf16 v[36:39], v[154:157], v[210:213], v[36:39]
	v_mfma_f32_16x16x32_bf16 v[28:31], v[166:169], v[210:213], v[28:31]
	v_mfma_f32_16x16x32_bf16 v[20:23], v[154:157], v[218:221], v[20:23]
	v_mfma_f32_16x16x32_bf16 v[12:15], v[166:169], v[218:221], v[12:15]
	v_mfma_f32_16x16x32_bf16 v[60:63], v[158:161], v[198:201], v[60:63]
	v_mfma_f32_16x16x32_bf16 v[56:59], v[170:173], v[198:201], v[56:59]
	v_mfma_f32_16x16x32_bf16 v[52:55], v[158:161], v[206:209], v[52:55]
	v_mfma_f32_16x16x32_bf16 v[44:47], v[170:173], v[206:209], v[44:47]
	v_mfma_f32_16x16x32_bf16 v[36:39], v[158:161], v[214:217], v[36:39]
	v_mfma_f32_16x16x32_bf16 v[28:31], v[170:173], v[214:217], v[28:31]
	v_mfma_f32_16x16x32_bf16 v[20:23], v[158:161], v[222:225], v[20:23]
	v_mfma_f32_16x16x32_bf16 v[12:15], v[170:173], v[222:225], v[12:15]
	v_mfma_f32_16x16x32_bf16 v[48:51], v[174:177], v[194:197], v[48:51]
	v_mfma_f32_16x16x32_bf16 v[40:43], v[186:189], v[194:197], v[40:43]
	v_mfma_f32_16x16x32_bf16 v[32:35], v[174:177], v[202:205], v[32:35]
	v_mfma_f32_16x16x32_bf16 v[24:27], v[186:189], v[202:205], v[24:27]
	v_mfma_f32_16x16x32_bf16 v[16:19], v[174:177], v[210:213], v[16:19]
	v_mfma_f32_16x16x32_bf16 v[8:11], v[186:189], v[210:213], v[8:11]
	v_mfma_f32_16x16x32_bf16 v[4:7], v[174:177], v[218:221], v[4:7]
	v_mfma_f32_16x16x32_bf16 v[0:3], v[186:189], v[218:221], v[0:3]
	v_mfma_f32_16x16x32_bf16 v[48:51], v[182:185], v[198:201], v[48:51]
	v_mfma_f32_16x16x32_bf16 v[40:43], v[190:193], v[198:201], v[40:43]
	v_mfma_f32_16x16x32_bf16 v[32:35], v[182:185], v[206:209], v[32:35]
	v_mfma_f32_16x16x32_bf16 v[24:27], v[190:193], v[206:209], v[24:27]
	v_mfma_f32_16x16x32_bf16 v[16:19], v[182:185], v[214:217], v[16:19]
	v_mfma_f32_16x16x32_bf16 v[8:11], v[190:193], v[214:217], v[8:11]
	v_mfma_f32_16x16x32_bf16 v[4:7], v[182:185], v[222:225], v[4:7]
	v_mfma_f32_16x16x32_bf16 v[0:3], v[190:193], v[222:225], v[0:3]
	s_barrier
	s_setprio 0
	s_add_i32 s63, s63, 2
	s_add_u32 s20, s20, 0x100
	s_addc_u32 s21, s21, 0
	s_add_u32 s61, s61, 0x100
	s_addc_u32 s62, s62, 0
	s_cmp_gt_u32 s63, 13
	s_cbranch_scc0 .LBB0_312
	s_and_b64 vcc, exec, s[8:9]
	s_cbranch_vccz .LBB0_315
	s_barrier

.LBB0_438:
	ds_read_b128 v[160:163], v155
	ds_read_b128 v[166:169], v155 offset:1024
	ds_read_b128 v[170:173], v155 offset:2048
	ds_read_b128 v[174:177], v155 offset:3072
	ds_read_b128 v[182:185], v156
	ds_read_b128 v[186:189], v156 offset:1024
	ds_read_b128 v[190:193], v156 offset:2048
	ds_read_b128 v[194:197], v156 offset:3072
	s_add_i32 s39, s22, 2
	s_add_u32 s73, s20, 0x80
	s_addc_u32 s23, s21, 0
	s_cmp_eq_u32 s60, s22
	s_cselect_b32 s22, s16, s73
	s_cselect_b32 s23, s17, s23
	s_cselect_b32 s77, s1, s38
	s_cselect_b32 s76, s0, s19
	s_mov_b32 m0, s52
	v_lshl_add_u64 v[178:179], s[20:21], 0, v[138:139]
	ds_read_b128 v[198:201], v157
	ds_read_b128 v[202:205], v157 offset:1024
	ds_read_b128 v[206:209], v157 offset:2048
	ds_read_b128 v[210:213], v157 offset:3072
	ds_read_b128 v[214:217], v157 offset:4096
	ds_read_b128 v[218:221], v157 offset:5120
	ds_read_b128 v[222:225], v157 offset:6144
	ds_read_b128 v[226:229], v157 offset:7168
	global_load_lds_dwordx4 v[178:179], off
	v_lshl_add_u64 v[178:179], s[20:21], 0, v[140:141]
	s_mov_b32 m0, s63
	s_nop 0
	global_load_lds_dwordx4 v[178:179], off
	s_waitcnt vmcnt(8)
	s_waitcnt lgkmcnt(0)
	s_setprio 1
	s_barrier
	v_mfma_f32_16x16x32_bf16 v[124:127], v[160:163], v[198:201], v[124:127]
	v_mfma_f32_16x16x32_bf16 v[120:123], v[170:173], v[198:201], v[120:123]
	v_mfma_f32_16x16x32_bf16 v[92:95], v[160:163], v[206:209], v[92:95]
	v_mfma_f32_16x16x32_bf16 v[88:91], v[170:173], v[206:209], v[88:91]
	v_mfma_f32_16x16x32_bf16 v[60:63], v[160:163], v[214:217], v[60:63]
	v_mfma_f32_16x16x32_bf16 v[56:59], v[170:173], v[214:217], v[56:59]
	v_mfma_f32_16x16x32_bf16 v[28:31], v[160:163], v[222:225], v[28:31]
	v_mfma_f32_16x16x32_bf16 v[24:27], v[170:173], v[222:225], v[24:27]
	v_mfma_f32_16x16x32_bf16 v[124:127], v[166:169], v[202:205], v[124:127]
	v_mfma_f32_16x16x32_bf16 v[120:123], v[174:177], v[202:205], v[120:123]
	v_mfma_f32_16x16x32_bf16 v[92:95], v[166:169], v[210:213], v[92:95]
	v_mfma_f32_16x16x32_bf16 v[88:91], v[174:177], v[210:213], v[88:91]
	v_mfma_f32_16x16x32_bf16 v[60:63], v[166:169], v[218:221], v[60:63]
	v_mfma_f32_16x16x32_bf16 v[56:59], v[174:177], v[218:221], v[56:59]
	v_mfma_f32_16x16x32_bf16 v[28:31], v[166:169], v[226:229], v[28:31]
	v_mfma_f32_16x16x32_bf16 v[24:27], v[174:177], v[226:229], v[24:27]
	v_mfma_f32_16x16x32_bf16 v[108:111], v[182:185], v[198:201], v[108:111]
	v_mfma_f32_16x16x32_bf16 v[104:107], v[190:193], v[198:201], v[104:107]
	v_mfma_f32_16x16x32_bf16 v[76:79], v[182:185], v[206:209], v[76:79]
	v_mfma_f32_16x16x32_bf16 v[72:75], v[190:193], v[206:209], v[72:75]
	v_mfma_f32_16x16x32_bf16 v[44:47], v[182:185], v[214:217], v[44:47]
	v_mfma_f32_16x16x32_bf16 v[40:43], v[190:193], v[214:217], v[40:43]
	v_mfma_f32_16x16x32_bf16 v[12:15], v[182:185], v[222:225], v[12:15]
	v_mfma_f32_16x16x32_bf16 v[8:11], v[190:193], v[222:225], v[8:11]
	v_mfma_f32_16x16x32_bf16 v[108:111], v[186:189], v[202:205], v[108:111]
	v_mfma_f32_16x16x32_bf16 v[104:107], v[194:197], v[202:205], v[104:107]
	v_mfma_f32_16x16x32_bf16 v[76:79], v[186:189], v[210:213], v[76:79]
	v_mfma_f32_16x16x32_bf16 v[72:75], v[194:197], v[210:213], v[72:75]
	v_mfma_f32_16x16x32_bf16 v[44:47], v[186:189], v[218:221], v[44:47]
	v_mfma_f32_16x16x32_bf16 v[40:43], v[194:197], v[218:221], v[40:43]
	v_mfma_f32_16x16x32_bf16 v[12:15], v[186:189], v[226:229], v[12:15]
	v_mfma_f32_16x16x32_bf16 v[8:11], v[194:197], v[226:229], v[8:11]
	s_barrier
	s_setprio 0
	s_mov_b32 m0, s64
	v_lshl_add_u64 v[178:179], s[76:77], 0, v[132:133]
	v_lshl_add_u64 v[230:231], s[76:77], 0, v[128:129]
	s_add_u32 s76, s76, s6
	ds_read_b128 v[198:201], v157 offset:16384
	ds_read_b128 v[202:205], v157 offset:17408
	ds_read_b128 v[206:209], v157 offset:18432
	ds_read_b128 v[210:213], v157 offset:19456
	ds_read_b128 v[214:217], v157 offset:20480
	ds_read_b128 v[218:221], v157 offset:21504
	ds_read_b128 v[222:225], v157 offset:22528
	ds_read_b128 v[226:229], v157 offset:23552
	global_load_lds_dwordx4 v[178:179], off
	s_mov_b32 m0, s65
	s_addc_u32 s77, s77, s7
	global_load_lds_dwordx4 v[230:231], off
	v_lshl_add_u64 v[232:233], s[76:77], 0, v[132:133]
	s_mov_b32 m0, s66
	v_lshl_add_u64 v[234:235], s[76:77], 0, v[128:129]
	global_load_lds_dwordx4 v[232:233], off
	s_mov_b32 m0, s67
	v_lshl_add_u64 v[236:237], s[22:23], 0, v[134:135]
	global_load_lds_dwordx4 v[234:235], off
	s_mov_b32 m0, s29
	v_lshl_add_u64 v[238:239], s[22:23], 0, v[130:131]
	global_load_lds_dwordx4 v[236:237], off
	s_mov_b32 m0, s30
	s_nop 0
	global_load_lds_dwordx4 v[238:239], off
	s_waitcnt vmcnt(8)
	s_waitcnt lgkmcnt(0)
	s_setprio 1
	s_barrier
	v_mfma_f32_16x16x32_bf16 v[116:119], v[160:163], v[198:201], v[116:119]
	v_mfma_f32_16x16x32_bf16 v[112:115], v[170:173], v[198:201], v[112:115]
	v_mfma_f32_16x16x32_bf16 v[84:87], v[160:163], v[206:209], v[84:87]
	v_mfma_f32_16x16x32_bf16 v[80:83], v[170:173], v[206:209], v[80:83]
	v_mfma_f32_16x16x32_bf16 v[52:55], v[160:163], v[214:217], v[52:55]
	v_mfma_f32_16x16x32_bf16 v[48:51], v[170:173], v[214:217], v[48:51]
	v_mfma_f32_16x16x32_bf16 v[20:23], v[160:163], v[222:225], v[20:23]
	v_mfma_f32_16x16x32_bf16 v[16:19], v[170:173], v[222:225], v[16:19]
	v_mfma_f32_16x16x32_bf16 v[116:119], v[166:169], v[202:205], v[116:119]
	v_mfma_f32_16x16x32_bf16 v[112:115], v[174:177], v[202:205], v[112:115]
	v_mfma_f32_16x16x32_bf16 v[84:87], v[166:169], v[210:213], v[84:87]
	v_mfma_f32_16x16x32_bf16 v[80:83], v[174:177], v[210:213], v[80:83]
	v_mfma_f32_16x16x32_bf16 v[52:55], v[166:169], v[218:221], v[52:55]
	v_mfma_f32_16x16x32_bf16 v[48:51], v[174:177], v[218:221], v[48:51]
	v_mfma_f32_16x16x32_bf16 v[20:23], v[166:169], v[226:229], v[20:23]
	v_mfma_f32_16x16x32_bf16 v[16:19], v[174:177], v[226:229], v[16:19]
	v_mfma_f32_16x16x32_bf16 v[100:103], v[182:185], v[198:201], v[100:103]
	v_mfma_f32_16x16x32_bf16 v[96:99], v[190:193], v[198:201], v[96:99]
	v_mfma_f32_16x16x32_bf16 v[68:71], v[182:185], v[206:209], v[68:71]
	v_mfma_f32_16x16x32_bf16 v[64:67], v[190:193], v[206:209], v[64:67]
	v_mfma_f32_16x16x32_bf16 v[36:39], v[182:185], v[214:217], v[36:39]
	v_mfma_f32_16x16x32_bf16 v[32:35], v[190:193], v[214:217], v[32:35]
	v_mfma_f32_16x16x32_bf16 v[4:7], v[182:185], v[222:225], v[4:7]
	v_mfma_f32_16x16x32_bf16 v[0:3], v[190:193], v[222:225], v[0:3]
	v_mfma_f32_16x16x32_bf16 v[100:103], v[186:189], v[202:205], v[100:103]
	v_mfma_f32_16x16x32_bf16 v[96:99], v[194:197], v[202:205], v[96:99]
	v_mfma_f32_16x16x32_bf16 v[68:71], v[186:189], v[210:213], v[68:71]
	v_mfma_f32_16x16x32_bf16 v[64:67], v[194:197], v[210:213], v[64:67]
	v_mfma_f32_16x16x32_bf16 v[36:39], v[186:189], v[218:221], v[36:39]
	v_mfma_f32_16x16x32_bf16 v[32:35], v[194:197], v[218:221], v[32:35]
	v_mfma_f32_16x16x32_bf16 v[4:7], v[186:189], v[226:229], v[4:7]
	v_mfma_f32_16x16x32_bf16 v[0:3], v[194:197], v[226:229], v[0:3]
	s_barrier
	s_setprio 0
	ds_read_b128 v[160:163], v158
	ds_read_b128 v[166:169], v158 offset:1024
	ds_read_b128 v[170:173], v158 offset:2048
	ds_read_b128 v[174:177], v158 offset:3072
	ds_read_b128 v[182:185], v159
	ds_read_b128 v[186:189], v159 offset:1024
	ds_read_b128 v[190:193], v159 offset:2048
	ds_read_b128 v[194:197], v159 offset:3072
	s_add_u32 s22, s22, s6
	s_addc_u32 s23, s23, s7
	s_mov_b32 m0, s31
	v_lshl_add_u64 v[240:241], s[22:23], 0, v[134:135]
	ds_read_b128 v[198:201], v157 offset:32768
	ds_read_b128 v[202:205], v157 offset:33792
	ds_read_b128 v[206:209], v157 offset:34816
	ds_read_b128 v[210:213], v157 offset:35840
	ds_read_b128 v[214:217], v157 offset:36864
	ds_read_b128 v[218:221], v157 offset:37888
	ds_read_b128 v[222:225], v157 offset:38912
	ds_read_b128 v[226:229], v157 offset:39936
	global_load_lds_dwordx4 v[240:241], off
	v_lshl_add_u64 v[240:241], s[22:23], 0, v[130:131]
	s_mov_b32 m0, s34
	s_nop 0
	global_load_lds_dwordx4 v[240:241], off
	s_waitcnt vmcnt(8)
	s_waitcnt lgkmcnt(0)
	s_setprio 1
	s_barrier
	v_mfma_f32_16x16x32_bf16 v[124:127], v[160:163], v[198:201], v[124:127]
	v_mfma_f32_16x16x32_bf16 v[120:123], v[170:173], v[198:201], v[120:123]
	v_mfma_f32_16x16x32_bf16 v[92:95], v[160:163], v[206:209], v[92:95]
	v_mfma_f32_16x16x32_bf16 v[88:91], v[170:173], v[206:209], v[88:91]
	v_mfma_f32_16x16x32_bf16 v[60:63], v[160:163], v[214:217], v[60:63]
	v_mfma_f32_16x16x32_bf16 v[56:59], v[170:173], v[214:217], v[56:59]
	v_mfma_f32_16x16x32_bf16 v[28:31], v[160:163], v[222:225], v[28:31]
	v_mfma_f32_16x16x32_bf16 v[24:27], v[170:173], v[222:225], v[24:27]
	v_mfma_f32_16x16x32_bf16 v[124:127], v[166:169], v[202:205], v[124:127]
	v_mfma_f32_16x16x32_bf16 v[120:123], v[174:177], v[202:205], v[120:123]
	v_mfma_f32_16x16x32_bf16 v[92:95], v[166:169], v[210:213], v[92:95]
	v_mfma_f32_16x16x32_bf16 v[88:91], v[174:177], v[210:213], v[88:91]
	v_mfma_f32_16x16x32_bf16 v[60:63], v[166:169], v[218:221], v[60:63]
	v_mfma_f32_16x16x32_bf16 v[56:59], v[174:177], v[218:221], v[56:59]
	v_mfma_f32_16x16x32_bf16 v[28:31], v[166:169], v[226:229], v[28:31]
	v_mfma_f32_16x16x32_bf16 v[24:27], v[174:177], v[226:229], v[24:27]
	v_mfma_f32_16x16x32_bf16 v[108:111], v[182:185], v[198:201], v[108:111]
	v_mfma_f32_16x16x32_bf16 v[104:107], v[190:193], v[198:201], v[104:107]
	v_mfma_f32_16x16x32_bf16 v[76:79], v[182:185], v[206:209], v[76:79]
	v_mfma_f32_16x16x32_bf16 v[72:75], v[190:193], v[206:209], v[72:75]
	v_mfma_f32_16x16x32_bf16 v[44:47], v[182:185], v[214:217], v[44:47]
	v_mfma_f32_16x16x32_bf16 v[40:43], v[190:193], v[214:217], v[40:43]
	v_mfma_f32_16x16x32_bf16 v[12:15], v[182:185], v[222:225], v[12:15]
	v_mfma_f32_16x16x32_bf16 v[8:11], v[190:193], v[222:225], v[8:11]
	v_mfma_f32_16x16x32_bf16 v[108:111], v[186:189], v[202:205], v[108:111]
	v_mfma_f32_16x16x32_bf16 v[104:107], v[194:197], v[202:205], v[104:107]
	v_mfma_f32_16x16x32_bf16 v[76:79], v[186:189], v[210:213], v[76:79]
	v_mfma_f32_16x16x32_bf16 v[72:75], v[194:197], v[210:213], v[72:75]
	v_mfma_f32_16x16x32_bf16 v[44:47], v[186:189], v[218:221], v[44:47]
	v_mfma_f32_16x16x32_bf16 v[40:43], v[194:197], v[218:221], v[40:43]
	v_mfma_f32_16x16x32_bf16 v[12:15], v[186:189], v[226:229], v[12:15]
	v_mfma_f32_16x16x32_bf16 v[8:11], v[194:197], v[226:229], v[8:11]
	s_barrier
	s_setprio 0
	s_mov_b32 m0, s68
	v_lshl_add_u64 v[178:179], v[178:179], 0, s[12:13]
	ds_read_b128 v[198:201], v157 offset:49152
	ds_read_b128 v[202:205], v157 offset:50176
	ds_read_b128 v[206:209], v157 offset:51200
	ds_read_b128 v[210:213], v157 offset:52224
	ds_read_b128 v[214:217], v157 offset:53248
	ds_read_b128 v[218:221], v157 offset:54272
	ds_read_b128 v[222:225], v157 offset:55296
	ds_read_b128 v[226:229], v157 offset:56320
	global_load_lds_dwordx4 v[178:179], off
	v_lshl_add_u64 v[178:179], v[230:231], 0, s[12:13]
	s_mov_b32 m0, s69
	s_nop 0
	global_load_lds_dwordx4 v[178:179], off
	v_lshl_add_u64 v[178:179], v[232:233], 0, s[12:13]
	s_mov_b32 m0, s70
	s_nop 0
	global_load_lds_dwordx4 v[178:179], off
	v_lshl_add_u64 v[178:179], v[234:235], 0, s[12:13]
	s_mov_b32 m0, s71
	s_nop 0
	global_load_lds_dwordx4 v[178:179], off
	v_lshl_add_u64 v[178:179], v[236:237], 0, s[12:13]
	s_mov_b32 m0, s36
	s_nop 0
	global_load_lds_dwordx4 v[178:179], off
	v_lshl_add_u64 v[178:179], v[238:239], 0, s[12:13]
	s_mov_b32 m0, s37
	s_nop 0
	global_load_lds_dwordx4 v[178:179], off
	s_waitcnt vmcnt(8)
	s_waitcnt lgkmcnt(0)
	s_setprio 1
	s_barrier
	v_mfma_f32_16x16x32_bf16 v[116:119], v[160:163], v[198:201], v[116:119]
	v_mfma_f32_16x16x32_bf16 v[112:115], v[170:173], v[198:201], v[112:115]
	v_mfma_f32_16x16x32_bf16 v[84:87], v[160:163], v[206:209], v[84:87]
	v_mfma_f32_16x16x32_bf16 v[80:83], v[170:173], v[206:209], v[80:83]
	v_mfma_f32_16x16x32_bf16 v[52:55], v[160:163], v[214:217], v[52:55]
	v_mfma_f32_16x16x32_bf16 v[48:51], v[170:173], v[214:217], v[48:51]
	v_mfma_f32_16x16x32_bf16 v[20:23], v[160:163], v[222:225], v[20:23]
	v_mfma_f32_16x16x32_bf16 v[16:19], v[170:173], v[222:225], v[16:19]
	v_mfma_f32_16x16x32_bf16 v[116:119], v[166:169], v[202:205], v[116:119]
	v_mfma_f32_16x16x32_bf16 v[112:115], v[174:177], v[202:205], v[112:115]
	v_mfma_f32_16x16x32_bf16 v[84:87], v[166:169], v[210:213], v[84:87]
	v_mfma_f32_16x16x32_bf16 v[80:83], v[174:177], v[210:213], v[80:83]
	v_mfma_f32_16x16x32_bf16 v[52:55], v[166:169], v[218:221], v[52:55]
	v_mfma_f32_16x16x32_bf16 v[48:51], v[174:177], v[218:221], v[48:51]
	v_mfma_f32_16x16x32_bf16 v[20:23], v[166:169], v[226:229], v[20:23]
	v_mfma_f32_16x16x32_bf16 v[16:19], v[174:177], v[226:229], v[16:19]
	v_mfma_f32_16x16x32_bf16 v[100:103], v[182:185], v[198:201], v[100:103]
	v_mfma_f32_16x16x32_bf16 v[96:99], v[190:193], v[198:201], v[96:99]
	v_mfma_f32_16x16x32_bf16 v[68:71], v[182:185], v[206:209], v[68:71]
	v_mfma_f32_16x16x32_bf16 v[64:67], v[190:193], v[206:209], v[64:67]
	v_mfma_f32_16x16x32_bf16 v[36:39], v[182:185], v[214:217], v[36:39]
	v_mfma_f32_16x16x32_bf16 v[32:35], v[190:193], v[214:217], v[32:35]
	v_mfma_f32_16x16x32_bf16 v[4:7], v[182:185], v[222:225], v[4:7]
	v_mfma_f32_16x16x32_bf16 v[0:3], v[190:193], v[222:225], v[0:3]
	v_mfma_f32_16x16x32_bf16 v[100:103], v[186:189], v[202:205], v[100:103]
	v_mfma_f32_16x16x32_bf16 v[96:99], v[194:197], v[202:205], v[96:99]
	v_mfma_f32_16x16x32_bf16 v[68:71], v[186:189], v[210:213], v[68:71]
	v_mfma_f32_16x16x32_bf16 v[64:67], v[194:197], v[210:213], v[64:67]
	v_mfma_f32_16x16x32_bf16 v[36:39], v[186:189], v[218:221], v[36:39]
	v_mfma_f32_16x16x32_bf16 v[32:35], v[194:197], v[218:221], v[32:35]
	v_mfma_f32_16x16x32_bf16 v[4:7], v[186:189], v[226:229], v[4:7]
	v_mfma_f32_16x16x32_bf16 v[0:3], v[194:197], v[226:229], v[0:3]
	s_barrier
	s_setprio 0
	s_add_u32 s20, s20, 0x100
	s_addc_u32 s21, s21, 0
	s_add_u32 s19, s19, 0x100
	s_addc_u32 s38, s38, 0
	s_cmp_ge_i32 s39, s51
	s_mov_b32 s22, s39
	s_cbranch_scc0 .LBB0_438

.LBB0_457:
	ds_read_b128 v[152:155], v147
	ds_read_b128 v[156:159], v147 offset:1024
	ds_read_b128 v[160:163], v147 offset:2048
	ds_read_b128 v[166:169], v147 offset:3072
	ds_read_b128 v[170:173], v148
	ds_read_b128 v[174:177], v148 offset:1024
	ds_read_b128 v[182:185], v148 offset:2048
	ds_read_b128 v[186:189], v148 offset:3072
	s_add_i32 s39, s22, 2
	s_add_u32 s72, s20, 0x80
	s_addc_u32 s23, s21, 0
	s_cmp_eq_u32 s53, s22
	s_cselect_b32 s22, s16, s72
	s_cselect_b32 s23, s17, s23
	s_cselect_b32 s73, s1, s38
	s_cselect_b32 s72, s0, s19
	s_mov_b32 m0, s50
	v_lshl_add_u64 v[178:179], s[20:21], 0, v[138:139]
	ds_read_b128 v[190:193], v149
	ds_read_b128 v[194:197], v149 offset:1024
	ds_read_b128 v[198:201], v149 offset:2048
	ds_read_b128 v[202:205], v149 offset:3072
	ds_read_b128 v[206:209], v149 offset:4096
	ds_read_b128 v[210:213], v149 offset:5120
	ds_read_b128 v[214:217], v149 offset:6144
	ds_read_b128 v[218:221], v149 offset:7168
	global_load_lds_dwordx4 v[178:179], off
	v_lshl_add_u64 v[178:179], s[20:21], 0, v[140:141]
	s_mov_b32 m0, s62
	s_nop 0
	global_load_lds_dwordx4 v[178:179], off
	s_waitcnt vmcnt(8)
	s_waitcnt lgkmcnt(0)
	s_setprio 1
	s_barrier
	v_mfma_f32_16x16x32_bf16 v[124:127], v[152:155], v[190:193], v[124:127]
	v_mfma_f32_16x16x32_bf16 v[120:123], v[160:163], v[190:193], v[120:123]
	v_mfma_f32_16x16x32_bf16 v[92:95], v[152:155], v[198:201], v[92:95]
	v_mfma_f32_16x16x32_bf16 v[88:91], v[160:163], v[198:201], v[88:91]
	v_mfma_f32_16x16x32_bf16 v[60:63], v[152:155], v[206:209], v[60:63]
	v_mfma_f32_16x16x32_bf16 v[56:59], v[160:163], v[206:209], v[56:59]
	v_mfma_f32_16x16x32_bf16 v[28:31], v[152:155], v[214:217], v[28:31]
	v_mfma_f32_16x16x32_bf16 v[24:27], v[160:163], v[214:217], v[24:27]
	v_mfma_f32_16x16x32_bf16 v[124:127], v[156:159], v[194:197], v[124:127]
	v_mfma_f32_16x16x32_bf16 v[120:123], v[166:169], v[194:197], v[120:123]
	v_mfma_f32_16x16x32_bf16 v[92:95], v[156:159], v[202:205], v[92:95]
	v_mfma_f32_16x16x32_bf16 v[88:91], v[166:169], v[202:205], v[88:91]
	v_mfma_f32_16x16x32_bf16 v[60:63], v[156:159], v[210:213], v[60:63]
	v_mfma_f32_16x16x32_bf16 v[56:59], v[166:169], v[210:213], v[56:59]
	v_mfma_f32_16x16x32_bf16 v[28:31], v[156:159], v[218:221], v[28:31]
	v_mfma_f32_16x16x32_bf16 v[24:27], v[166:169], v[218:221], v[24:27]
	v_mfma_f32_16x16x32_bf16 v[108:111], v[170:173], v[190:193], v[108:111]
	v_mfma_f32_16x16x32_bf16 v[104:107], v[182:185], v[190:193], v[104:107]
	v_mfma_f32_16x16x32_bf16 v[76:79], v[170:173], v[198:201], v[76:79]
	v_mfma_f32_16x16x32_bf16 v[72:75], v[182:185], v[198:201], v[72:75]
	v_mfma_f32_16x16x32_bf16 v[44:47], v[170:173], v[206:209], v[44:47]
	v_mfma_f32_16x16x32_bf16 v[40:43], v[182:185], v[206:209], v[40:43]
	v_mfma_f32_16x16x32_bf16 v[12:15], v[170:173], v[214:217], v[12:15]
	v_mfma_f32_16x16x32_bf16 v[8:11], v[182:185], v[214:217], v[8:11]
	v_mfma_f32_16x16x32_bf16 v[108:111], v[174:177], v[194:197], v[108:111]
	v_mfma_f32_16x16x32_bf16 v[104:107], v[186:189], v[194:197], v[104:107]
	v_mfma_f32_16x16x32_bf16 v[76:79], v[174:177], v[202:205], v[76:79]
	v_mfma_f32_16x16x32_bf16 v[72:75], v[186:189], v[202:205], v[72:75]
	v_mfma_f32_16x16x32_bf16 v[44:47], v[174:177], v[210:213], v[44:47]
	v_mfma_f32_16x16x32_bf16 v[40:43], v[186:189], v[210:213], v[40:43]
	v_mfma_f32_16x16x32_bf16 v[12:15], v[174:177], v[218:221], v[12:15]
	v_mfma_f32_16x16x32_bf16 v[8:11], v[186:189], v[218:221], v[8:11]
	s_barrier
	s_setprio 0
	s_mov_b32 m0, s63
	v_lshl_add_u64 v[178:179], s[72:73], 0, v[132:133]
	v_lshl_add_u64 v[222:223], s[72:73], 0, v[128:129]
	s_add_u32 s72, s72, s6
	ds_read_b128 v[190:193], v149 offset:16384
	ds_read_b128 v[194:197], v149 offset:17408
	ds_read_b128 v[198:201], v149 offset:18432
	ds_read_b128 v[202:205], v149 offset:19456
	ds_read_b128 v[206:209], v149 offset:20480
	ds_read_b128 v[210:213], v149 offset:21504
	ds_read_b128 v[214:217], v149 offset:22528
	ds_read_b128 v[218:221], v149 offset:23552
	global_load_lds_dwordx4 v[178:179], off
	s_mov_b32 m0, s64
	s_addc_u32 s73, s73, s7
	global_load_lds_dwordx4 v[222:223], off
	v_lshl_add_u64 v[224:225], s[72:73], 0, v[132:133]
	s_mov_b32 m0, s65
	v_lshl_add_u64 v[226:227], s[72:73], 0, v[128:129]
	global_load_lds_dwordx4 v[224:225], off
	s_mov_b32 m0, s66
	v_lshl_add_u64 v[228:229], s[22:23], 0, v[134:135]
	global_load_lds_dwordx4 v[226:227], off
	s_mov_b32 m0, s29
	v_lshl_add_u64 v[230:231], s[22:23], 0, v[130:131]
	global_load_lds_dwordx4 v[228:229], off
	s_mov_b32 m0, s30
	s_nop 0
	global_load_lds_dwordx4 v[230:231], off
	s_waitcnt vmcnt(8)
	s_waitcnt lgkmcnt(0)
	s_setprio 1
	s_barrier
	v_mfma_f32_16x16x32_bf16 v[116:119], v[152:155], v[190:193], v[116:119]
	v_mfma_f32_16x16x32_bf16 v[112:115], v[160:163], v[190:193], v[112:115]
	v_mfma_f32_16x16x32_bf16 v[84:87], v[152:155], v[198:201], v[84:87]
	v_mfma_f32_16x16x32_bf16 v[80:83], v[160:163], v[198:201], v[80:83]
	v_mfma_f32_16x16x32_bf16 v[52:55], v[152:155], v[206:209], v[52:55]
	v_mfma_f32_16x16x32_bf16 v[48:51], v[160:163], v[206:209], v[48:51]
	v_mfma_f32_16x16x32_bf16 v[20:23], v[152:155], v[214:217], v[20:23]
	v_mfma_f32_16x16x32_bf16 v[16:19], v[160:163], v[214:217], v[16:19]
	v_mfma_f32_16x16x32_bf16 v[116:119], v[156:159], v[194:197], v[116:119]
	v_mfma_f32_16x16x32_bf16 v[112:115], v[166:169], v[194:197], v[112:115]
	v_mfma_f32_16x16x32_bf16 v[84:87], v[156:159], v[202:205], v[84:87]
	v_mfma_f32_16x16x32_bf16 v[80:83], v[166:169], v[202:205], v[80:83]
	v_mfma_f32_16x16x32_bf16 v[52:55], v[156:159], v[210:213], v[52:55]
	v_mfma_f32_16x16x32_bf16 v[48:51], v[166:169], v[210:213], v[48:51]
	v_mfma_f32_16x16x32_bf16 v[20:23], v[156:159], v[218:221], v[20:23]
	v_mfma_f32_16x16x32_bf16 v[16:19], v[166:169], v[218:221], v[16:19]
	v_mfma_f32_16x16x32_bf16 v[100:103], v[170:173], v[190:193], v[100:103]
	v_mfma_f32_16x16x32_bf16 v[96:99], v[182:185], v[190:193], v[96:99]
	v_mfma_f32_16x16x32_bf16 v[68:71], v[170:173], v[198:201], v[68:71]
	v_mfma_f32_16x16x32_bf16 v[64:67], v[182:185], v[198:201], v[64:67]
	v_mfma_f32_16x16x32_bf16 v[36:39], v[170:173], v[206:209], v[36:39]
	v_mfma_f32_16x16x32_bf16 v[32:35], v[182:185], v[206:209], v[32:35]
	v_mfma_f32_16x16x32_bf16 v[4:7], v[170:173], v[214:217], v[4:7]
	v_mfma_f32_16x16x32_bf16 v[0:3], v[182:185], v[214:217], v[0:3]
	v_mfma_f32_16x16x32_bf16 v[100:103], v[174:177], v[194:197], v[100:103]
	v_mfma_f32_16x16x32_bf16 v[96:99], v[186:189], v[194:197], v[96:99]
	v_mfma_f32_16x16x32_bf16 v[68:71], v[174:177], v[202:205], v[68:71]
	v_mfma_f32_16x16x32_bf16 v[64:67], v[186:189], v[202:205], v[64:67]
	v_mfma_f32_16x16x32_bf16 v[36:39], v[174:177], v[210:213], v[36:39]
	v_mfma_f32_16x16x32_bf16 v[32:35], v[186:189], v[210:213], v[32:35]
	v_mfma_f32_16x16x32_bf16 v[4:7], v[174:177], v[218:221], v[4:7]
	v_mfma_f32_16x16x32_bf16 v[0:3], v[186:189], v[218:221], v[0:3]
	s_barrier
	s_setprio 0
	ds_read_b128 v[152:155], v150
	ds_read_b128 v[156:159], v150 offset:1024
	ds_read_b128 v[160:163], v150 offset:2048
	ds_read_b128 v[166:169], v150 offset:3072
	ds_read_b128 v[170:173], v151
	ds_read_b128 v[174:177], v151 offset:1024
	ds_read_b128 v[182:185], v151 offset:2048
	ds_read_b128 v[186:189], v151 offset:3072
	s_add_u32 s22, s22, s6
	s_addc_u32 s23, s23, s7
	s_mov_b32 m0, s31
	v_lshl_add_u64 v[232:233], s[22:23], 0, v[134:135]
	ds_read_b128 v[190:193], v149 offset:32768
	ds_read_b128 v[194:197], v149 offset:33792
	ds_read_b128 v[198:201], v149 offset:34816
	ds_read_b128 v[202:205], v149 offset:35840
	ds_read_b128 v[206:209], v149 offset:36864
	ds_read_b128 v[210:213], v149 offset:37888
	ds_read_b128 v[214:217], v149 offset:38912
	ds_read_b128 v[218:221], v149 offset:39936
	global_load_lds_dwordx4 v[232:233], off
	v_lshl_add_u64 v[232:233], s[22:23], 0, v[130:131]
	s_mov_b32 m0, s34
	s_nop 0
	global_load_lds_dwordx4 v[232:233], off
	s_waitcnt vmcnt(8)
	s_waitcnt lgkmcnt(0)
	s_setprio 1
	s_barrier
	v_mfma_f32_16x16x32_bf16 v[124:127], v[152:155], v[190:193], v[124:127]
	v_mfma_f32_16x16x32_bf16 v[120:123], v[160:163], v[190:193], v[120:123]
	v_mfma_f32_16x16x32_bf16 v[92:95], v[152:155], v[198:201], v[92:95]
	v_mfma_f32_16x16x32_bf16 v[88:91], v[160:163], v[198:201], v[88:91]
	v_mfma_f32_16x16x32_bf16 v[60:63], v[152:155], v[206:209], v[60:63]
	v_mfma_f32_16x16x32_bf16 v[56:59], v[160:163], v[206:209], v[56:59]
	v_mfma_f32_16x16x32_bf16 v[28:31], v[152:155], v[214:217], v[28:31]
	v_mfma_f32_16x16x32_bf16 v[24:27], v[160:163], v[214:217], v[24:27]
	v_mfma_f32_16x16x32_bf16 v[124:127], v[156:159], v[194:197], v[124:127]
	v_mfma_f32_16x16x32_bf16 v[120:123], v[166:169], v[194:197], v[120:123]
	v_mfma_f32_16x16x32_bf16 v[92:95], v[156:159], v[202:205], v[92:95]
	v_mfma_f32_16x16x32_bf16 v[88:91], v[166:169], v[202:205], v[88:91]
	v_mfma_f32_16x16x32_bf16 v[60:63], v[156:159], v[210:213], v[60:63]
	v_mfma_f32_16x16x32_bf16 v[56:59], v[166:169], v[210:213], v[56:59]
	v_mfma_f32_16x16x32_bf16 v[28:31], v[156:159], v[218:221], v[28:31]
	v_mfma_f32_16x16x32_bf16 v[24:27], v[166:169], v[218:221], v[24:27]
	v_mfma_f32_16x16x32_bf16 v[108:111], v[170:173], v[190:193], v[108:111]
	v_mfma_f32_16x16x32_bf16 v[104:107], v[182:185], v[190:193], v[104:107]
	v_mfma_f32_16x16x32_bf16 v[76:79], v[170:173], v[198:201], v[76:79]
	v_mfma_f32_16x16x32_bf16 v[72:75], v[182:185], v[198:201], v[72:75]
	v_mfma_f32_16x16x32_bf16 v[44:47], v[170:173], v[206:209], v[44:47]
	v_mfma_f32_16x16x32_bf16 v[40:43], v[182:185], v[206:209], v[40:43]
	v_mfma_f32_16x16x32_bf16 v[12:15], v[170:173], v[214:217], v[12:15]
	v_mfma_f32_16x16x32_bf16 v[8:11], v[182:185], v[214:217], v[8:11]
	v_mfma_f32_16x16x32_bf16 v[108:111], v[174:177], v[194:197], v[108:111]
	v_mfma_f32_16x16x32_bf16 v[104:107], v[186:189], v[194:197], v[104:107]
	v_mfma_f32_16x16x32_bf16 v[76:79], v[174:177], v[202:205], v[76:79]
	v_mfma_f32_16x16x32_bf16 v[72:75], v[186:189], v[202:205], v[72:75]
	v_mfma_f32_16x16x32_bf16 v[44:47], v[174:177], v[210:213], v[44:47]
	v_mfma_f32_16x16x32_bf16 v[40:43], v[186:189], v[210:213], v[40:43]
	v_mfma_f32_16x16x32_bf16 v[12:15], v[174:177], v[218:221], v[12:15]
	v_mfma_f32_16x16x32_bf16 v[8:11], v[186:189], v[218:221], v[8:11]
	s_barrier
	s_setprio 0
	s_mov_b32 m0, s67
	v_lshl_add_u64 v[178:179], v[178:179], 0, s[12:13]
	ds_read_b128 v[190:193], v149 offset:49152
	ds_read_b128 v[194:197], v149 offset:50176
	ds_read_b128 v[198:201], v149 offset:51200
	ds_read_b128 v[202:205], v149 offset:52224
	ds_read_b128 v[206:209], v149 offset:53248
	ds_read_b128 v[210:213], v149 offset:54272
	ds_read_b128 v[214:217], v149 offset:55296
	ds_read_b128 v[218:221], v149 offset:56320
	global_load_lds_dwordx4 v[178:179], off
	v_lshl_add_u64 v[178:179], v[222:223], 0, s[12:13]
	s_mov_b32 m0, s68
	s_nop 0
	global_load_lds_dwordx4 v[178:179], off
	v_lshl_add_u64 v[178:179], v[224:225], 0, s[12:13]
	s_mov_b32 m0, s69
	s_nop 0
	global_load_lds_dwordx4 v[178:179], off
	v_lshl_add_u64 v[178:179], v[226:227], 0, s[12:13]
	s_mov_b32 m0, s70
	s_nop 0
	global_load_lds_dwordx4 v[178:179], off
	v_lshl_add_u64 v[178:179], v[228:229], 0, s[12:13]
	s_mov_b32 m0, s36
	s_nop 0
	global_load_lds_dwordx4 v[178:179], off
	v_lshl_add_u64 v[178:179], v[230:231], 0, s[12:13]
	s_mov_b32 m0, s37
	s_nop 0
	global_load_lds_dwordx4 v[178:179], off
	s_waitcnt vmcnt(8)
	s_waitcnt lgkmcnt(0)
	s_setprio 1
	s_barrier
	v_mfma_f32_16x16x32_bf16 v[116:119], v[152:155], v[190:193], v[116:119]
	v_mfma_f32_16x16x32_bf16 v[112:115], v[160:163], v[190:193], v[112:115]
	v_mfma_f32_16x16x32_bf16 v[84:87], v[152:155], v[198:201], v[84:87]
	v_mfma_f32_16x16x32_bf16 v[80:83], v[160:163], v[198:201], v[80:83]
	v_mfma_f32_16x16x32_bf16 v[52:55], v[152:155], v[206:209], v[52:55]
	v_mfma_f32_16x16x32_bf16 v[48:51], v[160:163], v[206:209], v[48:51]
	v_mfma_f32_16x16x32_bf16 v[20:23], v[152:155], v[214:217], v[20:23]
	v_mfma_f32_16x16x32_bf16 v[16:19], v[160:163], v[214:217], v[16:19]
	v_mfma_f32_16x16x32_bf16 v[116:119], v[156:159], v[194:197], v[116:119]
	v_mfma_f32_16x16x32_bf16 v[112:115], v[166:169], v[194:197], v[112:115]
	v_mfma_f32_16x16x32_bf16 v[84:87], v[156:159], v[202:205], v[84:87]
	v_mfma_f32_16x16x32_bf16 v[80:83], v[166:169], v[202:205], v[80:83]
	v_mfma_f32_16x16x32_bf16 v[52:55], v[156:159], v[210:213], v[52:55]
	v_mfma_f32_16x16x32_bf16 v[48:51], v[166:169], v[210:213], v[48:51]
	v_mfma_f32_16x16x32_bf16 v[20:23], v[156:159], v[218:221], v[20:23]
	v_mfma_f32_16x16x32_bf16 v[16:19], v[166:169], v[218:221], v[16:19]
	v_mfma_f32_16x16x32_bf16 v[100:103], v[170:173], v[190:193], v[100:103]
	v_mfma_f32_16x16x32_bf16 v[96:99], v[182:185], v[190:193], v[96:99]
	v_mfma_f32_16x16x32_bf16 v[68:71], v[170:173], v[198:201], v[68:71]
	v_mfma_f32_16x16x32_bf16 v[64:67], v[182:185], v[198:201], v[64:67]
	v_mfma_f32_16x16x32_bf16 v[36:39], v[170:173], v[206:209], v[36:39]
	v_mfma_f32_16x16x32_bf16 v[32:35], v[182:185], v[206:209], v[32:35]
	v_mfma_f32_16x16x32_bf16 v[4:7], v[170:173], v[214:217], v[4:7]
	v_mfma_f32_16x16x32_bf16 v[0:3], v[182:185], v[214:217], v[0:3]
	v_mfma_f32_16x16x32_bf16 v[100:103], v[174:177], v[194:197], v[100:103]
	v_mfma_f32_16x16x32_bf16 v[96:99], v[186:189], v[194:197], v[96:99]
	v_mfma_f32_16x16x32_bf16 v[68:71], v[174:177], v[202:205], v[68:71]
	v_mfma_f32_16x16x32_bf16 v[64:67], v[186:189], v[202:205], v[64:67]
	v_mfma_f32_16x16x32_bf16 v[36:39], v[174:177], v[210:213], v[36:39]
	v_mfma_f32_16x16x32_bf16 v[32:35], v[186:189], v[210:213], v[32:35]
	v_mfma_f32_16x16x32_bf16 v[4:7], v[174:177], v[218:221], v[4:7]
	v_mfma_f32_16x16x32_bf16 v[0:3], v[186:189], v[218:221], v[0:3]
	s_barrier
	s_setprio 0
	s_add_u32 s20, s20, 0x100
	s_addc_u32 s21, s21, 0
	s_add_u32 s19, s19, 0x100
	s_addc_u32 s38, s38, 0
	s_cmp_ge_i32 s39, s51
	s_mov_b32 s22, s39
	s_cbranch_scc0 .LBB0_457

.LBB0_623:
	ds_read_b128 v[96:99], v89
	ds_read_b128 v[100:103], v89 offset:1024
	ds_read_b128 v[104:107], v89 offset:2048
	ds_read_b128 v[108:111], v89 offset:3072
	ds_read_b128 v[112:115], v90
	ds_read_b128 v[116:119], v90 offset:1024
	ds_read_b128 v[120:123], v90 offset:2048
	ds_read_b128 v[124:127], v90 offset:3072
	s_add_i32 s31, s28, 2
	s_add_u32 s39, s26, 0x80
	s_addc_u32 s29, s27, 0
	s_cmp_eq_u32 s71, s28
	s_cselect_b32 s28, s22, s39
	s_cselect_b32 s29, s23, s29
	s_cselect_b32 vcc_hi, s1, s30
	s_cselect_b32 vcc_lo, s0, s25
	s_mov_b32 m0, s76
	v_lshl_add_u64 v[84:85], s[26:27], 0, v[76:77]
	ds_read_b128 v[128:131], v91
	ds_read_b128 v[132:135], v91 offset:1024
	ds_read_b128 v[138:141], v91 offset:2048
	ds_read_b128 v[142:145], v91 offset:3072
	ds_read_b128 v[146:149], v91 offset:4096
	ds_read_b128 v[150:153], v91 offset:5120
	ds_read_b128 v[154:157], v91 offset:6144
	ds_read_b128 v[158:161], v91 offset:7168
	global_load_lds_dwordx4 v[84:85], off
	v_lshl_add_u64 v[84:85], s[26:27], 0, v[78:79]
	s_mov_b32 m0, s77
	s_nop 0
	global_load_lds_dwordx4 v[84:85], off
	s_waitcnt vmcnt(8)
	s_waitcnt lgkmcnt(0)
	s_setprio 1
	s_barrier
	v_mfma_f32_16x16x32_bf16 v[60:63], v[96:99], v[128:131], v[60:63]
	v_mfma_f32_16x16x32_bf16 v[56:59], v[104:107], v[128:131], v[56:59]
	v_mfma_f32_16x16x32_bf16 v[44:47], v[96:99], v[138:141], v[44:47]
	v_mfma_f32_16x16x32_bf16 v[40:43], v[104:107], v[138:141], v[40:43]
	v_mfma_f32_16x16x32_bf16 v[28:31], v[96:99], v[146:149], v[28:31]
	v_mfma_f32_16x16x32_bf16 v[24:27], v[104:107], v[146:149], v[24:27]
	v_mfma_f32_16x16x32_bf16 v[12:15], v[96:99], v[154:157], v[12:15]
	v_mfma_f32_16x16x32_bf16 v[8:11], v[104:107], v[154:157], v[8:11]
	v_mfma_f32_16x16x32_bf16 v[60:63], v[100:103], v[132:135], v[60:63]
	v_mfma_f32_16x16x32_bf16 v[56:59], v[108:111], v[132:135], v[56:59]
	v_mfma_f32_16x16x32_bf16 v[44:47], v[100:103], v[142:145], v[44:47]
	v_mfma_f32_16x16x32_bf16 v[40:43], v[108:111], v[142:145], v[40:43]
	v_mfma_f32_16x16x32_bf16 v[28:31], v[100:103], v[150:153], v[28:31]
	v_mfma_f32_16x16x32_bf16 v[24:27], v[108:111], v[150:153], v[24:27]
	v_mfma_f32_16x16x32_bf16 v[12:15], v[100:103], v[158:161], v[12:15]
	v_mfma_f32_16x16x32_bf16 v[8:11], v[108:111], v[158:161], v[8:11]
	v_mfma_f32_16x16x32_bf16 v[52:55], v[112:115], v[128:131], v[52:55]
	v_mfma_f32_16x16x32_bf16 v[48:51], v[120:123], v[128:131], v[48:51]
	v_mfma_f32_16x16x32_bf16 v[36:39], v[112:115], v[138:141], v[36:39]
	v_mfma_f32_16x16x32_bf16 v[32:35], v[120:123], v[138:141], v[32:35]
	v_mfma_f32_16x16x32_bf16 v[20:23], v[112:115], v[146:149], v[20:23]
	v_mfma_f32_16x16x32_bf16 v[16:19], v[120:123], v[146:149], v[16:19]
	v_mfma_f32_16x16x32_bf16 v[4:7], v[112:115], v[154:157], v[4:7]
	v_mfma_f32_16x16x32_bf16 v[0:3], v[120:123], v[154:157], v[0:3]
	v_mfma_f32_16x16x32_bf16 v[52:55], v[116:119], v[132:135], v[52:55]
	v_mfma_f32_16x16x32_bf16 v[48:51], v[124:127], v[132:135], v[48:51]
	v_mfma_f32_16x16x32_bf16 v[36:39], v[116:119], v[142:145], v[36:39]
	v_mfma_f32_16x16x32_bf16 v[32:35], v[124:127], v[142:145], v[32:35]
	v_mfma_f32_16x16x32_bf16 v[20:23], v[116:119], v[150:153], v[20:23]
	v_mfma_f32_16x16x32_bf16 v[16:19], v[124:127], v[150:153], v[16:19]
	v_mfma_f32_16x16x32_bf16 v[4:7], v[116:119], v[158:161], v[4:7]
	v_mfma_f32_16x16x32_bf16 v[0:3], v[124:127], v[158:161], v[0:3]
	s_barrier
	s_setprio 0
	s_mov_b32 m0, s93
	v_lshl_add_u64 v[84:85], vcc, 0, v[70:71]
	v_lshl_add_u64 v[162:163], vcc, 0, v[66:67]
	s_add_u32 vcc_lo, vcc_lo, s10
	global_load_lds_dwordx4 v[84:85], off
	s_mov_b32 m0, s94
	s_addc_u32 vcc_hi, vcc_hi, s11
	global_load_lds_dwordx4 v[162:163], off
	v_lshl_add_u64 v[166:167], vcc, 0, v[70:71]
	s_mov_b32 m0, s95
	v_lshl_add_u64 v[168:169], vcc, 0, v[66:67]
	global_load_lds_dwordx4 v[166:167], off
	s_mov_b32 m0, s96
	v_lshl_add_u64 v[170:171], s[28:29], 0, v[72:73]
	global_load_lds_dwordx4 v[168:169], off
	s_mov_b32 m0, s65
	v_lshl_add_u64 v[172:173], s[28:29], 0, v[68:69]
	global_load_lds_dwordx4 v[170:171], off
	s_mov_b32 m0, s66
	s_nop 0
	global_load_lds_dwordx4 v[172:173], off
	s_waitcnt vmcnt(8)
	s_waitcnt lgkmcnt(0)
	s_barrier
	s_setprio 1
	s_setprio 0
	s_setprio 1
	s_setprio 0
	s_barrier
	ds_read_b128 v[96:99], v92
	ds_read_b128 v[100:103], v92 offset:1024
	ds_read_b128 v[104:107], v92 offset:2048
	ds_read_b128 v[108:111], v92 offset:3072
	ds_read_b128 v[112:115], v93
	ds_read_b128 v[116:119], v93 offset:1024
	ds_read_b128 v[120:123], v93 offset:2048
	ds_read_b128 v[124:127], v93 offset:3072
	s_add_u32 s28, s28, s10
	s_addc_u32 s29, s29, s11
	s_mov_b32 m0, s67
	v_lshl_add_u64 v[174:175], s[28:29], 0, v[72:73]
	ds_read_b128 v[128:131], v91 offset:32768
	ds_read_b128 v[132:135], v91 offset:33792
	ds_read_b128 v[138:141], v91 offset:34816
	ds_read_b128 v[142:145], v91 offset:35840
	ds_read_b128 v[146:149], v91 offset:36864
	ds_read_b128 v[150:153], v91 offset:37888
	ds_read_b128 v[154:157], v91 offset:38912
	ds_read_b128 v[158:161], v91 offset:39936
	global_load_lds_dwordx4 v[174:175], off
	v_lshl_add_u64 v[174:175], s[28:29], 0, v[68:69]
	s_mov_b32 m0, s68
	s_nop 0
	global_load_lds_dwordx4 v[174:175], off
	s_waitcnt vmcnt(8)
	s_waitcnt lgkmcnt(0)
	s_setprio 1
	s_barrier
	v_mfma_f32_16x16x32_bf16 v[60:63], v[96:99], v[128:131], v[60:63]
	v_mfma_f32_16x16x32_bf16 v[56:59], v[104:107], v[128:131], v[56:59]
	v_mfma_f32_16x16x32_bf16 v[44:47], v[96:99], v[138:141], v[44:47]
	v_mfma_f32_16x16x32_bf16 v[40:43], v[104:107], v[138:141], v[40:43]
	v_mfma_f32_16x16x32_bf16 v[28:31], v[96:99], v[146:149], v[28:31]
	v_mfma_f32_16x16x32_bf16 v[24:27], v[104:107], v[146:149], v[24:27]
	v_mfma_f32_16x16x32_bf16 v[12:15], v[96:99], v[154:157], v[12:15]
	v_mfma_f32_16x16x32_bf16 v[8:11], v[104:107], v[154:157], v[8:11]
	v_mfma_f32_16x16x32_bf16 v[60:63], v[100:103], v[132:135], v[60:63]
	v_mfma_f32_16x16x32_bf16 v[56:59], v[108:111], v[132:135], v[56:59]
	v_mfma_f32_16x16x32_bf16 v[44:47], v[100:103], v[142:145], v[44:47]
	v_mfma_f32_16x16x32_bf16 v[40:43], v[108:111], v[142:145], v[40:43]
	v_mfma_f32_16x16x32_bf16 v[28:31], v[100:103], v[150:153], v[28:31]
	v_mfma_f32_16x16x32_bf16 v[24:27], v[108:111], v[150:153], v[24:27]
	v_mfma_f32_16x16x32_bf16 v[12:15], v[100:103], v[158:161], v[12:15]
	v_mfma_f32_16x16x32_bf16 v[8:11], v[108:111], v[158:161], v[8:11]
	v_mfma_f32_16x16x32_bf16 v[52:55], v[112:115], v[128:131], v[52:55]
	v_mfma_f32_16x16x32_bf16 v[48:51], v[120:123], v[128:131], v[48:51]
	v_mfma_f32_16x16x32_bf16 v[36:39], v[112:115], v[138:141], v[36:39]
	v_mfma_f32_16x16x32_bf16 v[32:35], v[120:123], v[138:141], v[32:35]
	v_mfma_f32_16x16x32_bf16 v[20:23], v[112:115], v[146:149], v[20:23]
	v_mfma_f32_16x16x32_bf16 v[16:19], v[120:123], v[146:149], v[16:19]
	v_mfma_f32_16x16x32_bf16 v[4:7], v[112:115], v[154:157], v[4:7]
	v_mfma_f32_16x16x32_bf16 v[0:3], v[120:123], v[154:157], v[0:3]
	v_mfma_f32_16x16x32_bf16 v[52:55], v[116:119], v[132:135], v[52:55]
	v_mfma_f32_16x16x32_bf16 v[48:51], v[124:127], v[132:135], v[48:51]
	v_mfma_f32_16x16x32_bf16 v[36:39], v[116:119], v[142:145], v[36:39]
	v_mfma_f32_16x16x32_bf16 v[32:35], v[124:127], v[142:145], v[32:35]
	v_mfma_f32_16x16x32_bf16 v[20:23], v[116:119], v[150:153], v[20:23]
	v_mfma_f32_16x16x32_bf16 v[16:19], v[124:127], v[150:153], v[16:19]
	v_mfma_f32_16x16x32_bf16 v[4:7], v[116:119], v[158:161], v[4:7]
	v_mfma_f32_16x16x32_bf16 v[0:3], v[124:127], v[158:161], v[0:3]
	s_barrier
	s_setprio 0
	s_mov_b32 m0, s97
	v_lshl_add_u64 v[84:85], v[84:85], 0, s[18:19]
	global_load_lds_dwordx4 v[84:85], off
	v_lshl_add_u64 v[84:85], v[162:163], 0, s[18:19]
	s_mov_b32 m0, s89
	s_nop 0
	global_load_lds_dwordx4 v[84:85], off
	v_lshl_add_u64 v[84:85], v[166:167], 0, s[18:19]
	s_mov_b32 m0, s73
	s_nop 0
	global_load_lds_dwordx4 v[84:85], off
	v_lshl_add_u64 v[84:85], v[168:169], 0, s[18:19]
	s_mov_b32 m0, s72
	s_nop 0
	global_load_lds_dwordx4 v[84:85], off
	v_lshl_add_u64 v[84:85], v[170:171], 0, s[18:19]
	s_mov_b32 m0, s69
	s_nop 0
	global_load_lds_dwordx4 v[84:85], off
	v_lshl_add_u64 v[84:85], v[172:173], 0, s[18:19]
	s_mov_b32 m0, s70
	s_nop 0
	global_load_lds_dwordx4 v[84:85], off
	s_waitcnt vmcnt(8)
	s_waitcnt lgkmcnt(0)
	s_barrier
	s_setprio 1
	s_setprio 0
	s_setprio 1
	s_setprio 0
	s_barrier
	s_add_u32 s26, s26, 0x100
	s_addc_u32 s27, s27, 0
	s_add_u32 s25, s25, 0x100
	s_addc_u32 s30, s30, 0
	s_cmp_ge_i32 s31, s36
	s_mov_b32 s28, s31
	s_cbranch_scc0 .LBB0_623

.LBB0_650:
	ds_read_b128 v[92:95], v86
	ds_read_b128 v[96:99], v86 offset:1024
	ds_read_b128 v[100:103], v86 offset:2048
	ds_read_b128 v[104:107], v86 offset:3072
	ds_read_b128 v[108:111], v87
	ds_read_b128 v[112:115], v87 offset:1024
	ds_read_b128 v[116:119], v87 offset:2048
	ds_read_b128 v[120:123], v87 offset:3072
	s_add_i32 s31, s28, 2
	s_add_u32 s39, s26, 0x80
	s_addc_u32 s29, s27, 0
	s_cmp_eq_u32 s68, s28
	s_cselect_b32 s28, s22, s39
	s_cselect_b32 s29, s23, s29
	s_cselect_b32 s95, s1, s30
	s_cselect_b32 s94, s0, s25
	s_mov_b32 m0, s50
	v_lshl_add_u64 v[84:85], s[26:27], 0, v[76:77]
	ds_read_b128 v[124:127], v88
	ds_read_b128 v[128:131], v88 offset:1024
	ds_read_b128 v[132:135], v88 offset:2048
	ds_read_b128 v[138:141], v88 offset:3072
	ds_read_b128 v[142:145], v88 offset:4096
	ds_read_b128 v[146:149], v88 offset:5120
	ds_read_b128 v[150:153], v88 offset:6144
	ds_read_b128 v[154:157], v88 offset:7168
	global_load_lds_dwordx4 v[84:85], off
	v_lshl_add_u64 v[84:85], s[26:27], 0, v[78:79]
	s_mov_b32 m0, s71
	s_nop 0
	global_load_lds_dwordx4 v[84:85], off
	s_waitcnt vmcnt(8)
	s_waitcnt lgkmcnt(0)
	s_setprio 1
	s_barrier
	v_mfma_f32_16x16x32_bf16 v[60:63], v[92:95], v[124:127], v[60:63]
	v_mfma_f32_16x16x32_bf16 v[56:59], v[100:103], v[124:127], v[56:59]
	v_mfma_f32_16x16x32_bf16 v[44:47], v[92:95], v[132:135], v[44:47]
	v_mfma_f32_16x16x32_bf16 v[40:43], v[100:103], v[132:135], v[40:43]
	v_mfma_f32_16x16x32_bf16 v[28:31], v[92:95], v[142:145], v[28:31]
	v_mfma_f32_16x16x32_bf16 v[24:27], v[100:103], v[142:145], v[24:27]
	v_mfma_f32_16x16x32_bf16 v[12:15], v[92:95], v[150:153], v[12:15]
	v_mfma_f32_16x16x32_bf16 v[8:11], v[100:103], v[150:153], v[8:11]
	v_mfma_f32_16x16x32_bf16 v[60:63], v[96:99], v[128:131], v[60:63]
	v_mfma_f32_16x16x32_bf16 v[56:59], v[104:107], v[128:131], v[56:59]
	v_mfma_f32_16x16x32_bf16 v[44:47], v[96:99], v[138:141], v[44:47]
	v_mfma_f32_16x16x32_bf16 v[40:43], v[104:107], v[138:141], v[40:43]
	v_mfma_f32_16x16x32_bf16 v[28:31], v[96:99], v[146:149], v[28:31]
	v_mfma_f32_16x16x32_bf16 v[24:27], v[104:107], v[146:149], v[24:27]
	v_mfma_f32_16x16x32_bf16 v[12:15], v[96:99], v[154:157], v[12:15]
	v_mfma_f32_16x16x32_bf16 v[8:11], v[104:107], v[154:157], v[8:11]
	v_mfma_f32_16x16x32_bf16 v[52:55], v[108:111], v[124:127], v[52:55]
	v_mfma_f32_16x16x32_bf16 v[48:51], v[116:119], v[124:127], v[48:51]
	v_mfma_f32_16x16x32_bf16 v[36:39], v[108:111], v[132:135], v[36:39]
	v_mfma_f32_16x16x32_bf16 v[32:35], v[116:119], v[132:135], v[32:35]
	v_mfma_f32_16x16x32_bf16 v[20:23], v[108:111], v[142:145], v[20:23]
	v_mfma_f32_16x16x32_bf16 v[16:19], v[116:119], v[142:145], v[16:19]
	v_mfma_f32_16x16x32_bf16 v[4:7], v[108:111], v[150:153], v[4:7]
	v_mfma_f32_16x16x32_bf16 v[0:3], v[116:119], v[150:153], v[0:3]
	v_mfma_f32_16x16x32_bf16 v[52:55], v[112:115], v[128:131], v[52:55]
	v_mfma_f32_16x16x32_bf16 v[48:51], v[120:123], v[128:131], v[48:51]
	v_mfma_f32_16x16x32_bf16 v[36:39], v[112:115], v[138:141], v[36:39]
	v_mfma_f32_16x16x32_bf16 v[32:35], v[120:123], v[138:141], v[32:35]
	v_mfma_f32_16x16x32_bf16 v[20:23], v[112:115], v[146:149], v[20:23]
	v_mfma_f32_16x16x32_bf16 v[16:19], v[120:123], v[146:149], v[16:19]
	v_mfma_f32_16x16x32_bf16 v[4:7], v[112:115], v[154:157], v[4:7]
	v_mfma_f32_16x16x32_bf16 v[0:3], v[120:123], v[154:157], v[0:3]
	s_barrier
	s_setprio 0
	s_mov_b32 m0, s74
	v_lshl_add_u64 v[84:85], s[94:95], 0, v[70:71]
	v_lshl_add_u64 v[158:159], s[94:95], 0, v[66:67]
	s_add_u32 s94, s94, s10
	global_load_lds_dwordx4 v[84:85], off
	s_mov_b32 m0, s75
	s_addc_u32 s95, s95, s11
	global_load_lds_dwordx4 v[158:159], off
	v_lshl_add_u64 v[160:161], s[94:95], 0, v[70:71]
	s_mov_b32 m0, s76
	v_lshl_add_u64 v[162:163], s[94:95], 0, v[66:67]
	global_load_lds_dwordx4 v[160:161], off
	s_mov_b32 m0, s77
	v_lshl_add_u64 v[166:167], s[28:29], 0, v[72:73]
	global_load_lds_dwordx4 v[162:163], off
	s_mov_b32 m0, s37
	v_lshl_add_u64 v[168:169], s[28:29], 0, v[68:69]
	global_load_lds_dwordx4 v[166:167], off
	s_mov_b32 m0, s51
	s_nop 0
	global_load_lds_dwordx4 v[168:169], off
	s_waitcnt vmcnt(8)
	s_waitcnt lgkmcnt(0)
	s_barrier
	s_setprio 1
	s_setprio 0
	s_setprio 1
	s_setprio 0
	s_barrier
	ds_read_b128 v[92:95], v89
	ds_read_b128 v[96:99], v89 offset:1024
	ds_read_b128 v[100:103], v89 offset:2048
	ds_read_b128 v[104:107], v89 offset:3072
	ds_read_b128 v[108:111], v90
	ds_read_b128 v[112:115], v90 offset:1024
	ds_read_b128 v[116:119], v90 offset:2048
	ds_read_b128 v[120:123], v90 offset:3072
	s_add_u32 s28, s28, s10
	s_addc_u32 s29, s29, s11
	s_mov_b32 m0, s52
	v_lshl_add_u64 v[170:171], s[28:29], 0, v[72:73]
	ds_read_b128 v[124:127], v88 offset:32768
	ds_read_b128 v[128:131], v88 offset:33792
	ds_read_b128 v[132:135], v88 offset:34816
	ds_read_b128 v[138:141], v88 offset:35840
	ds_read_b128 v[142:145], v88 offset:36864
	ds_read_b128 v[146:149], v88 offset:37888
	ds_read_b128 v[150:153], v88 offset:38912
	ds_read_b128 v[154:157], v88 offset:39936
	global_load_lds_dwordx4 v[170:171], off
	v_lshl_add_u64 v[170:171], s[28:29], 0, v[68:69]
	s_mov_b32 m0, s65
	s_nop 0
	global_load_lds_dwordx4 v[170:171], off
	s_waitcnt vmcnt(8)
	s_waitcnt lgkmcnt(0)
	s_setprio 1
	s_barrier
	v_mfma_f32_16x16x32_bf16 v[60:63], v[92:95], v[124:127], v[60:63]
	v_mfma_f32_16x16x32_bf16 v[56:59], v[100:103], v[124:127], v[56:59]
	v_mfma_f32_16x16x32_bf16 v[44:47], v[92:95], v[132:135], v[44:47]
	v_mfma_f32_16x16x32_bf16 v[40:43], v[100:103], v[132:135], v[40:43]
	v_mfma_f32_16x16x32_bf16 v[28:31], v[92:95], v[142:145], v[28:31]
	v_mfma_f32_16x16x32_bf16 v[24:27], v[100:103], v[142:145], v[24:27]
	v_mfma_f32_16x16x32_bf16 v[12:15], v[92:95], v[150:153], v[12:15]
	v_mfma_f32_16x16x32_bf16 v[8:11], v[100:103], v[150:153], v[8:11]
	v_mfma_f32_16x16x32_bf16 v[60:63], v[96:99], v[128:131], v[60:63]
	v_mfma_f32_16x16x32_bf16 v[56:59], v[104:107], v[128:131], v[56:59]
	v_mfma_f32_16x16x32_bf16 v[44:47], v[96:99], v[138:141], v[44:47]
	v_mfma_f32_16x16x32_bf16 v[40:43], v[104:107], v[138:141], v[40:43]
	v_mfma_f32_16x16x32_bf16 v[28:31], v[96:99], v[146:149], v[28:31]
	v_mfma_f32_16x16x32_bf16 v[24:27], v[104:107], v[146:149], v[24:27]
	v_mfma_f32_16x16x32_bf16 v[12:15], v[96:99], v[154:157], v[12:15]
	v_mfma_f32_16x16x32_bf16 v[8:11], v[104:107], v[154:157], v[8:11]
	v_mfma_f32_16x16x32_bf16 v[52:55], v[108:111], v[124:127], v[52:55]
	v_mfma_f32_16x16x32_bf16 v[48:51], v[116:119], v[124:127], v[48:51]
	v_mfma_f32_16x16x32_bf16 v[36:39], v[108:111], v[132:135], v[36:39]
	v_mfma_f32_16x16x32_bf16 v[32:35], v[116:119], v[132:135], v[32:35]
	v_mfma_f32_16x16x32_bf16 v[20:23], v[108:111], v[142:145], v[20:23]
	v_mfma_f32_16x16x32_bf16 v[16:19], v[116:119], v[142:145], v[16:19]
	v_mfma_f32_16x16x32_bf16 v[4:7], v[108:111], v[150:153], v[4:7]
	v_mfma_f32_16x16x32_bf16 v[0:3], v[116:119], v[150:153], v[0:3]
	v_mfma_f32_16x16x32_bf16 v[52:55], v[112:115], v[128:131], v[52:55]
	v_mfma_f32_16x16x32_bf16 v[48:51], v[120:123], v[128:131], v[48:51]
	v_mfma_f32_16x16x32_bf16 v[36:39], v[112:115], v[138:141], v[36:39]
	v_mfma_f32_16x16x32_bf16 v[32:35], v[120:123], v[138:141], v[32:35]
	v_mfma_f32_16x16x32_bf16 v[20:23], v[112:115], v[146:149], v[20:23]
	v_mfma_f32_16x16x32_bf16 v[16:19], v[120:123], v[146:149], v[16:19]
	v_mfma_f32_16x16x32_bf16 v[4:7], v[112:115], v[154:157], v[4:7]
	v_mfma_f32_16x16x32_bf16 v[0:3], v[120:123], v[154:157], v[0:3]
	s_barrier
	s_setprio 0
	s_mov_b32 m0, s89
	v_lshl_add_u64 v[84:85], v[84:85], 0, s[18:19]
	global_load_lds_dwordx4 v[84:85], off
	v_lshl_add_u64 v[84:85], v[158:159], 0, s[18:19]
	s_mov_b32 m0, s73
	s_nop 0
	global_load_lds_dwordx4 v[84:85], off
	v_lshl_add_u64 v[84:85], v[160:161], 0, s[18:19]
	s_mov_b32 m0, s72
	s_nop 0
	global_load_lds_dwordx4 v[84:85], off
	v_lshl_add_u64 v[84:85], v[162:163], 0, s[18:19]
	s_mov_b32 m0, s93
	s_nop 0
	global_load_lds_dwordx4 v[84:85], off
	v_lshl_add_u64 v[84:85], v[166:167], 0, s[18:19]
	s_mov_b32 m0, s66
	s_nop 0
	global_load_lds_dwordx4 v[84:85], off
	v_lshl_add_u64 v[84:85], v[168:169], 0, s[18:19]
	s_mov_b32 m0, s67
	s_nop 0
	global_load_lds_dwordx4 v[84:85], off
	s_waitcnt vmcnt(8)
	s_waitcnt lgkmcnt(0)
	s_barrier
	s_setprio 1
	s_setprio 0
	s_setprio 1
	s_setprio 0
	s_barrier
	s_add_u32 s26, s26, 0x100
	s_addc_u32 s27, s27, 0
	s_add_u32 s25, s25, 0x100
	s_addc_u32 s30, s30, 0
	s_cmp_ge_i32 s31, s36
	s_mov_b32 s28, s31
	s_cbranch_scc0 .LBB0_650

.LBB0_804:
	s_or_b32 s38, s38, 1
	v_add_u32_e32 v0, s69, v165
	s_mul_hi_u32 s39, s38, 0xa00000
	s_mul_i32 s38, s38, 0xa00000
	ds_read_b128 v[118:121], v0
	ds_read_b128 v[122:125], v0 offset:1024
	ds_read_b128 v[126:129], v0 offset:2048
	ds_read_b128 v[148:151], v0 offset:3072
	v_add_u32_e32 v0, s70, v165
	s_add_u32 s73, s30, s38
	ds_read_b128 v[152:155], v0
	ds_read_b128 v[156:159], v0 offset:1024
	ds_read_b128 v[160:163], v0 offset:2048
	ds_read_b128 v[206:209], v0 offset:3072
	s_addc_u32 s74, s31, s39
	s_add_u32 s75, s28, s40
	s_addc_u32 s76, s29, s41
	s_add_u32 s40, s44, 0xa00000
	s_addc_u32 s41, s45, 0
	s_and_b64 s[38:39], exec, s[42:43]
	s_cselect_b32 s43, s19, s76
	s_cselect_b32 s42, s25, s75
	s_add_u32 s38, s73, 0x2000
	s_addc_u32 s39, s74, 0
	v_lshl_add_u64 v[2:3], s[38:39], 0, v[166:167]
	s_add_i32 m0, s53, 0xc000
	ds_read_b128 v[210:213], v203
	ds_read_b128 v[214:217], v203 offset:1024
	ds_read_b128 v[218:221], v203 offset:2048
	ds_read_b128 v[222:225], v203 offset:3072
	ds_read_b128 v[226:229], v203 offset:4096
	ds_read_b128 v[230:233], v203 offset:5120
	ds_read_b128 v[234:237], v203 offset:6144
	ds_read_b128 v[238:241], v203 offset:7168
	global_load_lds_dwordx4 v[2:3], off
	v_lshl_add_u64 v[2:3], s[38:39], 0, v[170:171]
	s_add_i32 m0, s53, 0xe000
	s_nop 0
	global_load_lds_dwordx4 v[2:3], off
	s_waitcnt vmcnt(8)
	s_waitcnt lgkmcnt(0)
	s_setprio 1
	s_barrier
	v_mfma_f32_16x16x32_bf16 v[144:147], v[118:121], v[210:213], v[144:147]
	v_mfma_f32_16x16x32_bf16 v[140:143], v[126:129], v[210:213], v[140:143]
	v_mfma_f32_16x16x32_bf16 v[112:115], v[118:121], v[218:221], v[112:115]
	v_mfma_f32_16x16x32_bf16 v[108:111], v[126:129], v[218:221], v[108:111]
	v_mfma_f32_16x16x32_bf16 v[96:99], v[118:121], v[226:229], v[96:99]
	v_mfma_f32_16x16x32_bf16 v[92:95], v[126:129], v[226:229], v[92:95]
	v_mfma_f32_16x16x32_bf16 v[80:83], v[118:121], v[234:237], v[80:83]
	v_mfma_f32_16x16x32_bf16 v[76:79], v[126:129], v[234:237], v[76:79]
	v_mfma_f32_16x16x32_bf16 v[144:147], v[122:125], v[214:217], v[144:147]
	v_mfma_f32_16x16x32_bf16 v[140:143], v[148:151], v[214:217], v[140:143]
	v_mfma_f32_16x16x32_bf16 v[112:115], v[122:125], v[222:225], v[112:115]
	v_mfma_f32_16x16x32_bf16 v[108:111], v[148:151], v[222:225], v[108:111]
	v_mfma_f32_16x16x32_bf16 v[96:99], v[122:125], v[230:233], v[96:99]
	v_mfma_f32_16x16x32_bf16 v[92:95], v[148:151], v[230:233], v[92:95]
	v_mfma_f32_16x16x32_bf16 v[80:83], v[122:125], v[238:241], v[80:83]
	v_mfma_f32_16x16x32_bf16 v[76:79], v[148:151], v[238:241], v[76:79]
	v_mfma_f32_16x16x32_bf16 v[136:139], v[152:155], v[210:213], v[136:139]
	v_mfma_f32_16x16x32_bf16 v[130:133], v[160:163], v[210:213], v[132:135]
	v_mfma_f32_16x16x32_bf16 v[104:107], v[152:155], v[218:221], v[104:107]
	v_mfma_f32_16x16x32_bf16 v[100:103], v[160:163], v[218:221], v[100:103]
	v_mfma_f32_16x16x32_bf16 v[88:91], v[152:155], v[226:229], v[88:91]
	v_mfma_f32_16x16x32_bf16 v[84:87], v[160:163], v[226:229], v[84:87]
	v_mfma_f32_16x16x32_bf16 v[72:75], v[152:155], v[234:237], v[72:75]
	v_mfma_f32_16x16x32_bf16 v[68:71], v[160:163], v[234:237], v[68:71]
	v_mfma_f32_16x16x32_bf16 v[136:139], v[156:159], v[214:217], v[136:139]
	v_mfma_f32_16x16x32_bf16 v[130:133], v[206:209], v[214:217], v[130:133]
	v_mfma_f32_16x16x32_bf16 v[104:107], v[156:159], v[222:225], v[104:107]
	v_mfma_f32_16x16x32_bf16 v[100:103], v[206:209], v[222:225], v[100:103]
	v_mfma_f32_16x16x32_bf16 v[88:91], v[156:159], v[230:233], v[88:91]
	v_mfma_f32_16x16x32_bf16 v[84:87], v[206:209], v[230:233], v[84:87]
	v_mfma_f32_16x16x32_bf16 v[72:75], v[156:159], v[238:241], v[72:75]
	v_mfma_f32_16x16x32_bf16 v[68:71], v[206:209], v[238:241], v[68:71]
	s_barrier
	s_setprio 0
	s_add_i32 s38, s69, s48
	v_lshl_add_u64 v[242:243], s[42:43], 0, v[168:169]
	s_mov_b32 m0, s38
	ds_read_b128 v[210:213], v203 offset:16384
	ds_read_b128 v[214:217], v203 offset:17408
	ds_read_b128 v[218:221], v203 offset:18432
	ds_read_b128 v[222:225], v203 offset:19456
	ds_read_b128 v[226:229], v203 offset:20480
	ds_read_b128 v[230:233], v203 offset:21504
	ds_read_b128 v[234:237], v203 offset:22528
	ds_read_b128 v[238:241], v203 offset:23552
	global_load_lds_dwordx4 v[242:243], off
	s_add_i32 m0, s38, 0x2000
	s_add_u32 s38, s42, 0x40000
	v_lshl_add_u64 v[244:245], s[42:43], 0, v[172:173]
	s_addc_u32 s39, s43, 0
	s_add_i32 s73, s70, s48
	global_load_lds_dwordx4 v[244:245], off
	v_lshl_add_u64 v[2:3], s[38:39], 0, v[168:169]
	s_mov_b32 m0, s73
	s_nop 0
	global_load_lds_dwordx4 v[2:3], off
	v_lshl_add_u64 v[2:3], s[38:39], 0, v[172:173]
	s_add_i32 m0, s73, 0x2000
	s_nop 0
	global_load_lds_dwordx4 v[2:3], off
	v_lshl_add_u64 v[2:3], s[44:45], 0, v[166:167]
	s_mov_b32 m0, s53
	s_nop 0
	global_load_lds_dwordx4 v[2:3], off
	v_lshl_add_u64 v[2:3], s[44:45], 0, v[170:171]
	s_mov_b32 m0, s60
	s_nop 0
	global_load_lds_dwordx4 v[2:3], off
	s_waitcnt vmcnt(8)
	s_waitcnt lgkmcnt(0)
	s_setprio 1
	s_barrier
	v_mfma_f32_16x16x32_bf16 v[64:67], v[118:121], v[210:213], v[64:67]
	v_mfma_f32_16x16x32_bf16 v[60:63], v[126:129], v[210:213], v[60:63]
	v_mfma_f32_16x16x32_bf16 v[48:51], v[118:121], v[218:221], v[48:51]
	v_mfma_f32_16x16x32_bf16 v[44:47], v[126:129], v[218:221], v[44:47]
	v_mfma_f32_16x16x32_bf16 v[32:35], v[118:121], v[226:229], v[32:35]
	v_mfma_f32_16x16x32_bf16 v[28:31], v[126:129], v[226:229], v[28:31]
	v_mfma_f32_16x16x32_bf16 v[16:19], v[118:121], v[234:237], v[16:19]
	v_mfma_f32_16x16x32_bf16 v[12:15], v[126:129], v[234:237], v[12:15]
	v_mfma_f32_16x16x32_bf16 v[64:67], v[122:125], v[214:217], v[64:67]
	v_mfma_f32_16x16x32_bf16 v[60:63], v[148:151], v[214:217], v[60:63]
	v_mfma_f32_16x16x32_bf16 v[48:51], v[122:125], v[222:225], v[48:51]
	v_mfma_f32_16x16x32_bf16 v[44:47], v[148:151], v[222:225], v[44:47]
	v_mfma_f32_16x16x32_bf16 v[32:35], v[122:125], v[230:233], v[32:35]
	v_mfma_f32_16x16x32_bf16 v[28:31], v[148:151], v[230:233], v[28:31]
	v_mfma_f32_16x16x32_bf16 v[16:19], v[122:125], v[238:241], v[16:19]
	v_mfma_f32_16x16x32_bf16 v[12:15], v[148:151], v[238:241], v[12:15]
	v_mfma_f32_16x16x32_bf16 v[56:59], v[152:155], v[210:213], v[56:59]
	v_mfma_f32_16x16x32_bf16 v[52:55], v[160:163], v[210:213], v[52:55]
	v_mfma_f32_16x16x32_bf16 v[40:43], v[152:155], v[218:221], v[40:43]
	v_mfma_f32_16x16x32_bf16 v[36:39], v[160:163], v[218:221], v[36:39]
	v_mfma_f32_16x16x32_bf16 v[24:27], v[152:155], v[226:229], v[24:27]
	v_mfma_f32_16x16x32_bf16 v[20:23], v[160:163], v[226:229], v[20:23]
	v_mfma_f32_16x16x32_bf16 v[8:11], v[152:155], v[234:237], v[8:11]
	v_mfma_f32_16x16x32_bf16 v[2:5], v[160:163], v[234:237], v[4:7]
	v_mfma_f32_16x16x32_bf16 v[56:59], v[156:159], v[214:217], v[56:59]
	v_mfma_f32_16x16x32_bf16 v[52:55], v[206:209], v[214:217], v[52:55]
	v_mfma_f32_16x16x32_bf16 v[40:43], v[156:159], v[222:225], v[40:43]
	v_mfma_f32_16x16x32_bf16 v[36:39], v[206:209], v[222:225], v[36:39]
	v_mfma_f32_16x16x32_bf16 v[24:27], v[156:159], v[230:233], v[24:27]
	v_mfma_f32_16x16x32_bf16 v[20:23], v[206:209], v[230:233], v[20:23]
	v_mfma_f32_16x16x32_bf16 v[8:11], v[156:159], v[238:241], v[8:11]
	v_mfma_f32_16x16x32_bf16 v[2:5], v[206:209], v[238:241], v[2:5]
	s_barrier
	s_setprio 0
	s_add_i32 s73, 0, 0x18000
	v_add_u32_e32 v0, s73, v165
	s_add_i32 s74, 0, 0x1c000
	ds_read_b128 v[118:121], v0
	ds_read_b128 v[122:125], v0 offset:1024
	ds_read_b128 v[126:129], v0 offset:2048
	ds_read_b128 v[148:151], v0 offset:3072
	v_add_u32_e32 v0, s74, v165
	ds_read_b128 v[152:155], v0
	ds_read_b128 v[156:159], v0 offset:1024
	ds_read_b128 v[160:163], v0 offset:2048
	ds_read_b128 v[206:209], v0 offset:3072
	s_add_u32 s38, s44, 0x2000
	s_addc_u32 s39, s45, 0
	s_mov_b32 m0, s61
	v_lshl_add_u64 v[6:7], s[38:39], 0, v[166:167]
	ds_read_b128 v[210:213], v203 offset:32768
	ds_read_b128 v[214:217], v203 offset:33792
	ds_read_b128 v[218:221], v203 offset:34816
	ds_read_b128 v[222:225], v203 offset:35840
	ds_read_b128 v[226:229], v203 offset:36864
	ds_read_b128 v[230:233], v203 offset:37888
	ds_read_b128 v[234:237], v203 offset:38912
	ds_read_b128 v[238:241], v203 offset:39936
	global_load_lds_dwordx4 v[6:7], off
	v_lshl_add_u64 v[6:7], s[38:39], 0, v[170:171]
	s_mov_b32 m0, s62
	s_nop 0
	global_load_lds_dwordx4 v[6:7], off
	s_waitcnt vmcnt(8)
	s_waitcnt lgkmcnt(0)
	s_setprio 1
	s_barrier
	v_mfma_f32_16x16x32_bf16 v[144:147], v[118:121], v[210:213], v[144:147]
	v_mfma_f32_16x16x32_bf16 v[140:143], v[126:129], v[210:213], v[140:143]
	v_mfma_f32_16x16x32_bf16 v[112:115], v[118:121], v[218:221], v[112:115]
	v_mfma_f32_16x16x32_bf16 v[108:111], v[126:129], v[218:221], v[108:111]
	v_mfma_f32_16x16x32_bf16 v[96:99], v[118:121], v[226:229], v[96:99]
	v_mfma_f32_16x16x32_bf16 v[92:95], v[126:129], v[226:229], v[92:95]
	v_mfma_f32_16x16x32_bf16 v[80:83], v[118:121], v[234:237], v[80:83]
	v_mfma_f32_16x16x32_bf16 v[76:79], v[126:129], v[234:237], v[76:79]
	v_mfma_f32_16x16x32_bf16 v[144:147], v[122:125], v[214:217], v[144:147]
	v_mfma_f32_16x16x32_bf16 v[140:143], v[148:151], v[214:217], v[140:143]
	v_mfma_f32_16x16x32_bf16 v[112:115], v[122:125], v[222:225], v[112:115]
	v_mfma_f32_16x16x32_bf16 v[108:111], v[148:151], v[222:225], v[108:111]
	v_mfma_f32_16x16x32_bf16 v[96:99], v[122:125], v[230:233], v[96:99]
	v_mfma_f32_16x16x32_bf16 v[92:95], v[148:151], v[230:233], v[92:95]
	v_mfma_f32_16x16x32_bf16 v[80:83], v[122:125], v[238:241], v[80:83]
	v_mfma_f32_16x16x32_bf16 v[76:79], v[148:151], v[238:241], v[76:79]
	v_mfma_f32_16x16x32_bf16 v[134:137], v[152:155], v[210:213], v[136:139]
	v_mfma_f32_16x16x32_bf16 v[130:133], v[160:163], v[210:213], v[130:133]
	v_mfma_f32_16x16x32_bf16 v[104:107], v[152:155], v[218:221], v[104:107]
	v_mfma_f32_16x16x32_bf16 v[100:103], v[160:163], v[218:221], v[100:103]
	v_mfma_f32_16x16x32_bf16 v[88:91], v[152:155], v[226:229], v[88:91]
	v_mfma_f32_16x16x32_bf16 v[84:87], v[160:163], v[226:229], v[84:87]
	v_mfma_f32_16x16x32_bf16 v[72:75], v[152:155], v[234:237], v[72:75]
	v_mfma_f32_16x16x32_bf16 v[68:71], v[160:163], v[234:237], v[68:71]
	v_mfma_f32_16x16x32_bf16 v[136:139], v[156:159], v[214:217], v[134:137]
	v_mfma_f32_16x16x32_bf16 v[132:135], v[206:209], v[214:217], v[130:133]
	v_mfma_f32_16x16x32_bf16 v[104:107], v[156:159], v[222:225], v[104:107]
	v_mfma_f32_16x16x32_bf16 v[100:103], v[206:209], v[222:225], v[100:103]
	v_mfma_f32_16x16x32_bf16 v[88:91], v[156:159], v[230:233], v[88:91]
	v_mfma_f32_16x16x32_bf16 v[84:87], v[206:209], v[230:233], v[84:87]
	v_mfma_f32_16x16x32_bf16 v[72:75], v[156:159], v[238:241], v[72:75]
	v_mfma_f32_16x16x32_bf16 v[68:71], v[206:209], v[238:241], v[68:71]
	s_barrier
	s_setprio 0
	s_add_i32 s38, s73, s48
	v_lshl_add_u64 v[6:7], v[242:243], 0, s[10:11]
	s_mov_b32 m0, s38
	ds_read_b128 v[210:213], v203 offset:49152
	ds_read_b128 v[214:217], v203 offset:50176
	ds_read_b128 v[218:221], v203 offset:51200
	ds_read_b128 v[222:225], v203 offset:52224
	ds_read_b128 v[226:229], v203 offset:53248
	ds_read_b128 v[230:233], v203 offset:54272
	ds_read_b128 v[234:237], v203 offset:55296
	ds_read_b128 v[238:241], v203 offset:56320
	global_load_lds_dwordx4 v[6:7], off
	s_add_i32 m0, s38, 0x2000
	s_add_u32 s38, s42, 0x40080
	v_lshl_add_u64 v[6:7], v[244:245], 0, s[10:11]
	s_addc_u32 s39, s43, 0
	s_add_i32 s42, s74, s48
	global_load_lds_dwordx4 v[6:7], off
	v_lshl_add_u64 v[6:7], s[38:39], 0, v[168:169]
	s_mov_b32 m0, s42
	s_nop 0
	global_load_lds_dwordx4 v[6:7], off
	v_lshl_add_u64 v[6:7], s[38:39], 0, v[172:173]
	s_add_i32 m0, s42, 0x2000
	s_nop 0
	global_load_lds_dwordx4 v[6:7], off
	v_lshl_add_u64 v[6:7], s[40:41], 0, v[166:167]
	s_mov_b32 m0, s65
	s_nop 0
	global_load_lds_dwordx4 v[6:7], off
	v_lshl_add_u64 v[6:7], s[40:41], 0, v[170:171]
	s_mov_b32 m0, s66
	s_nop 0
	global_load_lds_dwordx4 v[6:7], off
	s_waitcnt vmcnt(8)
	s_waitcnt lgkmcnt(0)
	s_setprio 1
	s_barrier
	v_mfma_f32_16x16x32_bf16 v[64:67], v[118:121], v[210:213], v[64:67]
	v_mfma_f32_16x16x32_bf16 v[60:63], v[126:129], v[210:213], v[60:63]
	v_mfma_f32_16x16x32_bf16 v[48:51], v[118:121], v[218:221], v[48:51]
	v_mfma_f32_16x16x32_bf16 v[44:47], v[126:129], v[218:221], v[44:47]
	v_mfma_f32_16x16x32_bf16 v[32:35], v[118:121], v[226:229], v[32:35]
	v_mfma_f32_16x16x32_bf16 v[28:31], v[126:129], v[226:229], v[28:31]
	v_mfma_f32_16x16x32_bf16 v[16:19], v[118:121], v[234:237], v[16:19]
	v_mfma_f32_16x16x32_bf16 v[12:15], v[126:129], v[234:237], v[12:15]
	v_mfma_f32_16x16x32_bf16 v[64:67], v[122:125], v[214:217], v[64:67]
	v_mfma_f32_16x16x32_bf16 v[60:63], v[148:151], v[214:217], v[60:63]
	v_mfma_f32_16x16x32_bf16 v[48:51], v[122:125], v[222:225], v[48:51]
	v_mfma_f32_16x16x32_bf16 v[44:47], v[148:151], v[222:225], v[44:47]
	v_mfma_f32_16x16x32_bf16 v[32:35], v[122:125], v[230:233], v[32:35]
	v_mfma_f32_16x16x32_bf16 v[28:31], v[148:151], v[230:233], v[28:31]
	v_mfma_f32_16x16x32_bf16 v[16:19], v[122:125], v[238:241], v[16:19]
	v_mfma_f32_16x16x32_bf16 v[12:15], v[148:151], v[238:241], v[12:15]
	v_mfma_f32_16x16x32_bf16 v[56:59], v[152:155], v[210:213], v[56:59]
	v_mfma_f32_16x16x32_bf16 v[52:55], v[160:163], v[210:213], v[52:55]
	v_mfma_f32_16x16x32_bf16 v[40:43], v[152:155], v[218:221], v[40:43]
	v_mfma_f32_16x16x32_bf16 v[36:39], v[160:163], v[218:221], v[36:39]
	v_mfma_f32_16x16x32_bf16 v[24:27], v[152:155], v[226:229], v[24:27]
	v_mfma_f32_16x16x32_bf16 v[20:23], v[160:163], v[226:229], v[20:23]
	v_mfma_f32_16x16x32_bf16 v[6:9], v[152:155], v[234:237], v[8:11]
	v_mfma_f32_16x16x32_bf16 v[2:5], v[160:163], v[234:237], v[2:5]
	v_mfma_f32_16x16x32_bf16 v[56:59], v[156:159], v[214:217], v[56:59]
	v_mfma_f32_16x16x32_bf16 v[52:55], v[206:209], v[214:217], v[52:55]
	v_mfma_f32_16x16x32_bf16 v[40:43], v[156:159], v[222:225], v[40:43]
	v_mfma_f32_16x16x32_bf16 v[36:39], v[206:209], v[222:225], v[36:39]
	v_mfma_f32_16x16x32_bf16 v[24:27], v[156:159], v[230:233], v[24:27]
	v_mfma_f32_16x16x32_bf16 v[20:23], v[206:209], v[230:233], v[20:23]
	v_mfma_f32_16x16x32_bf16 v[8:11], v[156:159], v[238:241], v[6:9]
	v_mfma_f32_16x16x32_bf16 v[4:7], v[206:209], v[238:241], v[2:5]
	s_barrier
	s_setprio 0
	s_cmp_ge_u32 s0, s27
	s_cbranch_scc1 .LBB0_797
	s_mov_b32 s38, s0
	s_cmp_eq_u32 s38, 14
	s_cselect_b64 s[42:43], -1, 0
	s_and_b64 vcc, exec, s[42:43]
	s_cbranch_vccz .LBB0_802
	s_branch .LBB0_803

.LBB0_956:
	ds_read_b128 v[154:157], v150
	ds_read_b128 v[158:161], v150 offset:1024
	ds_read_b128 v[166:169], v150 offset:2048
	ds_read_b128 v[170:173], v150 offset:3072
	ds_read_b128 v[174:177], v151
	ds_read_b128 v[178:181], v151 offset:1024
	ds_read_b128 v[182:185], v151 offset:2048
	ds_read_b128 v[186:189], v151 offset:3072
	s_add_u32 s22, s20, 0xfffc0080
	s_addc_u32 s23, s21, -1
	s_cmp_eq_u32 s53, 12
	s_cselect_b32 s25, s13, s23
	s_cselect_b32 s24, s38, s22
	s_cselect_b32 s23, s11, s52
	s_cselect_b32 s22, s39, s51
	v_lshl_add_u64 v[146:147], s[20:21], 0, v[138:139]
	s_add_i32 m0, s35, 0xc000
	ds_read_b128 v[190:193], v152
	ds_read_b128 v[194:197], v152 offset:1024
	ds_read_b128 v[198:201], v152 offset:2048
	ds_read_b128 v[202:205], v152 offset:3072
	ds_read_b128 v[206:209], v152 offset:4096
	ds_read_b128 v[210:213], v152 offset:5120
	ds_read_b128 v[214:217], v152 offset:6144
	ds_read_b128 v[218:221], v152 offset:7168
	global_load_lds_dwordx4 v[146:147], off
	v_lshl_add_u64 v[146:147], s[20:21], 0, v[140:141]
	s_add_i32 m0, s35, 0xe000
	s_nop 0
	global_load_lds_dwordx4 v[146:147], off
	s_waitcnt vmcnt(8)
	s_waitcnt lgkmcnt(0)
	s_setprio 1
	s_barrier
	v_mfma_f32_16x16x32_bf16 v[124:127], v[154:157], v[190:193], v[124:127]
	v_mfma_f32_16x16x32_bf16 v[120:123], v[166:169], v[190:193], v[120:123]
	v_mfma_f32_16x16x32_bf16 v[108:111], v[154:157], v[198:201], v[108:111]
	v_mfma_f32_16x16x32_bf16 v[104:107], v[166:169], v[198:201], v[104:107]
	v_mfma_f32_16x16x32_bf16 v[92:95], v[154:157], v[206:209], v[92:95]
	v_mfma_f32_16x16x32_bf16 v[88:91], v[166:169], v[206:209], v[88:91]
	v_mfma_f32_16x16x32_bf16 v[76:79], v[154:157], v[214:217], v[76:79]
	v_mfma_f32_16x16x32_bf16 v[72:75], v[166:169], v[214:217], v[72:75]
	v_mfma_f32_16x16x32_bf16 v[124:127], v[158:161], v[194:197], v[124:127]
	v_mfma_f32_16x16x32_bf16 v[120:123], v[170:173], v[194:197], v[120:123]
	v_mfma_f32_16x16x32_bf16 v[108:111], v[158:161], v[202:205], v[108:111]
	v_mfma_f32_16x16x32_bf16 v[104:107], v[170:173], v[202:205], v[104:107]
	v_mfma_f32_16x16x32_bf16 v[92:95], v[158:161], v[210:213], v[92:95]
	v_mfma_f32_16x16x32_bf16 v[88:91], v[170:173], v[210:213], v[88:91]
	v_mfma_f32_16x16x32_bf16 v[76:79], v[158:161], v[218:221], v[76:79]
	v_mfma_f32_16x16x32_bf16 v[72:75], v[170:173], v[218:221], v[72:75]
	v_mfma_f32_16x16x32_bf16 v[116:119], v[174:177], v[190:193], v[116:119]
	v_mfma_f32_16x16x32_bf16 v[112:115], v[182:185], v[190:193], v[112:115]
	v_mfma_f32_16x16x32_bf16 v[100:103], v[174:177], v[198:201], v[100:103]
	v_mfma_f32_16x16x32_bf16 v[96:99], v[182:185], v[198:201], v[96:99]
	v_mfma_f32_16x16x32_bf16 v[84:87], v[174:177], v[206:209], v[84:87]
	v_mfma_f32_16x16x32_bf16 v[80:83], v[182:185], v[206:209], v[80:83]
	v_mfma_f32_16x16x32_bf16 v[68:71], v[174:177], v[214:217], v[68:71]
	v_mfma_f32_16x16x32_bf16 v[64:67], v[182:185], v[214:217], v[64:67]
	v_mfma_f32_16x16x32_bf16 v[116:119], v[178:181], v[194:197], v[116:119]
	v_mfma_f32_16x16x32_bf16 v[112:115], v[186:189], v[194:197], v[112:115]
	v_mfma_f32_16x16x32_bf16 v[100:103], v[178:181], v[202:205], v[100:103]
	v_mfma_f32_16x16x32_bf16 v[96:99], v[186:189], v[202:205], v[96:99]
	v_mfma_f32_16x16x32_bf16 v[84:87], v[178:181], v[210:213], v[84:87]
	v_mfma_f32_16x16x32_bf16 v[80:83], v[186:189], v[210:213], v[80:83]
	v_mfma_f32_16x16x32_bf16 v[68:71], v[178:181], v[218:221], v[68:71]
	v_mfma_f32_16x16x32_bf16 v[64:67], v[186:189], v[218:221], v[64:67]
	s_barrier
	s_setprio 0
	s_add_i32 s54, s49, s30
	v_lshl_add_u64 v[146:147], s[22:23], 0, v[132:133]
	s_mov_b32 m0, s54
	ds_read_b128 v[190:193], v152 offset:16384
	ds_read_b128 v[194:197], v152 offset:17408
	ds_read_b128 v[198:201], v152 offset:18432
	ds_read_b128 v[202:205], v152 offset:19456
	ds_read_b128 v[206:209], v152 offset:20480
	ds_read_b128 v[210:213], v152 offset:21504
	ds_read_b128 v[214:217], v152 offset:22528
	ds_read_b128 v[218:221], v152 offset:23552
	global_load_lds_dwordx4 v[146:147], off
	s_add_i32 m0, s54, 0x2000
	s_add_u32 s54, s22, 0x40000
	v_lshl_add_u64 v[162:163], s[22:23], 0, v[128:129]
	s_addc_u32 s55, s23, 0
	s_add_i32 s56, s50, s30
	global_load_lds_dwordx4 v[162:163], off
	v_lshl_add_u64 v[222:223], s[54:55], 0, v[132:133]
	s_mov_b32 m0, s56
	v_lshl_add_u64 v[224:225], s[24:25], 0, v[130:131]
	global_load_lds_dwordx4 v[222:223], off
	v_lshl_add_u64 v[222:223], s[54:55], 0, v[128:129]
	s_add_i32 m0, s56, 0x2000
	s_nop 0
	global_load_lds_dwordx4 v[222:223], off
	v_lshl_add_u64 v[222:223], s[24:25], 0, v[134:135]
	s_mov_b32 m0, s35
	s_nop 0
	global_load_lds_dwordx4 v[222:223], off
	s_mov_b32 m0, s36
	s_nop 0
	global_load_lds_dwordx4 v[224:225], off
	s_waitcnt vmcnt(8)
	s_waitcnt lgkmcnt(0)
	s_setprio 1
	s_barrier
	v_mfma_f32_16x16x32_bf16 v[60:63], v[154:157], v[190:193], v[60:63]
	v_mfma_f32_16x16x32_bf16 v[56:59], v[166:169], v[190:193], v[56:59]
	v_mfma_f32_16x16x32_bf16 v[44:47], v[154:157], v[198:201], v[44:47]
	v_mfma_f32_16x16x32_bf16 v[40:43], v[166:169], v[198:201], v[40:43]
	v_mfma_f32_16x16x32_bf16 v[28:31], v[154:157], v[206:209], v[28:31]
	v_mfma_f32_16x16x32_bf16 v[24:27], v[166:169], v[206:209], v[24:27]
	v_mfma_f32_16x16x32_bf16 v[12:15], v[154:157], v[214:217], v[12:15]
	v_mfma_f32_16x16x32_bf16 v[8:11], v[166:169], v[214:217], v[8:11]
	v_mfma_f32_16x16x32_bf16 v[60:63], v[158:161], v[194:197], v[60:63]
	v_mfma_f32_16x16x32_bf16 v[56:59], v[170:173], v[194:197], v[56:59]
	v_mfma_f32_16x16x32_bf16 v[44:47], v[158:161], v[202:205], v[44:47]
	v_mfma_f32_16x16x32_bf16 v[40:43], v[170:173], v[202:205], v[40:43]
	v_mfma_f32_16x16x32_bf16 v[28:31], v[158:161], v[210:213], v[28:31]
	v_mfma_f32_16x16x32_bf16 v[24:27], v[170:173], v[210:213], v[24:27]
	v_mfma_f32_16x16x32_bf16 v[12:15], v[158:161], v[218:221], v[12:15]
	v_mfma_f32_16x16x32_bf16 v[8:11], v[170:173], v[218:221], v[8:11]
	v_mfma_f32_16x16x32_bf16 v[52:55], v[174:177], v[190:193], v[52:55]
	v_mfma_f32_16x16x32_bf16 v[48:51], v[182:185], v[190:193], v[48:51]
	v_mfma_f32_16x16x32_bf16 v[36:39], v[174:177], v[198:201], v[36:39]
	v_mfma_f32_16x16x32_bf16 v[32:35], v[182:185], v[198:201], v[32:35]
	v_mfma_f32_16x16x32_bf16 v[20:23], v[174:177], v[206:209], v[20:23]
	v_mfma_f32_16x16x32_bf16 v[16:19], v[182:185], v[206:209], v[16:19]
	v_mfma_f32_16x16x32_bf16 v[4:7], v[174:177], v[214:217], v[4:7]
	v_mfma_f32_16x16x32_bf16 v[0:3], v[182:185], v[214:217], v[0:3]
	v_mfma_f32_16x16x32_bf16 v[52:55], v[178:181], v[194:197], v[52:55]
	v_mfma_f32_16x16x32_bf16 v[48:51], v[186:189], v[194:197], v[48:51]
	v_mfma_f32_16x16x32_bf16 v[36:39], v[178:181], v[202:205], v[36:39]
	v_mfma_f32_16x16x32_bf16 v[32:35], v[186:189], v[202:205], v[32:35]
	v_mfma_f32_16x16x32_bf16 v[20:23], v[178:181], v[210:213], v[20:23]
	v_mfma_f32_16x16x32_bf16 v[16:19], v[186:189], v[210:213], v[16:19]
	v_mfma_f32_16x16x32_bf16 v[4:7], v[178:181], v[218:221], v[4:7]
	v_mfma_f32_16x16x32_bf16 v[0:3], v[186:189], v[218:221], v[0:3]
	s_barrier
	s_setprio 0
	s_add_i32 s54, 0, 0x18000
	v_add_u32_e32 v153, s54, v149
	s_add_i32 s55, 0, 0x1c000
	ds_read_b128 v[154:157], v153
	ds_read_b128 v[158:161], v153 offset:1024
	ds_read_b128 v[166:169], v153 offset:2048
	ds_read_b128 v[170:173], v153 offset:3072
	v_add_u32_e32 v153, s55, v149
	ds_read_b128 v[174:177], v153
	ds_read_b128 v[178:181], v153 offset:1024
	ds_read_b128 v[182:185], v153 offset:2048
	ds_read_b128 v[186:189], v153 offset:3072
	s_add_u32 s24, s24, 0x40000
	s_addc_u32 s25, s25, 0
	s_mov_b32 m0, s37
	v_lshl_add_u64 v[226:227], s[24:25], 0, v[134:135]
	ds_read_b128 v[190:193], v152 offset:32768
	ds_read_b128 v[194:197], v152 offset:33792
	ds_read_b128 v[198:201], v152 offset:34816
	ds_read_b128 v[202:205], v152 offset:35840
	ds_read_b128 v[206:209], v152 offset:36864
	ds_read_b128 v[210:213], v152 offset:37888
	ds_read_b128 v[214:217], v152 offset:38912
	ds_read_b128 v[218:221], v152 offset:39936
	global_load_lds_dwordx4 v[226:227], off
	v_lshl_add_u64 v[226:227], s[24:25], 0, v[130:131]
	s_mov_b32 m0, s40
	s_nop 0
	global_load_lds_dwordx4 v[226:227], off
	s_waitcnt vmcnt(8)
	s_waitcnt lgkmcnt(0)
	s_setprio 1
	s_barrier
	v_mfma_f32_16x16x32_bf16 v[124:127], v[154:157], v[190:193], v[124:127]
	v_mfma_f32_16x16x32_bf16 v[120:123], v[166:169], v[190:193], v[120:123]
	v_mfma_f32_16x16x32_bf16 v[108:111], v[154:157], v[198:201], v[108:111]
	v_mfma_f32_16x16x32_bf16 v[104:107], v[166:169], v[198:201], v[104:107]
	v_mfma_f32_16x16x32_bf16 v[92:95], v[154:157], v[206:209], v[92:95]
	v_mfma_f32_16x16x32_bf16 v[88:91], v[166:169], v[206:209], v[88:91]
	v_mfma_f32_16x16x32_bf16 v[76:79], v[154:157], v[214:217], v[76:79]
	v_mfma_f32_16x16x32_bf16 v[72:75], v[166:169], v[214:217], v[72:75]
	v_mfma_f32_16x16x32_bf16 v[124:127], v[158:161], v[194:197], v[124:127]
	v_mfma_f32_16x16x32_bf16 v[120:123], v[170:173], v[194:197], v[120:123]
	v_mfma_f32_16x16x32_bf16 v[108:111], v[158:161], v[202:205], v[108:111]
	v_mfma_f32_16x16x32_bf16 v[104:107], v[170:173], v[202:205], v[104:107]
	v_mfma_f32_16x16x32_bf16 v[92:95], v[158:161], v[210:213], v[92:95]
	v_mfma_f32_16x16x32_bf16 v[88:91], v[170:173], v[210:213], v[88:91]
	v_mfma_f32_16x16x32_bf16 v[76:79], v[158:161], v[218:221], v[76:79]
	v_mfma_f32_16x16x32_bf16 v[72:75], v[170:173], v[218:221], v[72:75]
	v_mfma_f32_16x16x32_bf16 v[116:119], v[174:177], v[190:193], v[116:119]
	v_mfma_f32_16x16x32_bf16 v[112:115], v[182:185], v[190:193], v[112:115]
	v_mfma_f32_16x16x32_bf16 v[100:103], v[174:177], v[198:201], v[100:103]
	v_mfma_f32_16x16x32_bf16 v[96:99], v[182:185], v[198:201], v[96:99]
	v_mfma_f32_16x16x32_bf16 v[84:87], v[174:177], v[206:209], v[84:87]
	v_mfma_f32_16x16x32_bf16 v[80:83], v[182:185], v[206:209], v[80:83]
	v_mfma_f32_16x16x32_bf16 v[68:71], v[174:177], v[214:217], v[68:71]
	v_mfma_f32_16x16x32_bf16 v[64:67], v[182:185], v[214:217], v[64:67]
	v_mfma_f32_16x16x32_bf16 v[116:119], v[178:181], v[194:197], v[116:119]
	v_mfma_f32_16x16x32_bf16 v[112:115], v[186:189], v[194:197], v[112:115]
	v_mfma_f32_16x16x32_bf16 v[100:103], v[178:181], v[202:205], v[100:103]
	v_mfma_f32_16x16x32_bf16 v[96:99], v[186:189], v[202:205], v[96:99]
	v_mfma_f32_16x16x32_bf16 v[84:87], v[178:181], v[210:213], v[84:87]
	v_mfma_f32_16x16x32_bf16 v[80:83], v[186:189], v[210:213], v[80:83]
	v_mfma_f32_16x16x32_bf16 v[68:71], v[178:181], v[218:221], v[68:71]
	v_mfma_f32_16x16x32_bf16 v[64:67], v[186:189], v[218:221], v[64:67]
	s_barrier
	s_setprio 0
	s_add_i32 s24, s54, s30
	v_lshl_add_u64 v[146:147], v[146:147], 0, s[6:7]
	s_mov_b32 m0, s24
	ds_read_b128 v[190:193], v152 offset:49152
	ds_read_b128 v[194:197], v152 offset:50176
	ds_read_b128 v[198:201], v152 offset:51200
	ds_read_b128 v[202:205], v152 offset:52224
	ds_read_b128 v[206:209], v152 offset:53248
	ds_read_b128 v[210:213], v152 offset:54272
	ds_read_b128 v[214:217], v152 offset:55296
	ds_read_b128 v[218:221], v152 offset:56320
	global_load_lds_dwordx4 v[146:147], off
	s_add_i32 m0, s24, 0x2000
	s_add_u32 s22, s22, 0x40080
	v_lshl_add_u64 v[146:147], v[162:163], 0, s[6:7]
	s_addc_u32 s23, s23, 0
	s_add_i32 s24, s55, s30
	global_load_lds_dwordx4 v[146:147], off
	v_lshl_add_u64 v[146:147], s[22:23], 0, v[132:133]
	s_mov_b32 m0, s24
	s_nop 0
	global_load_lds_dwordx4 v[146:147], off
	v_lshl_add_u64 v[146:147], s[22:23], 0, v[128:129]
	s_add_i32 m0, s24, 0x2000
	s_nop 0
	global_load_lds_dwordx4 v[146:147], off
	v_lshl_add_u64 v[146:147], v[222:223], 0, s[6:7]
	s_mov_b32 m0, s45
	s_nop 0
	global_load_lds_dwordx4 v[146:147], off
	v_lshl_add_u64 v[146:147], v[224:225], 0, s[6:7]
	s_mov_b32 m0, s46
	s_nop 0
	global_load_lds_dwordx4 v[146:147], off
	s_waitcnt vmcnt(8)
	s_waitcnt lgkmcnt(0)
	s_setprio 1
	s_barrier
	v_mfma_f32_16x16x32_bf16 v[60:63], v[154:157], v[190:193], v[60:63]
	v_mfma_f32_16x16x32_bf16 v[56:59], v[166:169], v[190:193], v[56:59]
	v_mfma_f32_16x16x32_bf16 v[44:47], v[154:157], v[198:201], v[44:47]
	v_mfma_f32_16x16x32_bf16 v[40:43], v[166:169], v[198:201], v[40:43]
	v_mfma_f32_16x16x32_bf16 v[28:31], v[154:157], v[206:209], v[28:31]
	v_mfma_f32_16x16x32_bf16 v[24:27], v[166:169], v[206:209], v[24:27]
	v_mfma_f32_16x16x32_bf16 v[12:15], v[154:157], v[214:217], v[12:15]
	v_mfma_f32_16x16x32_bf16 v[8:11], v[166:169], v[214:217], v[8:11]
	v_mfma_f32_16x16x32_bf16 v[60:63], v[158:161], v[194:197], v[60:63]
	v_mfma_f32_16x16x32_bf16 v[56:59], v[170:173], v[194:197], v[56:59]
	v_mfma_f32_16x16x32_bf16 v[44:47], v[158:161], v[202:205], v[44:47]
	v_mfma_f32_16x16x32_bf16 v[40:43], v[170:173], v[202:205], v[40:43]
	v_mfma_f32_16x16x32_bf16 v[28:31], v[158:161], v[210:213], v[28:31]
	v_mfma_f32_16x16x32_bf16 v[24:27], v[170:173], v[210:213], v[24:27]
	v_mfma_f32_16x16x32_bf16 v[12:15], v[158:161], v[218:221], v[12:15]
	v_mfma_f32_16x16x32_bf16 v[8:11], v[170:173], v[218:221], v[8:11]
	v_mfma_f32_16x16x32_bf16 v[52:55], v[174:177], v[190:193], v[52:55]
	v_mfma_f32_16x16x32_bf16 v[48:51], v[182:185], v[190:193], v[48:51]
	v_mfma_f32_16x16x32_bf16 v[36:39], v[174:177], v[198:201], v[36:39]
	v_mfma_f32_16x16x32_bf16 v[32:35], v[182:185], v[198:201], v[32:35]
	v_mfma_f32_16x16x32_bf16 v[20:23], v[174:177], v[206:209], v[20:23]
	v_mfma_f32_16x16x32_bf16 v[16:19], v[182:185], v[206:209], v[16:19]
	v_mfma_f32_16x16x32_bf16 v[4:7], v[174:177], v[214:217], v[4:7]
	v_mfma_f32_16x16x32_bf16 v[0:3], v[182:185], v[214:217], v[0:3]
	v_mfma_f32_16x16x32_bf16 v[52:55], v[178:181], v[194:197], v[52:55]
	v_mfma_f32_16x16x32_bf16 v[48:51], v[186:189], v[194:197], v[48:51]
	v_mfma_f32_16x16x32_bf16 v[36:39], v[178:181], v[202:205], v[36:39]
	v_mfma_f32_16x16x32_bf16 v[32:35], v[186:189], v[202:205], v[32:35]
	v_mfma_f32_16x16x32_bf16 v[20:23], v[178:181], v[210:213], v[20:23]
	v_mfma_f32_16x16x32_bf16 v[16:19], v[186:189], v[210:213], v[16:19]
	v_mfma_f32_16x16x32_bf16 v[4:7], v[178:181], v[218:221], v[4:7]
	v_mfma_f32_16x16x32_bf16 v[0:3], v[186:189], v[218:221], v[0:3]
	s_barrier
	s_setprio 0
	s_add_i32 s53, s53, 2
	s_add_u32 s20, s20, 0x100
	s_addc_u32 s21, s21, 0
	s_add_u32 s51, s51, 0x100
	s_addc_u32 s52, s52, 0
	s_cmp_gt_u32 s53, 13
	s_cbranch_scc0 .LBB0_956
	s_and_b64 vcc, exec, s[8:9]
	s_cbranch_vccz .LBB0_959
	s_barrier

.LBB0_1029:
	ds_read_b128 v[72:75], v173
	ds_read_b128 v[76:79], v173 offset:1024
	ds_read_b128 v[88:91], v173 offset:2048
	ds_read_b128 v[92:95], v173 offset:3072
	ds_read_b128 v[166:169], v174
	ds_read_b128 v[178:181], v174 offset:1024
	ds_read_b128 v[182:185], v174 offset:2048
	ds_read_b128 v[186:189], v174 offset:3072
	s_add_u32 s20, s2, 0x9fe000
	s_addc_u32 s21, s3, 0
	s_cmp_eq_u32 s55, 40
	s_cselect_b32 s24, s52, s20
	s_cselect_b32 s25, s13, s21
	s_cselect_b32 s22, s14, s53
	s_cselect_b32 s23, s15, s54
	s_add_u32 s20, s24, 0xa00000
	s_addc_u32 s21, s25, 0
	v_lshl_add_u64 v[222:223], s[2:3], 0, v[158:159]
	s_add_i32 m0, s19, 0xc000
	ds_read_b128 v[190:193], v175
	ds_read_b128 v[194:197], v175 offset:1024
	ds_read_b128 v[198:201], v175 offset:2048
	ds_read_b128 v[202:205], v175 offset:3072
	ds_read_b128 v[206:209], v175 offset:4096
	ds_read_b128 v[210:213], v175 offset:5120
	ds_read_b128 v[214:217], v175 offset:6144
	ds_read_b128 v[218:221], v175 offset:7168
	global_load_lds_dwordx4 v[222:223], off
	v_lshl_add_u64 v[222:223], s[2:3], 0, v[160:161]
	s_add_i32 m0, s19, 0xe000
	s_nop 0
	global_load_lds_dwordx4 v[222:223], off
	s_waitcnt vmcnt(8)
	s_waitcnt lgkmcnt(0)
	s_setprio 1
	s_barrier
	v_mfma_f32_16x16x32_bf16 v[140:143], v[72:75], v[190:193], v[140:143]
	v_mfma_f32_16x16x32_bf16 v[136:139], v[88:91], v[190:193], v[136:139]
	v_mfma_f32_16x16x32_bf16 v[124:127], v[72:75], v[198:201], v[124:127]
	v_mfma_f32_16x16x32_bf16 v[120:123], v[88:91], v[198:201], v[120:123]
	v_mfma_f32_16x16x32_bf16 v[108:111], v[72:75], v[206:209], v[108:111]
	v_mfma_f32_16x16x32_bf16 v[104:107], v[88:91], v[206:209], v[104:107]
	v_mfma_f32_16x16x32_bf16 v[84:87], v[72:75], v[214:217], v[84:87]
	v_mfma_f32_16x16x32_bf16 v[80:83], v[88:91], v[214:217], v[80:83]
	v_mfma_f32_16x16x32_bf16 v[140:143], v[76:79], v[194:197], v[140:143]
	v_mfma_f32_16x16x32_bf16 v[136:139], v[92:95], v[194:197], v[136:139]
	v_mfma_f32_16x16x32_bf16 v[124:127], v[76:79], v[202:205], v[124:127]
	v_mfma_f32_16x16x32_bf16 v[120:123], v[92:95], v[202:205], v[120:123]
	v_mfma_f32_16x16x32_bf16 v[108:111], v[76:79], v[210:213], v[108:111]
	v_mfma_f32_16x16x32_bf16 v[104:107], v[92:95], v[210:213], v[104:107]
	v_mfma_f32_16x16x32_bf16 v[84:87], v[76:79], v[218:221], v[84:87]
	v_mfma_f32_16x16x32_bf16 v[80:83], v[92:95], v[218:221], v[80:83]
	v_mfma_f32_16x16x32_bf16 v[132:135], v[166:169], v[190:193], v[132:135]
	v_mfma_f32_16x16x32_bf16 v[128:131], v[182:185], v[190:193], v[128:131]
	v_mfma_f32_16x16x32_bf16 v[116:119], v[166:169], v[198:201], v[116:119]
	v_mfma_f32_16x16x32_bf16 v[112:115], v[182:185], v[198:201], v[112:115]
	v_mfma_f32_16x16x32_bf16 v[100:103], v[166:169], v[206:209], v[100:103]
	v_mfma_f32_16x16x32_bf16 v[96:99], v[182:185], v[206:209], v[96:99]
	v_mfma_f32_16x16x32_bf16 v[68:71], v[166:169], v[214:217], v[68:71]
	v_mfma_f32_16x16x32_bf16 v[64:67], v[182:185], v[214:217], v[64:67]
	v_mfma_f32_16x16x32_bf16 v[132:135], v[178:181], v[194:197], v[132:135]
	v_mfma_f32_16x16x32_bf16 v[128:131], v[186:189], v[194:197], v[128:131]
	v_mfma_f32_16x16x32_bf16 v[116:119], v[178:181], v[202:205], v[116:119]
	v_mfma_f32_16x16x32_bf16 v[112:115], v[186:189], v[202:205], v[112:115]
	v_mfma_f32_16x16x32_bf16 v[100:103], v[178:181], v[210:213], v[100:103]
	v_mfma_f32_16x16x32_bf16 v[96:99], v[186:189], v[210:213], v[96:99]
	v_mfma_f32_16x16x32_bf16 v[68:71], v[178:181], v[218:221], v[68:71]
	v_mfma_f32_16x16x32_bf16 v[64:67], v[186:189], v[218:221], v[64:67]
	s_barrier
	s_setprio 0
	s_add_i32 s56, s47, s30
	v_lshl_add_u64 v[222:223], s[22:23], 0, v[148:149]
	s_mov_b32 m0, s56
	ds_read_b128 v[190:193], v175 offset:16384
	ds_read_b128 v[194:197], v175 offset:17408
	ds_read_b128 v[198:201], v175 offset:18432
	ds_read_b128 v[202:205], v175 offset:19456
	ds_read_b128 v[206:209], v175 offset:20480
	ds_read_b128 v[210:213], v175 offset:21504
	ds_read_b128 v[214:217], v175 offset:22528
	ds_read_b128 v[218:221], v175 offset:23552
	global_load_lds_dwordx4 v[222:223], off
	s_add_i32 m0, s56, 0x2000
	s_add_u32 s56, s22, 0xb0000
	v_lshl_add_u64 v[224:225], s[22:23], 0, v[144:145]
	s_addc_u32 s57, s23, 0
	s_add_i32 s58, s48, s30
	global_load_lds_dwordx4 v[224:225], off
	v_lshl_add_u64 v[226:227], s[56:57], 0, v[148:149]
	s_mov_b32 m0, s58
	s_nop 0
	global_load_lds_dwordx4 v[226:227], off
	v_lshl_add_u64 v[226:227], s[56:57], 0, v[144:145]
	s_add_i32 m0, s58, 0x2000
	s_nop 0
	global_load_lds_dwordx4 v[226:227], off
	v_lshl_add_u64 v[226:227], s[24:25], 0, v[150:151]
	s_mov_b32 m0, s19
	s_nop 0
	global_load_lds_dwordx4 v[226:227], off
	v_lshl_add_u64 v[226:227], s[24:25], 0, v[146:147]
	s_mov_b32 m0, s35
	s_nop 0
	global_load_lds_dwordx4 v[226:227], off
	s_waitcnt vmcnt(8)
	s_waitcnt lgkmcnt(0)
	s_setprio 1
	s_barrier
	v_mfma_f32_16x16x32_bf16 v[60:63], v[72:75], v[190:193], v[60:63]
	v_mfma_f32_16x16x32_bf16 v[56:59], v[88:91], v[190:193], v[56:59]
	v_mfma_f32_16x16x32_bf16 v[44:47], v[72:75], v[198:201], v[44:47]
	v_mfma_f32_16x16x32_bf16 v[40:43], v[88:91], v[198:201], v[40:43]
	v_mfma_f32_16x16x32_bf16 v[28:31], v[72:75], v[206:209], v[28:31]
	v_mfma_f32_16x16x32_bf16 v[24:27], v[88:91], v[206:209], v[24:27]
	v_mfma_f32_16x16x32_bf16 v[12:15], v[72:75], v[214:217], v[12:15]
	v_mfma_f32_16x16x32_bf16 v[8:11], v[88:91], v[214:217], v[8:11]
	v_mfma_f32_16x16x32_bf16 v[60:63], v[76:79], v[194:197], v[60:63]
	v_mfma_f32_16x16x32_bf16 v[56:59], v[92:95], v[194:197], v[56:59]
	v_mfma_f32_16x16x32_bf16 v[44:47], v[76:79], v[202:205], v[44:47]
	v_mfma_f32_16x16x32_bf16 v[40:43], v[92:95], v[202:205], v[40:43]
	v_mfma_f32_16x16x32_bf16 v[28:31], v[76:79], v[210:213], v[28:31]
	v_mfma_f32_16x16x32_bf16 v[24:27], v[92:95], v[210:213], v[24:27]
	v_mfma_f32_16x16x32_bf16 v[12:15], v[76:79], v[218:221], v[12:15]
	v_mfma_f32_16x16x32_bf16 v[8:11], v[92:95], v[218:221], v[8:11]
	v_mfma_f32_16x16x32_bf16 v[52:55], v[166:169], v[190:193], v[52:55]
	v_mfma_f32_16x16x32_bf16 v[48:51], v[182:185], v[190:193], v[48:51]
	v_mfma_f32_16x16x32_bf16 v[36:39], v[166:169], v[198:201], v[36:39]
	v_mfma_f32_16x16x32_bf16 v[32:35], v[182:185], v[198:201], v[32:35]
	v_mfma_f32_16x16x32_bf16 v[20:23], v[166:169], v[206:209], v[20:23]
	v_mfma_f32_16x16x32_bf16 v[16:19], v[182:185], v[206:209], v[16:19]
	v_mfma_f32_16x16x32_bf16 v[4:7], v[166:169], v[214:217], v[4:7]
	v_mfma_f32_16x16x32_bf16 v[0:3], v[182:185], v[214:217], v[0:3]
	v_mfma_f32_16x16x32_bf16 v[52:55], v[178:181], v[194:197], v[52:55]
	v_mfma_f32_16x16x32_bf16 v[48:51], v[186:189], v[194:197], v[48:51]
	v_mfma_f32_16x16x32_bf16 v[36:39], v[178:181], v[202:205], v[36:39]
	v_mfma_f32_16x16x32_bf16 v[32:35], v[186:189], v[202:205], v[32:35]
	v_mfma_f32_16x16x32_bf16 v[20:23], v[178:181], v[210:213], v[20:23]
	v_mfma_f32_16x16x32_bf16 v[16:19], v[186:189], v[210:213], v[16:19]
	v_mfma_f32_16x16x32_bf16 v[4:7], v[178:181], v[218:221], v[4:7]
	v_mfma_f32_16x16x32_bf16 v[0:3], v[186:189], v[218:221], v[0:3]
	s_barrier
	s_setprio 0
	s_add_i32 s56, 0, 0x18000
	s_add_i32 s57, 0, 0x1c000
	v_add_u32_e32 v92, s56, v155
	v_add_u32_e32 v152, s57, v155
	ds_read_b128 v[72:75], v92
	ds_read_b128 v[76:79], v92 offset:1024
	ds_read_b128 v[88:91], v92 offset:2048
	ds_read_b128 v[92:95], v92 offset:3072
	ds_read_b128 v[166:169], v152
	ds_read_b128 v[178:181], v152 offset:1024
	ds_read_b128 v[182:185], v152 offset:2048
	ds_read_b128 v[186:189], v152 offset:3072
	s_add_u32 s24, s24, 0x2000
	s_addc_u32 s25, s25, 0
	s_mov_b32 m0, s36
	v_lshl_add_u64 v[226:227], s[24:25], 0, v[150:151]
	ds_read_b128 v[190:193], v175 offset:32768
	ds_read_b128 v[194:197], v175 offset:33792
	ds_read_b128 v[198:201], v175 offset:34816
	ds_read_b128 v[202:205], v175 offset:35840
	ds_read_b128 v[206:209], v175 offset:36864
	ds_read_b128 v[210:213], v175 offset:37888
	ds_read_b128 v[214:217], v175 offset:38912
	ds_read_b128 v[218:221], v175 offset:39936
	global_load_lds_dwordx4 v[226:227], off
	v_lshl_add_u64 v[226:227], s[24:25], 0, v[146:147]
	s_mov_b32 m0, s37
	s_nop 0
	global_load_lds_dwordx4 v[226:227], off
	s_waitcnt vmcnt(8)
	s_waitcnt lgkmcnt(0)
	s_setprio 1
	s_barrier
	v_mfma_f32_16x16x32_bf16 v[140:143], v[72:75], v[190:193], v[140:143]
	v_mfma_f32_16x16x32_bf16 v[136:139], v[88:91], v[190:193], v[136:139]
	v_mfma_f32_16x16x32_bf16 v[124:127], v[72:75], v[198:201], v[124:127]
	v_mfma_f32_16x16x32_bf16 v[120:123], v[88:91], v[198:201], v[120:123]
	v_mfma_f32_16x16x32_bf16 v[108:111], v[72:75], v[206:209], v[108:111]
	v_mfma_f32_16x16x32_bf16 v[104:107], v[88:91], v[206:209], v[104:107]
	v_mfma_f32_16x16x32_bf16 v[84:87], v[72:75], v[214:217], v[84:87]
	v_mfma_f32_16x16x32_bf16 v[80:83], v[88:91], v[214:217], v[80:83]
	v_mfma_f32_16x16x32_bf16 v[140:143], v[76:79], v[194:197], v[140:143]
	v_mfma_f32_16x16x32_bf16 v[136:139], v[92:95], v[194:197], v[136:139]
	v_mfma_f32_16x16x32_bf16 v[124:127], v[76:79], v[202:205], v[124:127]
	v_mfma_f32_16x16x32_bf16 v[120:123], v[92:95], v[202:205], v[120:123]
	v_mfma_f32_16x16x32_bf16 v[108:111], v[76:79], v[210:213], v[108:111]
	v_mfma_f32_16x16x32_bf16 v[104:107], v[92:95], v[210:213], v[104:107]
	v_mfma_f32_16x16x32_bf16 v[84:87], v[76:79], v[218:221], v[84:87]
	v_mfma_f32_16x16x32_bf16 v[80:83], v[92:95], v[218:221], v[80:83]
	v_mfma_f32_16x16x32_bf16 v[132:135], v[166:169], v[190:193], v[132:135]
	v_mfma_f32_16x16x32_bf16 v[128:131], v[182:185], v[190:193], v[128:131]
	v_mfma_f32_16x16x32_bf16 v[116:119], v[166:169], v[198:201], v[116:119]
	v_mfma_f32_16x16x32_bf16 v[112:115], v[182:185], v[198:201], v[112:115]
	v_mfma_f32_16x16x32_bf16 v[100:103], v[166:169], v[206:209], v[100:103]
	v_mfma_f32_16x16x32_bf16 v[96:99], v[182:185], v[206:209], v[96:99]
	v_mfma_f32_16x16x32_bf16 v[68:71], v[166:169], v[214:217], v[68:71]
	v_mfma_f32_16x16x32_bf16 v[64:67], v[182:185], v[214:217], v[64:67]
	v_mfma_f32_16x16x32_bf16 v[132:135], v[178:181], v[194:197], v[132:135]
	v_mfma_f32_16x16x32_bf16 v[128:131], v[186:189], v[194:197], v[128:131]
	v_mfma_f32_16x16x32_bf16 v[116:119], v[178:181], v[202:205], v[116:119]
	v_mfma_f32_16x16x32_bf16 v[112:115], v[186:189], v[202:205], v[112:115]
	v_mfma_f32_16x16x32_bf16 v[100:103], v[178:181], v[210:213], v[100:103]
	v_mfma_f32_16x16x32_bf16 v[96:99], v[186:189], v[210:213], v[96:99]
	v_mfma_f32_16x16x32_bf16 v[68:71], v[178:181], v[218:221], v[68:71]
	v_mfma_f32_16x16x32_bf16 v[64:67], v[186:189], v[218:221], v[64:67]
	s_barrier
	s_setprio 0
	s_add_i32 s24, s56, s30
	v_lshl_add_u64 v[222:223], v[222:223], 0, s[6:7]
	s_mov_b32 m0, s24
	ds_read_b128 v[190:193], v175 offset:49152
	ds_read_b128 v[194:197], v175 offset:50176
	ds_read_b128 v[198:201], v175 offset:51200
	ds_read_b128 v[202:205], v175 offset:52224
	ds_read_b128 v[206:209], v175 offset:53248
	ds_read_b128 v[210:213], v175 offset:54272
	ds_read_b128 v[214:217], v175 offset:55296
	ds_read_b128 v[218:221], v175 offset:56320
	global_load_lds_dwordx4 v[222:223], off
	s_add_i32 m0, s24, 0x2000
	s_add_u32 s22, s22, 0xb0080
	v_lshl_add_u64 v[222:223], v[224:225], 0, s[6:7]
	s_addc_u32 s23, s23, 0
	s_add_i32 s24, s57, s30
	global_load_lds_dwordx4 v[222:223], off
	v_lshl_add_u64 v[222:223], s[22:23], 0, v[148:149]
	s_mov_b32 m0, s24
	s_nop 0
	global_load_lds_dwordx4 v[222:223], off
	v_lshl_add_u64 v[222:223], s[22:23], 0, v[144:145]
	s_add_i32 m0, s24, 0x2000
	s_nop 0
	global_load_lds_dwordx4 v[222:223], off
	v_lshl_add_u64 v[222:223], s[20:21], 0, v[150:151]
	s_mov_b32 m0, s43
	s_nop 0
	global_load_lds_dwordx4 v[222:223], off
	v_lshl_add_u64 v[222:223], s[20:21], 0, v[146:147]
	s_mov_b32 m0, s44
	s_nop 0
	global_load_lds_dwordx4 v[222:223], off
	s_waitcnt vmcnt(8)
	s_waitcnt lgkmcnt(0)
	s_setprio 1
	s_barrier
	v_mfma_f32_16x16x32_bf16 v[60:63], v[72:75], v[190:193], v[60:63]
	v_mfma_f32_16x16x32_bf16 v[56:59], v[88:91], v[190:193], v[56:59]
	v_mfma_f32_16x16x32_bf16 v[44:47], v[72:75], v[198:201], v[44:47]
	v_mfma_f32_16x16x32_bf16 v[40:43], v[88:91], v[198:201], v[40:43]
	v_mfma_f32_16x16x32_bf16 v[28:31], v[72:75], v[206:209], v[28:31]
	v_mfma_f32_16x16x32_bf16 v[24:27], v[88:91], v[206:209], v[24:27]
	v_mfma_f32_16x16x32_bf16 v[12:15], v[72:75], v[214:217], v[12:15]
	v_mfma_f32_16x16x32_bf16 v[8:11], v[88:91], v[214:217], v[8:11]
	v_mfma_f32_16x16x32_bf16 v[60:63], v[76:79], v[194:197], v[60:63]
	v_mfma_f32_16x16x32_bf16 v[56:59], v[92:95], v[194:197], v[56:59]
	v_mfma_f32_16x16x32_bf16 v[44:47], v[76:79], v[202:205], v[44:47]
	v_mfma_f32_16x16x32_bf16 v[40:43], v[92:95], v[202:205], v[40:43]
	v_mfma_f32_16x16x32_bf16 v[28:31], v[76:79], v[210:213], v[28:31]
	v_mfma_f32_16x16x32_bf16 v[24:27], v[92:95], v[210:213], v[24:27]
	v_mfma_f32_16x16x32_bf16 v[12:15], v[76:79], v[218:221], v[12:15]
	v_mfma_f32_16x16x32_bf16 v[8:11], v[92:95], v[218:221], v[8:11]
	v_mfma_f32_16x16x32_bf16 v[52:55], v[166:169], v[190:193], v[52:55]
	v_mfma_f32_16x16x32_bf16 v[48:51], v[182:185], v[190:193], v[48:51]
	v_mfma_f32_16x16x32_bf16 v[36:39], v[166:169], v[198:201], v[36:39]
	v_mfma_f32_16x16x32_bf16 v[32:35], v[182:185], v[198:201], v[32:35]
	v_mfma_f32_16x16x32_bf16 v[20:23], v[166:169], v[206:209], v[20:23]
	v_mfma_f32_16x16x32_bf16 v[16:19], v[182:185], v[206:209], v[16:19]
	v_mfma_f32_16x16x32_bf16 v[4:7], v[166:169], v[214:217], v[4:7]
	v_mfma_f32_16x16x32_bf16 v[0:3], v[182:185], v[214:217], v[0:3]
	v_mfma_f32_16x16x32_bf16 v[52:55], v[178:181], v[194:197], v[52:55]
	v_mfma_f32_16x16x32_bf16 v[48:51], v[186:189], v[194:197], v[48:51]
	v_mfma_f32_16x16x32_bf16 v[36:39], v[178:181], v[202:205], v[36:39]
	v_mfma_f32_16x16x32_bf16 v[32:35], v[186:189], v[202:205], v[32:35]
	v_mfma_f32_16x16x32_bf16 v[20:23], v[178:181], v[210:213], v[20:23]
	v_mfma_f32_16x16x32_bf16 v[16:19], v[186:189], v[210:213], v[16:19]
	v_mfma_f32_16x16x32_bf16 v[4:7], v[178:181], v[218:221], v[4:7]
	v_mfma_f32_16x16x32_bf16 v[0:3], v[186:189], v[218:221], v[0:3]
	s_barrier
	s_setprio 0
	s_add_i32 s55, s55, 2
	s_add_u32 s53, s53, 0x100
	s_addc_u32 s54, s54, 0
	s_add_u32 s2, s2, 0x1400000
	s_addc_u32 s3, s3, 0
	s_cmp_gt_u32 s55, 41
	s_cbranch_scc0 .LBB0_1029
	s_and_b64 vcc, exec, s[8:9]
	s_cbranch_vccz .LBB0_1032
	s_barrier
